# attention loops: packed v_pk_fma_f32 of the softmax scale pass split into two v_fma_f32 each (asm guide 7.5)
# baseline (speedup 1.0000x reference)
; __device__ __forceinline__ int v_st(int k, int c) { const int kk = (k & ~0xC) | ((k & 4) << 1) | ((k & 8) >> 1); return ((kk >> 3) * 4 + (c >> 5)) * 512 + ((kk & 7) * 32 + (c & 31)) * 2; }
; __device__ __forceinline__ int v_rd_base(int lane) { return ((lane & 3) << 3) | (((lane >> 2) & 3) << 6) | (((lane >> 4) & 1) << 5) | (((lane >> 5) & 1) << 8); }
; #define SLOAD(i, k0) do { const long to_ = (long)(k0) * ldk * 2; const char* vt_ = (const char*)Vh + to_; const char* kt_ = (const char*)Kh + to_; \
;     sr_[i].vs0 = *(const bf16x8*)(vt_ + toff); sr_[i].vs1 = *(const bf16x8*)(vt_ + h32 + toff); \
;     sr_[i].ks0 = *(const bf16x8*)(kt_ + toff); sr_[i].ks1 = *(const bf16x8*)(kt_ + h32 + toff); } while (0)
; __device__ __forceinline__ void qkt(f32x16& p0, f32x16& p1, const bf16* Ks, const bf16x8* qr, int r32, int hi) {
;   p0 = f32x16{}; p1 = f32x16{};
;   for (int d0 = 0; d0 < 8; ++d0) { int cb = (d0 * 16 + hi * 8) * 2;
;     bf16x8 b0 = *reinterpret_cast<const bf16x8*>((const char*)Ks + KSWZ(r32, cb));
;     bf16x8 b1 = *reinterpret_cast<const bf16x8*>((const char*)Ks + KSWZ(32 + r32, cb));
;     p0 = __builtin_amdgcn_mfma_f32_32x32x16_bf16(b0, qr[d0], p0, 0, 0, 0);
;     p1 = __builtin_amdgcn_mfma_f32_32x32x16_bf16(b1, qr[d0], p1, 0, 0, 0); }
; template <int MODE, int QMODE> ...
;     ...
;   const int sr = tid >> 4, sc = (tid & 15) * 8, vst0 = v_st(sr, sc), vst1 = v_st(32 + sr, sc);
;   const int vb0 = (int)(uintptr_t)V_lds + v_rd_base(lane);
;   const unsigned toff = (unsigned)(sr * ldk + sc) * 2u; const long h32 = (long)ldk * 64;
;   constexpr int SDEPTH = (MODE == 0 && QMODE == 2) ? 2 : 1;
;   struct { typename St::T vs0, vs1, ks0, ks1; } sr_[SDEPTH];
;     ...
;   const int qw0 = qrel + wrow;
;     ...
;   if (wid >= 4) __builtin_amdgcn_s_setprio(1);
;   f32x16 pA0, pA1, pB0, pB1; float mnA, mnB, alA, alB; bf16x8 pa0, pa1, pa2, pa3; const int NT = seq / KVBLK;
;   constexpr int SE = 0, SO = SDEPTH - 1;
;   SLOAD(SE, 0); asm volatile("s_waitcnt vmcnt(0)" ::: "memory"); SWRITE(0, SE); __syncthreads();
;   qkt(pA0, pA1, K_lds, qr, r32, hi); MASK(pA0, pA1, 0); partialSM(pA0, pA1, m_reg, mnA, alA);
;   SLOAD(SO, KVBLK); if constexpr (SDEPTH == 2) { if (2 < NT) SLOAD(SE, 2 * KVBLK); }
.LBB0_170:
	s_mul_i32 s33, s17, 0x1800
	s_mul_hi_u32 s97, s17, 0x1800
	s_add_u32 s2, s40, s33
	v_ashrrev_i32_e32 v18, 4, v229
	v_lshlrev_b32_e32 v19, 3, v229
	s_addc_u32 s3, s41, s97
	s_and_b32 s17, s47, 0xffffff00
	v_and_b32_e32 v20, 0x78, v19
	v_mul_lo_u32 v2, v18, s59
	s_add_u32 s2, s2, s17
	v_or_b32_e32 v2, v2, v20
	s_addc_u32 s3, s3, 0
	v_lshlrev_b32_e32 v50, 1, v2
	v_mov_b32_e32 v51, v211
	v_lshl_add_u64 v[52:53], s[2:3], 0, v[50:51]
	v_add_co_u32_e32 v10, vcc, s60, v52
	v_lshlrev_b32_e32 v22, 4, v233
	s_nop 0
	v_addc_co_u32_e32 v11, vcc, 0, v53, vcc
	v_add_co_u32_e32 v14, vcc, s61, v52
	global_load_dwordx4 v[2:5], v[10:11], off offset:512
	s_nop 0
	v_addc_co_u32_e32 v15, vcc, 0, v53, vcc
	global_load_dwordx4 v[6:9], v[14:15], off offset:512
	s_nop 0
	global_load_dwordx4 v[10:13], v[10:11], off
	s_nop 0
	global_load_dwordx4 v[14:17], v[14:15], off
	v_and_b32_e32 v23, 0xfffff0, v18
	v_lshlrev_b32_e32 v24, 1, v18
	v_lshrrev_b32_e32 v25, 1, v18
	v_and_b32_e32 v26, 3, v18
	v_add_u32_e32 v27, 32, v18
	v_and_b32_e32 v71, 0xf0, v22
	v_and_or_b32 v22, v24, 8, v23
	v_and_or_b32 v23, v25, 4, v26
	v_and_b32_e32 v24, 0xfffff0, v27
	v_lshlrev_b32_e32 v25, 1, v27
	v_and_b32_e32 v21, 0xf0, v229
	v_bfe_u32 v19, v19, 5, 2
	v_lshlrev_b32_e32 v18, 8, v18
	v_lshlrev_b32_e32 v20, 1, v20
	v_lshlrev_b32_e32 v26, 8, v27
	v_lshrrev_b32_e32 v22, 1, v22
	v_and_or_b32 v24, v25, 8, v24
	v_and_b32_e32 v28, 48, v20
	v_bitop3_b32 v18, v20, v18, v21 bitop3:0xde
	v_bitop3_b32 v20, v20, v26, v21 bitop3:0xde
	v_or_b32_e32 v21, v22, v19
	v_lshrrev_b32_e32 v22, 1, v24
	v_lshlrev_b32_e32 v70, 8, v233
	v_lshlrev_b32_e32 v23, 6, v23
	v_add_u32_e32 v219, 0, v18
	v_lshlrev_b32_e32 v18, 9, v21
	v_or_b32_e32 v19, v22, v19
	v_bitop3_b32 v27, v210, v70, v71 bitop3:0xde
	v_or3_b32 v18, v18, v23, v28
	v_lshlrev_b32_e32 v19, 9, v19
	v_add_u32_e32 v218, 0, v27
	v_or3_b32 v19, v19, v23, v28
	v_add_u32_e32 v221, 0, v18
	v_add_u32_e32 v220, 0, v20
	s_waitcnt vmcnt(0)
	v_add_u32_e32 v222, 0, v19
	v_and_b32_e32 v98, 63, v229
	s_and_b32 s2, s16, 0x3fffffc0
	s_lshl_b32 s2, s2, 2
	s_add_i32 s95, s2, 0
	s_add_i32 s95, s95, 0x10000
	s_cmp_lg_u32 0, -1
	s_cselect_b32 s4, 0, 0
	s_mov_b32 s16, s9
	s_mov_b32 s17, s9
	s_mov_b32 s18, s9
	s_mov_b32 s19, s9
	s_mov_b32 s20, s9
	s_mov_b32 s21, s9
	s_mov_b32 s22, s9
	s_mov_b32 s23, s9
	s_mov_b32 s24, s9
	s_mov_b32 s25, s9
	s_mov_b32 s26, s9
	s_mov_b32 s27, s9
	s_mov_b32 s28, s9
	s_mov_b32 s29, s9
	s_mov_b32 s30, s9
	s_mov_b32 s31, s9
	s_mov_b32 s49, s9
	s_mov_b32 s96, 2
	v_cmp_gt_u32_e64 s[2:3], 32, v98
	v_lshl_add_u32 v214, v233, 2, s95
	v_mov_b32_e32 v215, 0
	s_waitcnt vmcnt(3)
	ds_write_b128 v221, v[2:5]
	s_waitcnt vmcnt(2)
	ds_write_b128 v222, v[6:9]
	s_waitcnt vmcnt(1)
	ds_write_b128 v219, v[10:13] offset:32768
	s_waitcnt vmcnt(0)
	ds_write_b128 v220, v[14:17] offset:32768
	s_waitcnt lgkmcnt(0)
	s_barrier
	ds_read_b128 v[2:5], v218 offset:32768
	ds_read_b128 v[6:9], v218 offset:40960
	s_waitcnt lgkmcnt(1)
	v_mfma_f32_32x32x16_bf16 v[18:33], v[2:5], v[134:137], 0
	v_or_b32_e32 v2, 32, v210
	v_bitop3_b32 v2, v2, v70, v71 bitop3:0xde
	v_add_u32_e32 v223, 0, v2
	v_or_b32_e32 v10, 0xa0, v210
	v_or_b32_e32 v11, 0xc0, v210
	v_lshlrev_b32_e32 v14, 3, v98
	s_waitcnt lgkmcnt(0)
	v_mfma_f32_32x32x16_bf16 v[34:49], v[6:9], v[134:137], 0
	ds_read_b128 v[2:5], v223 offset:32768
	ds_read_b128 v[6:9], v223 offset:40960
	s_waitcnt lgkmcnt(1)
	v_mfma_f32_32x32x16_bf16 v[18:33], v[2:5], v[142:145], v[18:33]
	v_or_b32_e32 v2, 64, v210
	v_bitop3_b32 v2, v2, v70, v71 bitop3:0xde
	v_add_u32_e32 v227, 0, v2
	s_waitcnt lgkmcnt(0)
	v_mfma_f32_32x32x16_bf16 v[34:49], v[6:9], v[142:145], v[34:49]
	ds_read_b128 v[2:5], v227 offset:32768
	ds_read_b128 v[6:9], v227 offset:40960
	s_waitcnt lgkmcnt(1)
	v_mfma_f32_32x32x16_bf16 v[18:33], v[2:5], v[130:133], v[18:33]
	v_or_b32_e32 v2, 0x60, v210
	v_bitop3_b32 v2, v2, v70, v71 bitop3:0xde
	v_add_u32_e32 v228, 0, v2
	ds_read_b128 v[2:5], v228 offset:32768
	s_waitcnt lgkmcnt(1)
	v_mfma_f32_32x32x16_bf16 v[34:49], v[6:9], v[130:133], v[34:49]
	ds_read_b128 v[6:9], v228 offset:40960
	s_waitcnt lgkmcnt(1)
	v_mfma_f32_32x32x16_bf16 v[18:33], v[2:5], v[138:141], v[18:33]
	v_or_b32_e32 v2, 0x80, v210
	v_bitop3_b32 v2, v2, v70, v71 bitop3:0xde
	v_add_u32_e32 v229, 0, v2
	ds_read_b128 v[2:5], v229 offset:32768
	s_waitcnt lgkmcnt(1)
	v_mfma_f32_32x32x16_bf16 v[34:49], v[6:9], v[138:141], v[34:49]
	v_lshlrev_b32_e32 v6, 4, v98
	v_lshlrev_b32_e32 v7, 1, v98
	v_and_b32_e32 v12, 0xc0, v6
	v_and_b32_e32 v15, 32, v7
	ds_read_b128 v[6:9], v229 offset:40960
	v_and_or_b32 v16, v14, 24, v12
	s_waitcnt lgkmcnt(1)
	v_mfma_f32_32x32x16_bf16 v[18:33], v[2:5], v[150:153], v[18:33]
	v_bitop3_b32 v2, v10, v70, v71 bitop3:0xde
	v_bitop3_b32 v3, v11, v70, v71 bitop3:0xde
	v_add_u32_e32 v231, 0, v2
	v_add_u32_e32 v230, 0, v3
	ds_read_b128 v[2:5], v231 offset:32768
	v_add_co_u32_e32 v10, vcc, s63, v52
	s_waitcnt lgkmcnt(1)
	v_mfma_f32_32x32x16_bf16 v[34:49], v[6:9], v[150:153], v[34:49]
	v_addc_co_u32_e32 v11, vcc, 0, v53, vcc
	v_add_co_u32_e32 v12, vcc, s64, v52
	ds_read_b128 v[6:9], v231 offset:40960
	s_nop 0
	v_addc_co_u32_e32 v13, vcc, 0, v53, vcc
	global_load_dwordx4 v[54:57], v[10:11], off offset:512
	s_waitcnt lgkmcnt(1)
	v_mfma_f32_32x32x16_bf16 v[18:33], v[2:5], v[158:161], v[18:33]
	global_load_dwordx4 v[58:61], v[12:13], off offset:512
	global_load_dwordx4 v[62:65], v[10:11], off
	global_load_dwordx4 v[66:69], v[12:13], off
	ds_read_b128 v[2:5], v230 offset:32768
	s_waitcnt lgkmcnt(1)
	v_mfma_f32_32x32x16_bf16 v[34:49], v[6:9], v[158:161], v[34:49]
	v_and_b32_e32 v6, 0x100, v14
	v_or3_b32 v99, v16, v15, v6
	ds_read_b128 v[6:9], v230 offset:40960
	v_add_u32_e32 v217, s4, v99
	s_waitcnt lgkmcnt(1)
; #define SLOAD(i, k0) do { const long to_ = (long)(k0) * ldk * 2; const char* vt_ = (const char*)Vh + to_; const char* kt_ = (const char*)Kh + to_; \
;     sr_[i].vs0 = *(const bf16x8*)(vt_ + toff); sr_[i].vs1 = *(const bf16x8*)(vt_ + h32 + toff); \
;     sr_[i].ks0 = *(const bf16x8*)(kt_ + toff); sr_[i].ks1 = *(const bf16x8*)(kt_ + h32 + toff); } while (0)
; #define SWAIT() do { if constexpr (SDEPTH == 2) asm volatile("s_waitcnt vmcnt(4)" ::: "memory"); else asm volatile("s_waitcnt vmcnt(0)" ::: "memory"); } while (0)
; #define MASK(P0, P1, k0) do { if constexpr (MODE == 1) { const int k0_ = (k0); \
;     if ((k0_ + 63 - qw0 > 128) || (k0_ - (qw0 + 31) < -128)) maskwin(P0, P1, k0_ - (qw0 + r32) + 128 + 4 * hi); } } while (0)
; __device__ __forceinline__ void partialSM(f32x16& p0, f32x16& p1, float& m_reg, float& mn, float& alpha) {
;   constexpr float C = SCALE * 1.4426950408889634f;
;   float pmax = p0[0]; for (int r = 1; r < 16; ++r) pmax = fmaxf(pmax, p0[r]); for (int r = 0; r < 16; ++r) pmax = fmaxf(pmax, p1[r]);
;   { auto rr = __builtin_amdgcn_permlane32_swap(__float_as_uint(pmax), __float_as_uint(pmax), false, false);
;     pmax = fmaxf(__uint_as_float(rr[0]), __uint_as_float(rr[1])); }
;   if (__builtin_expect(__all(pmax - m_reg <= THR / SCALE), 1)) { mn = m_reg; alpha = 1.f; }
;   else { mn = fmaxf(m_reg, pmax); alpha = __builtin_amdgcn_exp2f((m_reg - mn) * C); m_reg = mn; }
;   float mnC = -mn * C;
;   for (int r = 0; r < 16; ++r) p0[r] = fmaf(p0[r], C, mnC); for (int r = 0; r < 16; ++r) p1[r] = fmaf(p1[r], C, mnC);
;   for (int r = 0; r < 16; ++r) p0[r] = __builtin_amdgcn_exp2f(p0[r]);
; }
; template <int MODE, int QMODE> ...
;     ...
;   SLOAD(SE, 0); asm volatile("s_waitcnt vmcnt(0)" ::: "memory"); SWRITE(0, SE); __syncthreads();
;   qkt(pA0, pA1, K_lds, qr, r32, hi); MASK(pA0, pA1, 0); partialSM(pA0, pA1, m_reg, mnA, alA);
;   SLOAD(SO, KVBLK); if constexpr (SDEPTH == 2) { if (2 < NT) SLOAD(SE, 2 * KVBLK); }
;   SWAIT(); SWRITE(1, SO); __syncthreads();
	v_mfma_f32_32x32x16_bf16 v[18:33], v[2:5], v[146:149], v[18:33]
	v_or_b32_e32 v2, 0xe0, v210
	v_bitop3_b32 v2, v2, v70, v71 bitop3:0xde
	v_add_u32_e32 v232, 0, v2
	ds_read_b128 v[2:5], v232 offset:32768
	ds_read_b128 v[70:73], v232 offset:40960
	s_waitcnt lgkmcnt(2)
	v_mfma_f32_32x32x16_bf16 v[34:49], v[6:9], v[146:149], v[34:49]
	s_waitcnt lgkmcnt(1)
	v_mfma_f32_32x32x16_bf16 v[18:33], v[2:5], v[154:157], v[18:33]
	v_mov_b64_e32 v[2:3], s[16:17]
	v_mov_b64_e32 v[4:5], s[18:19]
	v_mov_b64_e32 v[6:7], s[20:21]
	v_mov_b64_e32 v[8:9], s[22:23]
	v_mov_b64_e32 v[10:11], s[24:25]
	v_mov_b64_e32 v[12:13], s[26:27]
	v_mov_b64_e32 v[14:15], s[28:29]
	s_waitcnt lgkmcnt(0)
	v_mfma_f32_32x32x16_bf16 v[34:49], v[70:73], v[154:157], v[34:49]
	s_nop 2
	v_max_f32_e32 v70, v19, v19
	v_max_f32_e32 v71, v18, v18
	v_max_f32_e32 v70, v71, v70
	v_max3_f32 v70, v70, v20, v21
	v_max3_f32 v70, v70, v22, v23
	v_max3_f32 v70, v70, v24, v25
	v_max3_f32 v70, v70, v26, v27
	v_max3_f32 v70, v70, v28, v29
	v_max3_f32 v70, v70, v30, v31
	v_max3_f32 v70, v70, v32, v33
	v_max3_f32 v70, v70, v34, v35
	v_max3_f32 v70, v70, v36, v37
	v_max3_f32 v70, v70, v38, v39
	v_max3_f32 v70, v70, v40, v41
	v_max3_f32 v70, v70, v42, v43
	v_max3_f32 v70, v70, v44, v45
	v_max3_f32 v70, v70, v46, v47
	v_max3_f32 v72, v70, v48, v49
	v_add_co_u32_e32 v70, vcc, s65, v52
	v_mov_b32_e32 v73, v72
	s_nop 0
	v_addc_co_u32_e32 v71, vcc, 0, v53, vcc
	v_add_co_u32_e32 v52, vcc, s66, v52
	v_permlane32_swap_b32_e32 v72, v73
	s_nop 0
	v_addc_co_u32_e32 v53, vcc, 0, v53, vcc
	global_load_dwordx4 v[162:165], v[70:71], off
	global_load_dwordx4 v[170:173], v[70:71], off offset:512
	global_load_dwordx4 v[174:177], v[52:53], off
	global_load_dwordx4 v[166:169], v[52:53], off offset:512
	v_max_f32_e32 v52, v73, v73
	v_max_f32_e32 v53, v72, v72
	v_max_f32_e32 v52, v53, v52
	v_add_f32_e32 v53, 0x7149f2ca, v52
	v_cmp_ge_f32_e32 vcc, s62, v53
	s_cmp_eq_u64 vcc, exec
	v_max_f32_e32 v52, 0xf149f2ca, v52
	s_cselect_b64 vcc, -1, 0
	v_cndmask_b32_e32 v237, v52, v225, vcc
	v_sub_f32_e32 v53, 0xf149f2ca, v52
	v_mul_f32_e32 v52, 0xbe0293ee, v237
	v_fmamk_f32 v18, v18, 0x3e0293ee, v52
	s_waitcnt vmcnt(4)
	s_waitcnt vmcnt(7)
	ds_write_b128 v221, v[54:57] offset:16384
	s_waitcnt vmcnt(6)
	ds_write_b128 v222, v[58:61] offset:16384
	s_waitcnt vmcnt(5)
	ds_write_b128 v219, v[62:65] offset:49152
	s_waitcnt vmcnt(4)
	ds_write_b128 v220, v[66:69] offset:49152
	v_exp_f32_e32 v66, v18
	v_fmamk_f32 v18, v19, 0x3e0293ee, v52
	v_exp_f32_e32 v67, v18
	v_fmamk_f32 v18, v20, 0x3e0293ee, v52
	v_exp_f32_e32 v68, v18
	v_fmamk_f32 v18, v21, 0x3e0293ee, v52
	v_exp_f32_e32 v69, v18
	v_fmamk_f32 v18, v22, 0x3e0293ee, v52
	v_exp_f32_e32 v70, v18
	v_fmamk_f32 v18, v23, 0x3e0293ee, v52
	v_exp_f32_e32 v71, v18
	v_fmamk_f32 v18, v24, 0x3e0293ee, v52
	v_exp_f32_e32 v72, v18
	v_fmamk_f32 v18, v25, 0x3e0293ee, v52
	v_exp_f32_e32 v73, v18
	v_fmamk_f32 v18, v26, 0x3e0293ee, v52
	v_mul_f32_e32 v53, 0x3e0293ee, v53
	v_exp_f32_e32 v74, v18
	v_fmamk_f32 v18, v27, 0x3e0293ee, v52
	v_exp_f32_e32 v53, v53
	v_exp_f32_e32 v75, v18
	v_fmamk_f32 v18, v28, 0x3e0293ee, v52
	v_mov_b64_e32 v[16:17], s[30:31]
	v_exp_f32_e32 v76, v18
	v_fmamk_f32 v18, v29, 0x3e0293ee, v52
	s_lshr_b32 s16, s48, 1
	v_exp_f32_e32 v77, v18
	v_fmamk_f32 v18, v30, 0x3e0293ee, v52
	s_addk_i32 s4, 0x4000
	s_lshl_b64 s[16:17], s[16:17], 8
	v_exp_f32_e32 v78, v18
	v_fmamk_f32 v18, v31, 0x3e0293ee, v52
	v_add_u32_e32 v216, s4, v99
	s_add_u32 s4, s33, s16
	v_fma_f32 v96, v48, s12, v52
	v_fma_f32 v97, v49, s12, v52
	v_fma_f32 v94, v46, s12, v52
	v_fma_f32 v95, v47, s12, v52
	v_fma_f32 v92, v44, s12, v52
	v_fma_f32 v93, v45, s12, v52
	v_fma_f32 v90, v42, s12, v52
	v_fma_f32 v91, v43, s12, v52
	v_fma_f32 v88, v40, s12, v52
	v_fma_f32 v89, v41, s12, v52
	v_fma_f32 v86, v38, s12, v52
	v_fma_f32 v87, v39, s12, v52
	v_fma_f32 v84, v36, s12, v52
	v_fma_f32 v85, v37, s12, v52
	v_fma_f32 v82, v34, s12, v52
	v_fma_f32 v83, v35, s12, v52
	v_exp_f32_e32 v79, v18
	v_fmamk_f32 v18, v32, 0x3e0293ee, v52
	v_fmac_f32_e32 v52, 0x3e0293ee, v33
	s_addc_u32 s5, s97, s17
	v_exp_f32_e32 v80, v18
	v_exp_f32_e32 v81, v52
	s_add_u32 s16, s13, s4
	s_addc_u32 s17, s50, s5
	v_cndmask_b32_e64 v234, v53, 1.0, vcc
	v_lshl_add_u64 v[212:213], s[16:17], 0, v[50:51]
	v_mov_b64_e32 v[32:33], v[16:17]
	v_mov_b64_e32 v[48:49], v[16:17]
	v_mov_b64_e32 v[64:65], v[16:17]
	v_mov_b64_e32 v[30:31], v[14:15]
	v_mov_b64_e32 v[28:29], v[12:13]
	v_mov_b64_e32 v[26:27], v[10:11]
	v_mov_b64_e32 v[24:25], v[8:9]
	v_mov_b64_e32 v[22:23], v[6:7]
	v_mov_b64_e32 v[20:21], v[4:5]
	v_mov_b64_e32 v[18:19], v[2:3]
	v_mov_b64_e32 v[46:47], v[14:15]
	v_mov_b64_e32 v[44:45], v[12:13]
	v_mov_b64_e32 v[42:43], v[10:11]
	v_mov_b64_e32 v[40:41], v[8:9]
	v_mov_b64_e32 v[38:39], v[6:7]
	v_mov_b64_e32 v[36:37], v[4:5]
	v_mov_b64_e32 v[34:35], v[2:3]
	v_mov_b64_e32 v[62:63], v[14:15]
	v_mov_b64_e32 v[60:61], v[12:13]
	v_mov_b64_e32 v[58:59], v[10:11]
	v_mov_b64_e32 v[56:57], v[8:9]
	v_mov_b64_e32 v[54:55], v[6:7]
	v_mov_b64_e32 v[52:53], v[4:5]
	v_mov_b64_e32 v[50:51], v[2:3]
	s_waitcnt lgkmcnt(0)
	s_barrier
; #define SBAR() __builtin_amdgcn_sched_barrier(0)
; #define SLOAD(i, k0) do { const long to_ = (long)(k0) * ldk * 2; const char* vt_ = (const char*)Vh + to_; const char* kt_ = (const char*)Kh + to_; \
;     sr_[i].vs0 = *(const bf16x8*)(vt_ + toff); sr_[i].vs1 = *(const bf16x8*)(vt_ + h32 + toff); \
;     sr_[i].ks0 = *(const bf16x8*)(kt_ + toff); sr_[i].ks1 = *(const bf16x8*)(kt_ + h32 + toff); } while (0)
; __device__ __forceinline__ void finishSM(f32x16& p0, f32x16& p1, float alpha, float& l_reg, bf16x8& pa0, bf16x8& pa1, bf16x8& pa2, bf16x8& pa3) {
;   for (int r = 0; r < 16; ++r) p1[r] = __builtin_amdgcn_exp2f(p1[r]);
;   float ps = 0; for (int r = 0; r < 16; ++r) ps += p0[r]; for (int r = 0; r < 16; ++r) ps += p1[r];
;   { auto rr = __builtin_amdgcn_permlane32_swap(__float_as_uint(ps), __float_as_uint(ps), false, false);
;     ps = __uint_as_float(rr[0]) + __uint_as_float(rr[1]); }
;   l_reg = l_reg * alpha + ps;
;     ...
;   PK4(p0, 0, pa0); PK4(p0, 8, pa1); PK4(p1, 0, pa2); PK4(p1, 8, pa3);
;     ...
; }
; template <int MODE, int QMODE> ...
;     ...
;     SBAR(); qkt(pB0, pB1, (bf16*)((char*)K_lds + SHM_K), qr, r32, hi);
;     finishSM(pA0, pA1, alA, l_reg, pa0, pa1, pa2, pa3); SBAR();
;     SLOAD(SO, (j + SDEPTH) * KVBLK); SBAR();
;     PVSM(vb0, pB0, pB1, j * KVBLK, mnB, alB);
.LBB0_171:
	ds_read_b128 v[98:101], v218 offset:49152
	ds_read_b128 v[102:105], v218 offset:57344
	ds_read_b128 v[178:181], v223 offset:49152
	ds_read_b128 v[182:185], v223 offset:57344
	ds_read_b128 v[186:189], v227 offset:49152
	ds_read_b128 v[190:193], v227 offset:57344
	v_exp_f32_e32 v82, v82
	v_exp_f32_e32 v83, v83
	s_waitcnt lgkmcnt(5)
	v_mfma_f32_32x32x16_bf16 v[114:129], v[98:101], v[134:137], 0
	v_exp_f32_e32 v84, v84
	v_exp_f32_e32 v85, v85
	v_exp_f32_e32 v86, v86
	v_exp_f32_e32 v87, v87
	v_exp_f32_e32 v88, v88
	v_exp_f32_e32 v89, v89
	v_exp_f32_e32 v90, v90
	s_waitcnt lgkmcnt(4)
	v_mfma_f32_32x32x16_bf16 v[98:113], v[102:105], v[134:137], 0
	v_exp_f32_e32 v91, v91
	v_exp_f32_e32 v92, v92
	v_exp_f32_e32 v93, v93
	v_exp_f32_e32 v94, v94
	v_exp_f32_e32 v95, v95
	v_exp_f32_e32 v96, v96
	v_exp_f32_e32 v97, v97
	s_waitcnt lgkmcnt(2)
	v_mfma_f32_32x32x16_bf16 v[98:113], v[182:185], v[142:145], v[98:113]
	v_mfma_f32_32x32x16_bf16 v[114:129], v[178:181], v[142:145], v[114:129]
	ds_read_b128 v[178:181], v228 offset:49152
	ds_read_b128 v[194:197], v228 offset:57344
	ds_read_b128 v[198:201], v229 offset:49152
	ds_read_b128 v[202:205], v229 offset:57344
	ds_read_b128 v[206:209], v231 offset:49152
	ds_read_b128 v[238:241], v231 offset:57344
	ds_read_b128 v[242:245], v230 offset:49152
	ds_read_b128 v[246:249], v230 offset:57344
	ds_read_b128 v[182:185], v232 offset:49152
	ds_read_b128 v[250:253], v232 offset:57344
	s_waitcnt lgkmcnt(10)
	v_mfma_f32_32x32x16_bf16 v[98:113], v[190:193], v[130:133], v[98:113]
	v_mfma_f32_32x32x16_bf16 v[114:129], v[186:189], v[130:133], v[114:129]
	v_add_f32_e32 v186, 0, v66
	v_add_f32_e32 v186, v67, v186
	v_add_f32_e32 v186, v68, v186
	s_waitcnt lgkmcnt(8)
	v_mfma_f32_32x32x16_bf16 v[98:113], v[194:197], v[138:141], v[98:113]
	v_cvt_pk_bf16_f32 v194, v66, v67
	v_cvt_pk_bf16_f32 v195, v68, v69
	v_cvt_pk_bf16_f32 v196, v70, v71
	v_cvt_pk_bf16_f32 v197, v72, v73
	s_nop 0
	v_permlane32_swap_b32_e32 v194, v196
	v_mfma_f32_32x32x16_bf16 v[114:129], v[178:181], v[138:141], v[114:129]
	v_add_f32_e32 v178, v69, v186
	v_add_f32_e32 v178, v70, v178
	v_add_f32_e32 v178, v71, v178
	v_add_f32_e32 v178, v72, v178
	v_add_f32_e32 v178, v73, v178
	v_add_f32_e32 v178, v74, v178
	v_add_f32_e32 v178, v75, v178
	s_waitcnt lgkmcnt(6)
	v_mfma_f32_32x32x16_bf16 v[98:113], v[202:205], v[150:153], v[98:113]
	v_add_f32_e32 v178, v76, v178
	v_add_f32_e32 v178, v77, v178
	v_add_f32_e32 v178, v78, v178
	v_add_f32_e32 v178, v79, v178
	v_add_f32_e32 v178, v80, v178
	v_add_f32_e32 v178, v81, v178
	v_add_f32_e32 v178, v82, v178
	v_mfma_f32_32x32x16_bf16 v[114:129], v[198:201], v[150:153], v[114:129]
	v_add_f32_e32 v178, v83, v178
	v_add_f32_e32 v178, v84, v178
	v_add_f32_e32 v178, v85, v178
	v_add_f32_e32 v178, v86, v178
	v_add_f32_e32 v178, v87, v178
	v_add_f32_e32 v178, v88, v178
	v_add_f32_e32 v178, v89, v178
	s_waitcnt lgkmcnt(4)
	v_mfma_f32_32x32x16_bf16 v[98:113], v[238:241], v[158:161], v[98:113]
	v_add_f32_e32 v178, v90, v178
	v_add_f32_e32 v178, v91, v178
	v_add_f32_e32 v178, v92, v178
	v_add_f32_e32 v178, v93, v178
	v_add_f32_e32 v178, v94, v178
	v_add_f32_e32 v178, v95, v178
	v_add_f32_e32 v178, v96, v178
	v_mfma_f32_32x32x16_bf16 v[114:129], v[206:209], v[158:161], v[114:129]
	v_add_f32_e32 v233, v97, v178
	v_mov_b32_e32 v235, v233
	s_nop 1
	v_permlane32_swap_b32_e32 v233, v235
	v_cvt_pk_bf16_f32 v198, v74, v75
	v_cvt_pk_bf16_f32 v199, v76, v77
	v_cvt_pk_bf16_f32 v200, v78, v79
	s_waitcnt lgkmcnt(2)
	v_mfma_f32_32x32x16_bf16 v[98:113], v[246:249], v[146:149], v[98:113]
	v_cvt_pk_bf16_f32 v201, v80, v81
	v_cvt_pk_bf16_f32 v206, v82, v83
	v_cvt_pk_bf16_f32 v207, v84, v85
	v_cvt_pk_bf16_f32 v208, v86, v87
	v_cvt_pk_bf16_f32 v209, v88, v89
	v_cvt_pk_bf16_f32 v202, v90, v91
	v_cvt_pk_bf16_f32 v203, v92, v93
	v_mfma_f32_32x32x16_bf16 v[114:129], v[242:245], v[146:149], v[114:129]
	v_cvt_pk_bf16_f32 v204, v94, v95
	v_cvt_pk_bf16_f32 v205, v96, v97
	v_permlane32_swap_b32_e32 v195, v197
	v_permlane32_swap_b32_e32 v198, v200
	v_permlane32_swap_b32_e32 v199, v201
	s_waitcnt lgkmcnt(0)
	v_mfma_f32_32x32x16_bf16 v[98:113], v[250:253], v[154:157], v[98:113]
	v_permlane32_swap_b32_e32 v206, v208
	v_permlane32_swap_b32_e32 v207, v209
	v_permlane32_swap_b32_e32 v202, v204
	v_permlane32_swap_b32_e32 v203, v205
	v_mfma_f32_32x32x16_bf16 v[114:129], v[182:185], v[154:157], v[114:129]
	v_add_co_u32_e32 v66, vcc, s67, v212
	s_nop 1
	v_addc_co_u32_e32 v67, vcc, -1, v213, vcc
	v_add_co_u32_e32 v68, vcc, s80, v212
	s_nop 1
	v_addc_co_u32_e32 v69, vcc, -1, v213, vcc
	global_load_dwordx4 v[178:181], v[66:67], off
	global_load_dwordx4 v[182:185], v[66:67], off offset:-512
	global_load_dwordx4 v[190:193], v[68:69], off
	global_load_dwordx4 v[186:189], v[68:69], off offset:-512
	ds_read_b64_tr_b16 v[66:67], v217 offset:0
	ds_read_b64_tr_b16 v[68:69], v217 offset:0x800
	ds_read_b64_tr_b16 v[70:71], v217 offset:0x1000
	ds_read_b64_tr_b16 v[72:73], v217 offset:0x1800
	ds_read_b64_tr_b16 v[74:75], v217 offset:0x2000
	ds_read_b64_tr_b16 v[76:77], v217 offset:0x2800
	ds_read_b64_tr_b16 v[78:79], v217 offset:0x3000
	ds_read_b64_tr_b16 v[80:81], v217 offset:0x3800
	s_waitcnt lgkmcnt(0)
	s_nop 0
	v_mfma_f32_32x32x16_bf16 v[50:65], v[194:197], v[66:69], v[50:65]
	v_max_f32_e32 v66, v114, v115
	v_max3_f32 v66, v66, v116, v117
	v_max3_f32 v66, v66, v118, v119
	v_max3_f32 v66, v66, v120, v121
	v_max3_f32 v66, v66, v122, v123
	v_mfma_f32_32x32x16_bf16 v[50:65], v[198:201], v[70:73], v[50:65]
	v_max3_f32 v66, v66, v124, v125
	v_max3_f32 v68, v66, v126, v127
	ds_read_b64_tr_b16 v[66:67], v217 offset:0x200
	v_max3_f32 v86, v68, v128, v129
	ds_read_b64_tr_b16 v[68:69], v217 offset:0xa00
	ds_read_b64_tr_b16 v[70:71], v217 offset:0x1200
	ds_read_b64_tr_b16 v[72:73], v217 offset:0x1a00
	v_mfma_f32_32x32x16_bf16 v[50:65], v[206:209], v[74:77], v[50:65]
	ds_read_b64_tr_b16 v[74:75], v217 offset:0x2200
	ds_read_b64_tr_b16 v[76:77], v217 offset:0x2a00
	ds_read_b64_tr_b16 v[82:83], v217 offset:0x3200
	ds_read_b64_tr_b16 v[84:85], v217 offset:0x3a00
	s_waitcnt lgkmcnt(0)
; __device__ __forceinline__ void psm_decide(float pmax, const f32x16& p1, float& m_reg, float& mn, float& alpha) {
;   constexpr float C = SCALE * 1.4426950408889634f;
;   for (int r = 0; r < 16; ++r) pmax = fmaxf(pmax, p1[r]);
;   { auto rr = __builtin_amdgcn_permlane32_swap(__float_as_uint(pmax), __float_as_uint(pmax), false, false);
;     pmax = fmaxf(__uint_as_float(rr[0]), __uint_as_float(rr[1])); }
;   if (__builtin_expect(__all(pmax - m_reg <= THR / SCALE), 1)) { mn = m_reg; alpha = 1.f; }
;   else { mn = fmaxf(m_reg, pmax); alpha = __builtin_amdgcn_exp2f((m_reg - mn) * C); m_reg = mn; }
; }
; __device__ __forceinline__ void psm_scale(f32x16& p0, f32x16& p1, float mn) {
;   constexpr float C = SCALE * 1.4426950408889634f; const float mnC = -mn * C;
;   for (int r = 0; r < 16; ++r) p0[r] = fmaf(p0[r], C, mnC); for (int r = 0; r < 16; ++r) p1[r] = fmaf(p1[r], C, mnC);
; }
	v_mfma_f32_32x32x16_bf16 v[50:65], v[202:205], v[78:81], v[50:65]
	v_mfma_f32_32x32x16_bf16 v[34:49], v[194:197], v[66:69], v[34:49]
	v_max3_f32 v78, v86, v98, v99
	v_max3_f32 v78, v78, v100, v101
	v_max3_f32 v78, v78, v102, v103
	v_max3_f32 v78, v78, v104, v105
	v_max3_f32 v78, v78, v106, v107
	v_max3_f32 v78, v78, v108, v109
	v_max3_f32 v66, v78, v110, v111
	v_max3_f32 v66, v66, v112, v113
	v_mfma_f32_32x32x16_bf16 v[34:49], v[198:201], v[70:73], v[34:49]
	v_mov_b32_e32 v67, v66
	s_nop 1
	v_permlane32_swap_b32_e32 v66, v67
	v_max_f32_e32 v66, v66, v67
	v_sub_f32_e32 v67, v66, v237
	v_cmp_ge_f32_e32 vcc, s62, v67
	v_max_f32_e32 v66, v237, v66
	v_sub_f32_e32 v67, v237, v66
	v_mfma_f32_32x32x16_bf16 v[34:49], v[206:209], v[74:77], v[34:49]
	v_mul_f32_e32 v67, 0x3e0293ee, v67
	v_exp_f32_e32 v67, v67
	s_cmp_eq_u64 vcc, exec
	s_cselect_b64 vcc, -1, 0
	v_cndmask_b32_e32 v236, v66, v237, vcc
	v_cndmask_b32_e64 v238, v67, 1.0, vcc
	ds_read_b64_tr_b16 v[66:67], v217 offset:0x400
	ds_read_b64_tr_b16 v[68:69], v217 offset:0xc00
	v_mfma_f32_32x32x16_bf16 v[34:49], v[202:205], v[82:85], v[34:49]
	ds_read_b64_tr_b16 v[82:83], v217 offset:0x1400
	ds_read_b64_tr_b16 v[84:85], v217 offset:0x1c00
	ds_read_b64_tr_b16 v[240:241], v217 offset:0x2400
	ds_read_b64_tr_b16 v[242:243], v217 offset:0x2c00
	ds_read_b64_tr_b16 v[244:245], v217 offset:0x3400
	ds_read_b64_tr_b16 v[246:247], v217 offset:0x3c00
	s_waitcnt lgkmcnt(0)
	v_mfma_f32_32x32x16_bf16 v[18:33], v[194:197], v[66:69], v[18:33]
	v_mul_f32_e32 v248, 0xbe0293ee, v236
	v_fma_f32 v80, v128, s12, v248
	v_fma_f32 v81, v129, s12, v248
	v_fma_f32 v78, v126, s12, v248
	v_fma_f32 v79, v127, s12, v248
	v_fma_f32 v76, v124, s12, v248
	v_fma_f32 v77, v125, s12, v248
	v_fma_f32 v74, v122, s12, v248
	v_fma_f32 v75, v123, s12, v248
	v_fma_f32 v72, v120, s12, v248
	v_fma_f32 v73, v121, s12, v248
	v_fma_f32 v70, v118, s12, v248
	v_fma_f32 v71, v119, s12, v248
	v_mfma_f32_32x32x16_bf16 v[18:33], v[198:201], v[82:85], v[18:33]
	v_fma_f32 v68, v116, s12, v248
	v_fma_f32 v69, v117, s12, v248
	v_fma_f32 v66, v114, s12, v248
	v_fma_f32 v67, v115, s12, v248
	v_fma_f32 v96, v112, s12, v248
	v_fma_f32 v97, v113, s12, v248
	v_fma_f32 v94, v110, s12, v248
	v_fma_f32 v95, v111, s12, v248
	v_fma_f32 v92, v108, s12, v248
	v_fma_f32 v93, v109, s12, v248
	v_fma_f32 v90, v106, s12, v248
	v_fma_f32 v91, v107, s12, v248
	v_fma_f32 v88, v104, s12, v248
	v_fma_f32 v89, v105, s12, v248
	v_mfma_f32_32x32x16_bf16 v[18:33], v[206:209], v[240:243], v[18:33]
	v_fma_f32 v86, v102, s12, v248
	v_fma_f32 v87, v103, s12, v248
	v_fma_f32 v84, v100, s12, v248
	v_fma_f32 v85, v101, s12, v248
	v_fma_f32 v82, v98, s12, v248
	v_fma_f32 v83, v99, s12, v248
	ds_read_b64_tr_b16 v[98:99], v217 offset:0x600
	ds_read_b64_tr_b16 v[100:101], v217 offset:0xe00
	ds_read_b64_tr_b16 v[102:103], v217 offset:0x1600
	ds_read_b64_tr_b16 v[104:105], v217 offset:0x1e00
	v_mfma_f32_32x32x16_bf16 v[18:33], v[202:205], v[244:247], v[18:33]
	ds_read_b64_tr_b16 v[108:109], v217 offset:0x2600
	ds_read_b64_tr_b16 v[110:111], v217 offset:0x2e00
	ds_read_b64_tr_b16 v[114:115], v217 offset:0x3600
	ds_read_b64_tr_b16 v[116:117], v217 offset:0x3e00
	s_waitcnt lgkmcnt(0)
	v_mfma_f32_32x32x16_bf16 v[2:17], v[194:197], v[98:101], v[2:17]
	v_exp_f32_e32 v98, v66
	v_exp_f32_e32 v99, v67
	v_exp_f32_e32 v100, v68
	v_exp_f32_e32 v101, v69
	v_exp_f32_e32 v106, v74
	v_exp_f32_e32 v107, v75
	v_exp_f32_e32 v112, v80
	v_mfma_f32_32x32x16_bf16 v[2:17], v[198:201], v[102:105], v[2:17]
	v_exp_f32_e32 v102, v70
	v_exp_f32_e32 v103, v71
	v_exp_f32_e32 v104, v72
	v_exp_f32_e32 v105, v73
	v_exp_f32_e32 v113, v81
	v_mfma_f32_32x32x16_bf16 v[2:17], v[206:209], v[108:111], v[2:17]
	v_exp_f32_e32 v108, v76
	v_exp_f32_e32 v109, v77
	v_exp_f32_e32 v110, v78
	v_exp_f32_e32 v111, v79
	v_mfma_f32_32x32x16_bf16 v[2:17], v[202:205], v[114:117], v[2:17]
	s_waitcnt vmcnt(4)
	v_cmp_gt_f32_e32 vcc, 1.0, v238
	ds_write_b128 v219, v[174:177] offset:32768
	ds_write_b128 v220, v[162:165] offset:32768
	s_cbranch_vccz .LBB0_175
	s_and_saveexec_b64 s[16:17], s[2:3]
	ds_write_b32 v214, v238 offset:128
	s_or_b64 exec, exec, s[16:17]
	s_waitcnt lgkmcnt(0)
	v_add_u32_e32 v78, s95, v210
	ds_read_b128 v[66:69], v78 offset:224
	ds_read_b128 v[70:73], v78 offset:192
	ds_read_b128 v[74:77], v78 offset:160
	ds_read_b128 v[78:81], v78 offset:128
	s_waitcnt lgkmcnt(3)
	v_pk_mul_f32 v[62:63], v[62:63], v[66:67]
	s_waitcnt lgkmcnt(2)
	v_pk_mul_f32 v[58:59], v[58:59], v[70:71]
	s_waitcnt lgkmcnt(1)
	v_pk_mul_f32 v[54:55], v[54:55], v[74:75]
	v_pk_mul_f32 v[64:65], v[64:65], v[68:69]
	v_pk_mul_f32 v[60:61], v[60:61], v[72:73]
	v_pk_mul_f32 v[56:57], v[56:57], v[76:77]
	s_waitcnt lgkmcnt(0)
	v_pk_mul_f32 v[52:53], v[52:53], v[80:81]
	v_pk_mul_f32 v[50:51], v[50:51], v[78:79]
	v_pk_mul_f32 v[46:47], v[46:47], v[66:67]
	v_pk_mul_f32 v[42:43], v[42:43], v[70:71]
	v_pk_mul_f32 v[38:39], v[38:39], v[74:75]
	v_pk_mul_f32 v[48:49], v[48:49], v[68:69]
	v_pk_mul_f32 v[44:45], v[44:45], v[72:73]
	v_pk_mul_f32 v[40:41], v[40:41], v[76:77]
	v_pk_mul_f32 v[36:37], v[36:37], v[80:81]
	v_pk_mul_f32 v[34:35], v[34:35], v[78:79]
	v_pk_mul_f32 v[30:31], v[30:31], v[66:67]
	v_pk_mul_f32 v[26:27], v[26:27], v[70:71]
	v_pk_mul_f32 v[22:23], v[22:23], v[74:75]
	v_pk_mul_f32 v[32:33], v[32:33], v[68:69]
	v_pk_mul_f32 v[28:29], v[28:29], v[72:73]
	v_pk_mul_f32 v[24:25], v[24:25], v[76:77]
	v_pk_mul_f32 v[20:21], v[20:21], v[80:81]
	v_pk_mul_f32 v[18:19], v[18:19], v[78:79]
	v_pk_mul_f32 v[14:15], v[14:15], v[66:67]
	v_pk_mul_f32 v[10:11], v[10:11], v[70:71]
	v_pk_mul_f32 v[6:7], v[6:7], v[74:75]
	v_pk_mul_f32 v[16:17], v[16:17], v[68:69]
	v_pk_mul_f32 v[12:13], v[12:13], v[72:73]
	v_pk_mul_f32 v[8:9], v[8:9], v[76:77]
	v_pk_mul_f32 v[4:5], v[4:5], v[80:81]
	v_pk_mul_f32 v[2:3], v[2:3], v[78:79]

; #define SBAR() __builtin_amdgcn_sched_barrier(0)
; #define SLOAD(i, k0) do { const long to_ = (long)(k0) * ldk * 2; const char* vt_ = (const char*)Vh + to_; const char* kt_ = (const char*)Kh + to_; \
;     sr_[i].vs0 = *(const bf16x8*)(vt_ + toff); sr_[i].vs1 = *(const bf16x8*)(vt_ + h32 + toff); \
;     sr_[i].ks0 = *(const bf16x8*)(kt_ + toff); sr_[i].ks1 = *(const bf16x8*)(kt_ + h32 + toff); } while (0)
; template <int MODE, int QMODE> ...
;     ...
;     SBAR(); qkt(pA0, pA1, K_lds, qr, r32, hi);
;     finishSM(pB0, pB1, alB, l_reg, pa0, pa1, pa2, pa3); SBAR();
;     if (SDEPTH == 1 || j + 3 < NT) SLOAD(SE, (j + 1 + SDEPTH) * KVBLK); SBAR();
;     PVSM(vb0 + (int)SHM_V, pA0, pA1, (j + 1) * KVBLK, mnA, alA);
.LBB0_177:
	ds_read_b64_tr_b16 v[82:83], v216 offset:0
	ds_read_b64_tr_b16 v[84:85], v216 offset:0x800
	ds_read_b64_tr_b16 v[86:87], v216 offset:0x1000
	ds_read_b64_tr_b16 v[88:89], v216 offset:0x1800
	ds_read_b64_tr_b16 v[90:91], v216 offset:0x2000
	ds_read_b64_tr_b16 v[92:93], v216 offset:0x2800
	ds_read_b64_tr_b16 v[94:95], v216 offset:0x3000
	ds_read_b64_tr_b16 v[96:97], v216 offset:0x3800
	s_waitcnt lgkmcnt(0)
	s_nop 0
	v_mfma_f32_32x32x16_bf16 v[50:65], v[206:209], v[82:85], v[50:65]
	v_max_f32_e32 v82, v114, v115
	v_max3_f32 v82, v82, v116, v117
	v_max3_f32 v82, v82, v118, v119
	v_max3_f32 v82, v82, v120, v121
	v_max3_f32 v82, v82, v122, v123
	v_mfma_f32_32x32x16_bf16 v[50:65], v[198:201], v[86:89], v[50:65]
	v_max3_f32 v82, v82, v124, v125
	v_max3_f32 v84, v82, v126, v127
	ds_read_b64_tr_b16 v[82:83], v216 offset:0x200
	v_max3_f32 v102, v84, v128, v129
	ds_read_b64_tr_b16 v[84:85], v216 offset:0xa00
	ds_read_b64_tr_b16 v[86:87], v216 offset:0x1200
	ds_read_b64_tr_b16 v[88:89], v216 offset:0x1a00
	v_mfma_f32_32x32x16_bf16 v[50:65], v[202:205], v[90:93], v[50:65]
	ds_read_b64_tr_b16 v[90:91], v216 offset:0x2200
	ds_read_b64_tr_b16 v[92:93], v216 offset:0x2a00
	ds_read_b64_tr_b16 v[98:99], v216 offset:0x3200
	ds_read_b64_tr_b16 v[100:101], v216 offset:0x3a00
	s_waitcnt lgkmcnt(0)
	v_mfma_f32_32x32x16_bf16 v[50:65], v[194:197], v[94:97], v[50:65]
	v_max3_f32 v94, v102, v66, v67
	v_mfma_f32_32x32x16_bf16 v[34:49], v[206:209], v[82:85], v[34:49]
	v_max3_f32 v94, v94, v68, v69
	v_max3_f32 v94, v94, v70, v71
	v_max3_f32 v94, v94, v72, v73
	v_max3_f32 v94, v94, v74, v75
	v_max3_f32 v94, v94, v76, v77
	v_max3_f32 v82, v94, v78, v79
	v_max3_f32 v82, v82, v80, v81
	v_mov_b32_e32 v83, v82
	v_mfma_f32_32x32x16_bf16 v[34:49], v[198:201], v[86:89], v[34:49]
	s_nop 0
	v_permlane32_swap_b32_e32 v82, v83
	v_max_f32_e32 v82, v82, v83
	v_sub_f32_e32 v83, v82, v236
	v_cmp_ge_f32_e32 vcc, s62, v83
	v_max_f32_e32 v82, v236, v82
	v_sub_f32_e32 v83, v236, v82
	v_mul_f32_e32 v83, 0x3e0293ee, v83
	v_mfma_f32_32x32x16_bf16 v[34:49], v[202:205], v[90:93], v[34:49]
	v_exp_f32_e32 v83, v83
	s_cmp_eq_u64 vcc, exec
	s_cselect_b64 vcc, -1, 0
	v_cndmask_b32_e32 v237, v82, v236, vcc
	v_cndmask_b32_e64 v236, v83, 1.0, vcc
	ds_read_b64_tr_b16 v[82:83], v216 offset:0x400
	ds_read_b64_tr_b16 v[84:85], v216 offset:0xc00
	ds_read_b64_tr_b16 v[86:87], v216 offset:0x1400
	v_mfma_f32_32x32x16_bf16 v[34:49], v[194:197], v[98:101], v[34:49]
	ds_read_b64_tr_b16 v[88:89], v216 offset:0x1c00
	ds_read_b64_tr_b16 v[242:243], v216 offset:0x2400
	ds_read_b64_tr_b16 v[244:245], v216 offset:0x2c00
	ds_read_b64_tr_b16 v[246:247], v216 offset:0x3400
	ds_read_b64_tr_b16 v[248:249], v216 offset:0x3c00
	s_waitcnt lgkmcnt(0)
	v_mfma_f32_32x32x16_bf16 v[18:33], v[206:209], v[82:85], v[18:33]
	v_mul_f32_e32 v250, 0xbe0293ee, v237
	v_fma_f32 v112, v128, s12, v250
	v_fma_f32 v113, v129, s12, v250
	v_fma_f32 v110, v126, s12, v250
	v_fma_f32 v111, v127, s12, v250
	v_fma_f32 v108, v124, s12, v250
	v_fma_f32 v109, v125, s12, v250
	v_fma_f32 v106, v122, s12, v250
	v_fma_f32 v107, v123, s12, v250
	v_fma_f32 v104, v120, s12, v250
	v_fma_f32 v105, v121, s12, v250
	v_fma_f32 v102, v118, s12, v250
	v_fma_f32 v103, v119, s12, v250
	v_mfma_f32_32x32x16_bf16 v[18:33], v[198:201], v[86:89], v[18:33]
	v_fma_f32 v100, v116, s12, v250
	v_fma_f32 v101, v117, s12, v250
	v_fma_f32 v98, v114, s12, v250
	v_fma_f32 v99, v115, s12, v250
	v_fma_f32 v96, v80, s12, v250
	v_fma_f32 v97, v81, s12, v250
	v_fma_f32 v94, v78, s12, v250
	v_fma_f32 v95, v79, s12, v250
	v_fma_f32 v92, v76, s12, v250
	v_fma_f32 v93, v77, s12, v250
	v_fma_f32 v90, v74, s12, v250
	v_fma_f32 v91, v75, s12, v250
	v_fma_f32 v88, v72, s12, v250
	v_fma_f32 v89, v73, s12, v250
	v_mfma_f32_32x32x16_bf16 v[18:33], v[202:205], v[242:245], v[18:33]
	v_fma_f32 v86, v70, s12, v250
	v_fma_f32 v87, v71, s12, v250
	v_fma_f32 v84, v68, s12, v250
	v_fma_f32 v85, v69, s12, v250
	v_fma_f32 v82, v66, s12, v250
	v_fma_f32 v83, v67, s12, v250
	ds_read_b64_tr_b16 v[66:67], v216 offset:0x600
	ds_read_b64_tr_b16 v[68:69], v216 offset:0xe00
	ds_read_b64_tr_b16 v[70:71], v216 offset:0x1600
	ds_read_b64_tr_b16 v[72:73], v216 offset:0x1e00
	v_mfma_f32_32x32x16_bf16 v[18:33], v[194:197], v[246:249], v[18:33]
	ds_read_b64_tr_b16 v[76:77], v216 offset:0x2600
	ds_read_b64_tr_b16 v[78:79], v216 offset:0x2e00
	ds_read_b64_tr_b16 v[114:115], v216 offset:0x3600
	ds_read_b64_tr_b16 v[116:117], v216 offset:0x3e00
	s_waitcnt lgkmcnt(0)
	v_mfma_f32_32x32x16_bf16 v[2:17], v[206:209], v[66:69], v[2:17]
	v_exp_f32_e32 v66, v98
	v_exp_f32_e32 v67, v99
	v_exp_f32_e32 v68, v100
	v_exp_f32_e32 v69, v101
	v_exp_f32_e32 v74, v106
	v_exp_f32_e32 v75, v107
	v_exp_f32_e32 v80, v112
	v_mfma_f32_32x32x16_bf16 v[2:17], v[198:201], v[70:73], v[2:17]
	v_exp_f32_e32 v70, v102
	v_exp_f32_e32 v71, v103
	v_exp_f32_e32 v72, v104
	v_exp_f32_e32 v73, v105
	v_exp_f32_e32 v81, v113
	v_mfma_f32_32x32x16_bf16 v[2:17], v[202:205], v[76:79], v[2:17]
	v_exp_f32_e32 v76, v108
	v_exp_f32_e32 v77, v109
	v_exp_f32_e32 v78, v110
	v_exp_f32_e32 v79, v111
	v_mfma_f32_32x32x16_bf16 v[2:17], v[194:197], v[114:117], v[2:17]
	s_waitcnt vmcnt(4)
	s_cmp_ge_u32 s96, s94
	s_cbranch_scc0 .Lb_nodrain
	s_waitcnt vmcnt(0)

; #define SBAR() __builtin_amdgcn_sched_barrier(0)
; __device__ __forceinline__ void finishSM(f32x16& p0, f32x16& p1, float alpha, float& l_reg, bf16x8& pa0, bf16x8& pa1, bf16x8& pa2, bf16x8& pa3) {
;   for (int r = 0; r < 16; ++r) p1[r] = __builtin_amdgcn_exp2f(p1[r]);
;   float ps = 0; for (int r = 0; r < 16; ++r) ps += p0[r]; for (int r = 0; r < 16; ++r) ps += p1[r];
;   { auto rr = __builtin_amdgcn_permlane32_swap(__float_as_uint(ps), __float_as_uint(ps), false, false);
;     ps = __uint_as_float(rr[0]) + __uint_as_float(rr[1]); }
;   l_reg = l_reg * alpha + ps;
;     ...
;   PK4(p0, 0, pa0); PK4(p0, 8, pa1); PK4(p1, 0, pa2); PK4(p1, 8, pa3);
;     ...
; }
; template <int MODE, int QMODE> ...
;     ...
;   SBAR(); qkt(pB0, pB1, (bf16*)((char*)K_lds + SHM_K), qr, r32, hi);
;   finishSM(pA0, pA1, alA, l_reg, pa0, pa1, pa2, pa3); SBAR();
;   PVSM(vb0, pB0, pB1, (NT - 1) * KVBLK, mnB, alB);
.LBB0_183:
	ds_read_b128 v[98:101], v218 offset:49152
	ds_read_b128 v[102:105], v218 offset:57344
	v_exp_f32_e32 v82, v82
	v_exp_f32_e32 v83, v83
	v_exp_f32_e32 v84, v84
	s_waitcnt lgkmcnt(1)
	v_mfma_f32_32x32x16_bf16 v[114:129], v[98:101], v[134:137], 0
	v_exp_f32_e32 v85, v85
	v_exp_f32_e32 v86, v86
	v_exp_f32_e32 v87, v87
	v_exp_f32_e32 v88, v88
	v_exp_f32_e32 v89, v89
	v_exp_f32_e32 v90, v90
	v_exp_f32_e32 v91, v91
	s_waitcnt lgkmcnt(0)
	v_mfma_f32_32x32x16_bf16 v[98:113], v[102:105], v[134:137], 0
	ds_read_b128 v[134:137], v223 offset:49152
	ds_read_b128 v[162:165], v223 offset:57344
	ds_read_b128 v[166:169], v227 offset:49152
	ds_read_b128 v[170:173], v227 offset:57344
	v_exp_f32_e32 v92, v92
	v_exp_f32_e32 v93, v93
	v_exp_f32_e32 v94, v94
	v_exp_f32_e32 v95, v95
	v_exp_f32_e32 v96, v96
	v_exp_f32_e32 v97, v97
	s_waitcnt lgkmcnt(3)
	v_mfma_f32_32x32x16_bf16 v[114:129], v[134:137], v[142:145], v[114:129]
	ds_read_b128 v[134:137], v228 offset:49152
	ds_read_b128 v[174:177], v228 offset:57344
	ds_read_b128 v[178:181], v229 offset:49152
	ds_read_b128 v[182:185], v229 offset:57344
	ds_read_b128 v[186:189], v231 offset:49152
	ds_read_b128 v[190:193], v231 offset:57344
	ds_read_b128 v[194:197], v230 offset:49152
	ds_read_b128 v[198:201], v230 offset:57344
	s_waitcnt lgkmcnt(10)
	v_mfma_f32_32x32x16_bf16 v[98:113], v[162:165], v[142:145], v[98:113]
	ds_read_b128 v[162:165], v232 offset:49152
	ds_read_b128 v[202:205], v232 offset:57344
	s_waitcnt lgkmcnt(11)
	v_mfma_f32_32x32x16_bf16 v[114:129], v[166:169], v[130:133], v[114:129]
	s_waitcnt lgkmcnt(10)
	v_mfma_f32_32x32x16_bf16 v[98:113], v[170:173], v[130:133], v[98:113]
	v_add_f32_e32 v130, 0, v66
	v_add_f32_e32 v130, v67, v130
	v_add_f32_e32 v130, v68, v130
	v_add_f32_e32 v130, v69, v130
	v_add_f32_e32 v130, v70, v130
	v_add_f32_e32 v130, v71, v130
	v_add_f32_e32 v130, v72, v130
	s_waitcnt lgkmcnt(9)
	v_mfma_f32_32x32x16_bf16 v[114:129], v[134:137], v[138:141], v[114:129]
	v_add_f32_e32 v130, v73, v130
	v_add_f32_e32 v130, v74, v130
	v_add_f32_e32 v130, v75, v130
	v_add_f32_e32 v130, v76, v130
	v_add_f32_e32 v130, v77, v130
	v_add_f32_e32 v130, v78, v130
	v_add_f32_e32 v130, v79, v130
	s_waitcnt lgkmcnt(8)
	v_mfma_f32_32x32x16_bf16 v[98:113], v[174:177], v[138:141], v[98:113]
	v_add_f32_e32 v130, v80, v130
	v_add_f32_e32 v130, v81, v130
	v_add_f32_e32 v130, v82, v130
	v_add_f32_e32 v130, v83, v130
	v_add_f32_e32 v130, v84, v130
	v_add_f32_e32 v130, v85, v130
	v_add_f32_e32 v130, v86, v130
	s_waitcnt lgkmcnt(7)
	v_mfma_f32_32x32x16_bf16 v[114:129], v[178:181], v[150:153], v[114:129]
	v_add_f32_e32 v130, v87, v130
	v_add_f32_e32 v130, v88, v130
	v_add_f32_e32 v130, v89, v130
	v_add_f32_e32 v130, v90, v130
	v_add_f32_e32 v130, v91, v130
	v_add_f32_e32 v130, v92, v130
	v_add_f32_e32 v130, v93, v130
	s_waitcnt lgkmcnt(6)
	v_mfma_f32_32x32x16_bf16 v[98:113], v[182:185], v[150:153], v[98:113]
	v_add_f32_e32 v130, v94, v130
	v_add_f32_e32 v130, v95, v130
	v_add_f32_e32 v130, v96, v130
	v_add_f32_e32 v150, v97, v130
	v_mov_b32_e32 v151, v150
	s_nop 1
	v_permlane32_swap_b32_e32 v150, v151
	s_waitcnt lgkmcnt(5)
	v_mfma_f32_32x32x16_bf16 v[114:129], v[186:189], v[158:161], v[114:129]
	v_cvt_pk_bf16_f32 v130, v66, v67
	v_cvt_pk_bf16_f32 v131, v68, v69
	v_cvt_pk_bf16_f32 v132, v70, v71
	v_cvt_pk_bf16_f32 v133, v72, v73
	v_cvt_pk_bf16_f32 v134, v74, v75
	v_cvt_pk_bf16_f32 v135, v76, v77
	v_cvt_pk_bf16_f32 v136, v78, v79
	s_waitcnt lgkmcnt(4)
	v_mfma_f32_32x32x16_bf16 v[98:113], v[190:193], v[158:161], v[98:113]
	v_cvt_pk_bf16_f32 v137, v80, v81
	v_cvt_pk_bf16_f32 v142, v82, v83
	v_cvt_pk_bf16_f32 v143, v84, v85
	v_cvt_pk_bf16_f32 v144, v86, v87
	v_cvt_pk_bf16_f32 v145, v88, v89
	v_cvt_pk_bf16_f32 v138, v90, v91
	v_cvt_pk_bf16_f32 v139, v92, v93
	s_waitcnt lgkmcnt(3)
	v_mfma_f32_32x32x16_bf16 v[114:129], v[194:197], v[146:149], v[114:129]
	v_cvt_pk_bf16_f32 v140, v94, v95
	v_cvt_pk_bf16_f32 v141, v96, v97
	v_permlane32_swap_b32_e32 v130, v132
	v_permlane32_swap_b32_e32 v131, v133
	v_permlane32_swap_b32_e32 v134, v136
	s_waitcnt lgkmcnt(2)
	v_mfma_f32_32x32x16_bf16 v[98:113], v[198:201], v[146:149], v[98:113]
	v_permlane32_swap_b32_e32 v135, v137
	v_permlane32_swap_b32_e32 v142, v144
	v_permlane32_swap_b32_e32 v143, v145
	v_permlane32_swap_b32_e32 v138, v140
	s_waitcnt lgkmcnt(1)
	v_mfma_f32_32x32x16_bf16 v[114:129], v[162:165], v[154:157], v[114:129]
	v_permlane32_swap_b32_e32 v139, v141
	s_waitcnt lgkmcnt(0)
	v_mfma_f32_32x32x16_bf16 v[98:113], v[202:205], v[154:157], v[98:113]
	ds_read_b64_tr_b16 v[66:67], v217 offset:0
	ds_read_b64_tr_b16 v[68:69], v217 offset:0x800
	ds_read_b64_tr_b16 v[70:71], v217 offset:0x1000
	ds_read_b64_tr_b16 v[72:73], v217 offset:0x1800
	ds_read_b64_tr_b16 v[74:75], v217 offset:0x2000
	ds_read_b64_tr_b16 v[76:77], v217 offset:0x2800
	ds_read_b64_tr_b16 v[78:79], v217 offset:0x3000
	ds_read_b64_tr_b16 v[80:81], v217 offset:0x3800
	s_waitcnt lgkmcnt(0)
	s_nop 0
	v_mfma_f32_32x32x16_bf16 v[50:65], v[130:133], v[66:69], v[50:65]
	s_nop 6
	v_max_f32_e32 v66, v115, v115
	v_max_f32_e32 v67, v114, v114
	v_max_f32_e32 v66, v67, v66
	v_max3_f32 v66, v66, v116, v117
	v_max3_f32 v66, v66, v118, v119
	v_max3_f32 v66, v66, v120, v121
	v_max3_f32 v66, v66, v122, v123
	v_mfma_f32_32x32x16_bf16 v[50:65], v[134:137], v[70:73], v[50:65]
	v_max3_f32 v66, v66, v124, v125
	v_max3_f32 v68, v66, v126, v127
	ds_read_b64_tr_b16 v[66:67], v217 offset:0x200
	v_max3_f32 v86, v68, v128, v129
	ds_read_b64_tr_b16 v[68:69], v217 offset:0xa00
	ds_read_b64_tr_b16 v[70:71], v217 offset:0x1200
	ds_read_b64_tr_b16 v[72:73], v217 offset:0x1a00
	v_mfma_f32_32x32x16_bf16 v[50:65], v[142:145], v[74:77], v[50:65]
	ds_read_b64_tr_b16 v[74:75], v217 offset:0x2200
	ds_read_b64_tr_b16 v[76:77], v217 offset:0x2a00
	ds_read_b64_tr_b16 v[82:83], v217 offset:0x3200
	ds_read_b64_tr_b16 v[84:85], v217 offset:0x3a00
	s_waitcnt lgkmcnt(0)
; #define RESC(a) do { if (__any((a) < 1.f)) { if (hi == 0) al_l[r32] = (a); asm volatile("s_waitcnt lgkmcnt(0)" ::: "memory"); \
;     for (int d = 0; d < 4; ++d) for (int r = 0; r < 16; ++r) o[d][r] *= al_l[crow(r, hi)]; } } while (0)
; __device__ __forceinline__ void psm_decide(float pmax, const f32x16& p1, float& m_reg, float& mn, float& alpha) {
;   constexpr float C = SCALE * 1.4426950408889634f;
;   for (int r = 0; r < 16; ++r) pmax = fmaxf(pmax, p1[r]);
;   { auto rr = __builtin_amdgcn_permlane32_swap(__float_as_uint(pmax), __float_as_uint(pmax), false, false);
;     pmax = fmaxf(__uint_as_float(rr[0]), __uint_as_float(rr[1])); }
;   if (__builtin_expect(__all(pmax - m_reg <= THR / SCALE), 1)) { mn = m_reg; alpha = 1.f; }
;   else { mn = fmaxf(m_reg, pmax); alpha = __builtin_amdgcn_exp2f((m_reg - mn) * C); m_reg = mn; }
; }
; __device__ __forceinline__ void psm_scale(f32x16& p0, f32x16& p1, float mn) {
;   constexpr float C = SCALE * 1.4426950408889634f; const float mnC = -mn * C;
;   for (int r = 0; r < 16; ++r) p0[r] = fmaf(p0[r], C, mnC); for (int r = 0; r < 16; ++r) p1[r] = fmaf(p1[r], C, mnC);
; }
; template <int MODE, int QMODE> ...
;     ...
;   PVSM(vb0, pB0, pB1, (NT - 1) * KVBLK, mnB, alB);
;   __syncthreads(); RESC(alB);
	v_mfma_f32_32x32x16_bf16 v[50:65], v[138:141], v[78:81], v[50:65]
	v_max3_f32 v78, v86, v98, v99
	v_mfma_f32_32x32x16_bf16 v[34:49], v[130:133], v[66:69], v[34:49]
	v_max3_f32 v78, v78, v100, v101
	v_max3_f32 v78, v78, v102, v103
	v_max3_f32 v78, v78, v104, v105
	v_max3_f32 v78, v78, v106, v107
	v_max3_f32 v78, v78, v108, v109
	v_max3_f32 v66, v78, v110, v111
	v_max3_f32 v66, v66, v112, v113
	v_mov_b32_e32 v67, v66
	v_mfma_f32_32x32x16_bf16 v[34:49], v[134:137], v[70:73], v[34:49]
	s_nop 0
	v_permlane32_swap_b32_e32 v66, v67
	v_max_f32_e32 v67, v67, v67
	v_max_f32_e32 v66, v66, v66
	v_max_f32_e32 v66, v66, v67
	v_sub_f32_e32 v67, v66, v237
	v_cmp_ge_f32_e32 vcc, s62, v67
	v_max_f32_e32 v67, v237, v237
	v_max_f32_e32 v66, v67, v66
	v_sub_f32_e32 v67, v237, v66
	v_mul_f32_e32 v67, 0x3e0293ee, v67
	v_mfma_f32_32x32x16_bf16 v[34:49], v[142:145], v[74:77], v[34:49]
	v_exp_f32_e32 v67, v67
	s_cmp_eq_u64 vcc, exec
	s_cselect_b64 vcc, -1, 0
	v_cndmask_b32_e32 v74, v66, v237, vcc
	v_cndmask_b32_e64 v146, v67, 1.0, vcc
	ds_read_b64_tr_b16 v[66:67], v217 offset:0x400
	ds_read_b64_tr_b16 v[68:69], v217 offset:0xc00
	ds_read_b64_tr_b16 v[70:71], v217 offset:0x1400
	v_mfma_f32_32x32x16_bf16 v[34:49], v[138:141], v[82:85], v[34:49]
	ds_read_b64_tr_b16 v[72:73], v217 offset:0x1c00
	ds_read_b64_tr_b16 v[152:153], v217 offset:0x2400
	ds_read_b64_tr_b16 v[154:155], v217 offset:0x2c00
	ds_read_b64_tr_b16 v[156:157], v217 offset:0x3400
	ds_read_b64_tr_b16 v[158:159], v217 offset:0x3c00
	s_waitcnt lgkmcnt(0)
	v_mfma_f32_32x32x16_bf16 v[18:33], v[130:133], v[66:69], v[18:33]
	v_mul_f32_e32 v148, 0xbe0293ee, v74
	v_fma_f32 v96, v128, s12, v148
	v_fma_f32 v97, v129, s12, v148
	v_fma_f32 v94, v126, s12, v148
	v_fma_f32 v95, v127, s12, v148
	v_fma_f32 v92, v124, s12, v148
	v_fma_f32 v93, v125, s12, v148
	v_fma_f32 v90, v122, s12, v148
	v_fma_f32 v91, v123, s12, v148
	v_fma_f32 v88, v120, s12, v148
	v_fma_f32 v89, v121, s12, v148
	v_fma_f32 v86, v118, s12, v148
	v_fma_f32 v87, v119, s12, v148
	v_mfma_f32_32x32x16_bf16 v[18:33], v[134:137], v[70:73], v[18:33]
	v_fma_f32 v84, v116, s12, v148
	v_fma_f32 v85, v117, s12, v148
	v_fma_f32 v82, v114, s12, v148
	v_fma_f32 v83, v115, s12, v148
	v_fma_f32 v80, v112, s12, v148
	v_fma_f32 v81, v113, s12, v148
	v_fma_f32 v78, v110, s12, v148
	v_fma_f32 v79, v111, s12, v148
	v_fma_f32 v76, v108, s12, v148
	v_fma_f32 v77, v109, s12, v148
	v_fma_f32 v74, v106, s12, v148
	v_fma_f32 v75, v107, s12, v148
	v_fma_f32 v72, v104, s12, v148
	v_fma_f32 v73, v105, s12, v148
	v_mfma_f32_32x32x16_bf16 v[18:33], v[142:145], v[152:155], v[18:33]
	v_fma_f32 v70, v102, s12, v148
	v_fma_f32 v71, v103, s12, v148
	v_fma_f32 v68, v100, s12, v148
	v_fma_f32 v69, v101, s12, v148
	v_fma_f32 v66, v98, s12, v148
	v_fma_f32 v67, v99, s12, v148
	ds_read_b64_tr_b16 v[98:99], v217 offset:0x600
	ds_read_b64_tr_b16 v[100:101], v217 offset:0xe00
	ds_read_b64_tr_b16 v[102:103], v217 offset:0x1600
	ds_read_b64_tr_b16 v[104:105], v217 offset:0x1e00
	v_mfma_f32_32x32x16_bf16 v[18:33], v[138:141], v[156:159], v[18:33]
	ds_read_b64_tr_b16 v[106:107], v217 offset:0x2600
	ds_read_b64_tr_b16 v[108:109], v217 offset:0x2e00
	ds_read_b64_tr_b16 v[110:111], v217 offset:0x3600
	ds_read_b64_tr_b16 v[112:113], v217 offset:0x3e00
	s_waitcnt lgkmcnt(0)
	v_mfma_f32_32x32x16_bf16 v[2:17], v[130:133], v[98:101], v[2:17]
	v_exp_f32_e32 v82, v82
	v_exp_f32_e32 v83, v83
	v_exp_f32_e32 v84, v84
	v_exp_f32_e32 v85, v85
	v_exp_f32_e32 v86, v86
	v_exp_f32_e32 v87, v87
	v_exp_f32_e32 v88, v88
	v_mfma_f32_32x32x16_bf16 v[2:17], v[134:137], v[102:105], v[2:17]
	v_exp_f32_e32 v89, v89
	v_exp_f32_e32 v90, v90
	v_exp_f32_e32 v91, v91
	v_exp_f32_e32 v92, v92
	v_exp_f32_e32 v93, v93
	v_exp_f32_e32 v94, v94
	v_exp_f32_e32 v95, v95
	v_mfma_f32_32x32x16_bf16 v[2:17], v[142:145], v[106:109], v[2:17]
	v_exp_f32_e32 v96, v96
	v_exp_f32_e32 v97, v97
	v_mfma_f32_32x32x16_bf16 v[2:17], v[138:141], v[110:113], v[2:17]
	v_cmp_gt_f32_e32 vcc, 1.0, v146
	s_barrier
	s_cbranch_vccz .LBB0_187
	s_and_saveexec_b64 s[16:17], s[2:3]
	ds_write_b32 v214, v146 offset:128
	s_or_b64 exec, exec, s[16:17]
	s_waitcnt lgkmcnt(0)
	v_add_u32_e32 v110, s95, v210
	ds_read_b128 v[98:101], v110 offset:224
	ds_read_b128 v[102:105], v110 offset:192
	ds_read_b128 v[106:109], v110 offset:160
	ds_read_b128 v[110:113], v110 offset:128
	s_waitcnt lgkmcnt(3)
	v_pk_mul_f32 v[62:63], v[62:63], v[98:99]
	s_waitcnt lgkmcnt(2)
	v_pk_mul_f32 v[58:59], v[58:59], v[102:103]
	s_waitcnt lgkmcnt(1)
	v_pk_mul_f32 v[54:55], v[54:55], v[106:107]
	v_pk_mul_f32 v[64:65], v[64:65], v[100:101]
	v_pk_mul_f32 v[60:61], v[60:61], v[104:105]
	v_pk_mul_f32 v[56:57], v[56:57], v[108:109]
	s_waitcnt lgkmcnt(0)
	v_pk_mul_f32 v[52:53], v[52:53], v[112:113]
	v_pk_mul_f32 v[50:51], v[50:51], v[110:111]
	v_pk_mul_f32 v[46:47], v[46:47], v[98:99]
	v_pk_mul_f32 v[42:43], v[42:43], v[102:103]
	v_pk_mul_f32 v[38:39], v[38:39], v[106:107]
	v_pk_mul_f32 v[48:49], v[48:49], v[100:101]
	v_pk_mul_f32 v[44:45], v[44:45], v[104:105]
	v_pk_mul_f32 v[40:41], v[40:41], v[108:109]
	v_pk_mul_f32 v[36:37], v[36:37], v[112:113]
	v_pk_mul_f32 v[34:35], v[34:35], v[110:111]
	v_pk_mul_f32 v[30:31], v[30:31], v[98:99]
	v_pk_mul_f32 v[26:27], v[26:27], v[102:103]
	v_pk_mul_f32 v[22:23], v[22:23], v[106:107]
	v_pk_mul_f32 v[32:33], v[32:33], v[100:101]
	v_pk_mul_f32 v[28:29], v[28:29], v[104:105]
	v_pk_mul_f32 v[24:25], v[24:25], v[108:109]
	v_pk_mul_f32 v[20:21], v[20:21], v[112:113]
	v_pk_mul_f32 v[18:19], v[18:19], v[110:111]
	v_pk_mul_f32 v[14:15], v[14:15], v[98:99]
	v_pk_mul_f32 v[10:11], v[10:11], v[102:103]
	v_pk_mul_f32 v[6:7], v[6:7], v[106:107]
	v_pk_mul_f32 v[16:17], v[16:17], v[100:101]
	v_pk_mul_f32 v[12:13], v[12:13], v[104:105]
	v_pk_mul_f32 v[8:9], v[8:9], v[108:109]
	v_pk_mul_f32 v[4:5], v[4:5], v[112:113]
	v_pk_mul_f32 v[2:3], v[2:3], v[110:111]

; #define SLOAD(i, k0) do { const long to_ = (long)(k0) * ldk * 2; const char* vt_ = (const char*)Vh + to_; const char* kt_ = (const char*)Kh + to_; \
;     sr_[i].vs0 = *(const bf16x8*)(vt_ + toff); sr_[i].vs1 = *(const bf16x8*)(vt_ + h32 + toff); \
;     sr_[i].ks0 = *(const bf16x8*)(kt_ + toff); sr_[i].ks1 = *(const bf16x8*)(kt_ + h32 + toff); } while (0)
; #define SWAIT() do { if constexpr (SDEPTH == 2) asm volatile("s_waitcnt vmcnt(4)" ::: "memory"); else asm volatile("s_waitcnt vmcnt(0)" ::: "memory"); } while (0)
; #define MASK(P0, P1, k0) do { if constexpr (MODE == 1) { const int k0_ = (k0); \
;     if ((k0_ + 63 - qw0 > 128) || (k0_ - (qw0 + 31) < -128)) maskwin(P0, P1, k0_ - (qw0 + r32) + 128 + 4 * hi); } } while (0)
; __device__ __forceinline__ void partialSM(f32x16& p0, f32x16& p1, float& m_reg, float& mn, float& alpha) {
;   constexpr float C = SCALE * 1.4426950408889634f;
;   float pmax = p0[0]; for (int r = 1; r < 16; ++r) pmax = fmaxf(pmax, p0[r]); for (int r = 0; r < 16; ++r) pmax = fmaxf(pmax, p1[r]);
;   { auto rr = __builtin_amdgcn_permlane32_swap(__float_as_uint(pmax), __float_as_uint(pmax), false, false);
;     pmax = fmaxf(__uint_as_float(rr[0]), __uint_as_float(rr[1])); }
;   if (__builtin_expect(__all(pmax - m_reg <= THR / SCALE), 1)) { mn = m_reg; alpha = 1.f; }
;   else { mn = fmaxf(m_reg, pmax); alpha = __builtin_amdgcn_exp2f((m_reg - mn) * C); m_reg = mn; }
;   float mnC = -mn * C;
;   for (int r = 0; r < 16; ++r) p0[r] = fmaf(p0[r], C, mnC); for (int r = 0; r < 16; ++r) p1[r] = fmaf(p1[r], C, mnC);
;   for (int r = 0; r < 16; ++r) p0[r] = __builtin_amdgcn_exp2f(p0[r]);
; }
; template <int MODE, int QMODE> ...
;     ...
;   qkt(pA0, pA1, K_lds, qr, r32, hi); MASK(pA0, pA1, 0); partialSM(pA0, pA1, m_reg, mnA, alA);
;   SLOAD(SO, KVBLK); if constexpr (SDEPTH == 2) { if (2 < NT) SLOAD(SE, 2 * KVBLK); }
;   SWAIT(); SWRITE(1, SO); __syncthreads();
;   for (int j = 1; j + 1 < NT; j += 2) {
.LBB0_228:
	v_and_b32_e32 v181, 63, v40
	v_lshlrev_b32_e32 v41, 4, v181
	v_lshlrev_b32_e32 v40, 3, v181
	v_and_b32_e32 v41, 0xc0, v41
	v_lshlrev_b32_e32 v42, 1, v181
	v_and_or_b32 v41, v40, 24, v41
	v_and_b32_e32 v42, 32, v42
	v_and_b32_e32 v40, 0x100, v40
	v_or3_b32 v185, v41, v42, v40
	v_add_co_u32_e32 v40, vcc, s46, v36
	v_max_f32_e32 v53, v19, v19
	s_nop 0
	v_addc_co_u32_e32 v41, vcc, 0, v37, vcc
	v_add_co_u32_e32 v36, vcc, s47, v36
	v_max_f32_e32 v54, v18, v18
	s_nop 0
	v_addc_co_u32_e32 v37, vcc, 0, v37, vcc
	global_load_dwordx4 v[40:43], v[40:41], off
	s_nop 0
	global_load_dwordx4 v[44:47], v[36:37], off
	v_add_co_u32_e32 v36, vcc, s46, v34
	v_max_f32_e32 v53, v54, v53
	s_nop 0
	v_addc_co_u32_e32 v37, vcc, 0, v35, vcc
	v_add_co_u32_e32 v48, vcc, s47, v34
	v_max3_f32 v53, v53, v20, v21
	s_nop 0
	v_addc_co_u32_e32 v49, vcc, 0, v35, vcc
	global_load_dwordx4 v[34:37], v[36:37], off
	s_nop 0
	global_load_dwordx4 v[48:51], v[48:49], off
	v_max3_f32 v53, v53, v22, v23
	v_max3_f32 v53, v53, v24, v25
	v_max3_f32 v53, v53, v26, v27
	v_max3_f32 v53, v53, v28, v29
	v_max3_f32 v53, v53, v30, v31
	v_max3_f32 v53, v53, v32, v33
	v_max3_f32 v53, v53, v2, v3
	v_max3_f32 v53, v53, v4, v5
	v_max3_f32 v53, v53, v6, v7
	v_max3_f32 v53, v53, v8, v9
	v_max3_f32 v53, v53, v10, v11
	v_max3_f32 v53, v53, v12, v13
	v_max3_f32 v53, v53, v14, v15
	v_max3_f32 v53, v53, v16, v17
	s_add_i32 s4, s20, 0x100
	v_mov_b32_e32 v54, v53
	s_min_i32 s2, s4, s2
	s_nop 0
	v_permlane32_swap_b32_e32 v53, v54
	s_sub_i32 s82, s2, s3
	s_and_b32 s2, s21, 0x3fffffc0
	v_max_f32_e32 v54, v54, v54
	v_max_f32_e32 v53, v53, v53
	s_lshl_b32 s2, s2, 2
	v_mul_f32_e32 v52, 0x413504f3, v39
	v_max_f32_e32 v53, v53, v54
	s_add_i32 s80, s2, 0
	v_fmamk_f32 v54, v39, 0xc13504f3, v53
	v_max_f32_e32 v53, v52, v53
	s_add_i32 s80, s80, 0x10000
	v_fma_f32 v39, v39, s44, -v53
	s_cmp_lg_u32 0, -1
	v_cmp_ge_f32_e32 vcc, s45, v54
	v_mul_f32_e32 v39, 0x3e0293ee, v39
	s_cselect_b32 s2, 0, 0
	s_cmp_eq_u64 vcc, exec
	v_exp_f32_e32 v39, v39
	s_cselect_b64 vcc, -1, 0
	v_cndmask_b32_e32 v206, v53, v52, vcc
	v_mul_f32_e32 v52, 0xbe0293ee, v206
	v_cndmask_b32_e64 v203, v39, 1.0, vcc
	v_mov_b32_e32 v39, v52
	v_fmamk_f32 v18, v18, 0x3e0293ee, v52
	v_fmamk_f32 v19, v19, 0x3e0293ee, v52
	v_fmamk_f32 v20, v20, 0x3e0293ee, v52
	v_fmamk_f32 v21, v21, 0x3e0293ee, v52
	v_fmamk_f32 v22, v22, 0x3e0293ee, v52
	v_fmamk_f32 v23, v23, 0x3e0293ee, v52
	v_fmamk_f32 v24, v24, 0x3e0293ee, v52
	v_fmamk_f32 v25, v25, 0x3e0293ee, v52
	v_fmamk_f32 v26, v26, 0x3e0293ee, v52
	v_fmamk_f32 v27, v27, 0x3e0293ee, v52
	v_fmamk_f32 v28, v28, 0x3e0293ee, v52
	v_fmamk_f32 v29, v29, 0x3e0293ee, v52
	v_fmamk_f32 v30, v30, 0x3e0293ee, v52
	v_fmamk_f32 v31, v31, 0x3e0293ee, v52
	v_fmamk_f32 v32, v32, 0x3e0293ee, v52
	v_fmac_f32_e32 v39, 0x3e0293ee, v33
	v_exp_f32_e32 v66, v18
	v_exp_f32_e32 v67, v19
	v_exp_f32_e32 v68, v20
	v_exp_f32_e32 v69, v21
	v_exp_f32_e32 v70, v22
	v_exp_f32_e32 v71, v23
	v_exp_f32_e32 v72, v24
	v_exp_f32_e32 v73, v25
	v_exp_f32_e32 v74, v26
	v_exp_f32_e32 v75, v27
	v_exp_f32_e32 v76, v28
	v_exp_f32_e32 v77, v29
	v_exp_f32_e32 v78, v30
	v_exp_f32_e32 v79, v31
	v_exp_f32_e32 v80, v32
	v_exp_f32_e32 v81, v39
	s_waitcnt vmcnt(0)
	v_add_u32_e32 v188, s2, v185
	v_mov_b32_e32 v186, 1.0
	v_fma_f32 v96, v16, s8, v52
	v_fma_f32 v97, v17, s8, v52
	v_fma_f32 v94, v14, s8, v52
	v_fma_f32 v95, v15, s8, v52
	v_fma_f32 v92, v12, s8, v52
	v_fma_f32 v93, v13, s8, v52
	v_fma_f32 v90, v10, s8, v52
	v_fma_f32 v91, v11, s8, v52
	v_fma_f32 v88, v8, s8, v52
	v_fma_f32 v89, v9, s8, v52
	v_fma_f32 v86, v6, s8, v52
	v_fma_f32 v87, v7, s8, v52
	v_fma_f32 v84, v4, s8, v52
	v_fma_f32 v85, v5, s8, v52
	v_fma_f32 v82, v2, s8, v52
	v_fma_f32 v83, v3, s8, v52
	v_mov_b32_e32 v33, 0
	s_cmpk_lt_i32 s82, 0xc0
	v_cmp_gt_u32_e64 s[2:3], 32, v181
	v_lshl_add_u32 v187, v38, 2, s80
	s_waitcnt vmcnt(3)
	ds_write_b128 v201, v[40:43] offset:16384
	s_waitcnt vmcnt(2)
	ds_write_b128 v202, v[44:47] offset:16384
	s_waitcnt vmcnt(1)
	ds_write_b128 v199, v[34:37] offset:49152
	s_waitcnt vmcnt(0)
	ds_write_b128 v200, v[48:51] offset:49152
	s_waitcnt lgkmcnt(0)
	s_barrier
	s_cbranch_scc1 .LBB0_244
	s_and_b32 s4, s9, 0xffffff80
	s_and_b32 s22, s64, 2
	s_ashr_i32 s21, s82, 6
	s_add_i32 s5, s4, 0xffffff80
	s_lshl_b32 s22, s22, 7
	s_cmp_lg_u32 0, -1
	s_cselect_b32 s23, 0, 0
	s_addk_i32 s23, 0x4000
	s_max_i32 s5, s84, s5
	v_add_u32_e32 v204, s23, v185
	s_sub_i32 s23, s5, s66
	s_sub_i32 s4, s23, s4
	s_add_i32 s84, s4, 0x61
	s_mul_hi_u32 s4, s5, 0x1800
	s_mulk_i32 s5, 0x1800
	s_or_b32 s5, s5, s22
	s_add_u32 s22, s25, s5
	s_addc_u32 s23, s26, s4
	v_mov_b32_e32 v2, 0
	s_mov_b32 s83, 2
	v_sub_u32_e32 v205, v189, v38
	v_lshl_add_u64 v[182:183], s[22:23], 0, v[178:179]
	v_mov_b32_e32 v186, 1.0
	v_mov_b32_e32 v3, v2
	v_mov_b32_e32 v4, v2
	v_mov_b32_e32 v5, v2
	v_mov_b32_e32 v6, v2
	v_mov_b32_e32 v7, v2
	v_mov_b32_e32 v8, v2
	v_mov_b32_e32 v9, v2
	v_mov_b32_e32 v10, v2
	v_mov_b32_e32 v11, v2
	v_mov_b32_e32 v12, v2
	v_mov_b32_e32 v13, v2
	v_mov_b32_e32 v14, v2
	v_mov_b32_e32 v15, v2
	v_mov_b32_e32 v16, v2
	v_mov_b32_e32 v17, v2
	v_mov_b32_e32 v34, v2
	v_mov_b32_e32 v35, v2
	v_mov_b32_e32 v36, v2
	v_mov_b32_e32 v37, v2
	v_mov_b32_e32 v38, v2
	v_mov_b32_e32 v39, v2
	v_mov_b32_e32 v40, v2
	v_mov_b32_e32 v41, v2
	v_mov_b32_e32 v42, v2
	v_mov_b32_e32 v43, v2
	v_mov_b32_e32 v44, v2
	v_mov_b32_e32 v45, v2
	v_mov_b32_e32 v46, v2
	v_mov_b32_e32 v47, v2
	v_mov_b32_e32 v48, v2
	v_mov_b32_e32 v49, v2
	v_mov_b32_e32 v50, v2
	v_mov_b32_e32 v51, v2
	v_mov_b32_e32 v52, v2
	v_mov_b32_e32 v53, v2
	v_mov_b32_e32 v54, v2
	v_mov_b32_e32 v55, v2
	v_mov_b32_e32 v56, v2
	v_mov_b32_e32 v57, v2
	v_mov_b32_e32 v58, v2
	v_mov_b32_e32 v59, v2
	v_mov_b32_e32 v60, v2
	v_mov_b32_e32 v61, v2
	v_mov_b32_e32 v62, v2
	v_mov_b32_e32 v63, v2
	v_mov_b32_e32 v64, v2
	v_mov_b32_e32 v65, v2
	v_mov_b32_e32 v18, v2
	v_mov_b32_e32 v19, v2
	v_mov_b32_e32 v20, v2
	v_mov_b32_e32 v21, v2
	v_mov_b32_e32 v22, v2
	v_mov_b32_e32 v23, v2
	v_mov_b32_e32 v24, v2
	v_mov_b32_e32 v25, v2
	v_mov_b32_e32 v26, v2
	v_mov_b32_e32 v27, v2
	v_mov_b32_e32 v28, v2
	v_mov_b32_e32 v29, v2
	v_mov_b32_e32 v30, v2
	v_mov_b32_e32 v31, v2
	v_mov_b32_e32 v32, v2
	v_mov_b32_e32 v33, v2

; __device__ __forceinline__ void psm_decide(float pmax, const f32x16& p1, float& m_reg, float& mn, float& alpha) {
;   constexpr float C = SCALE * 1.4426950408889634f;
;   for (int r = 0; r < 16; ++r) pmax = fmaxf(pmax, p1[r]);
;   { auto rr = __builtin_amdgcn_permlane32_swap(__float_as_uint(pmax), __float_as_uint(pmax), false, false);
;     pmax = fmaxf(__uint_as_float(rr[0]), __uint_as_float(rr[1])); }
;   if (__builtin_expect(__all(pmax - m_reg <= THR / SCALE), 1)) { mn = m_reg; alpha = 1.f; }
;   else { mn = fmaxf(m_reg, pmax); alpha = __builtin_amdgcn_exp2f((m_reg - mn) * C); m_reg = mn; }
; }
; __device__ __forceinline__ void psm_scale(f32x16& p0, f32x16& p1, float mn) {
;   constexpr float C = SCALE * 1.4426950408889634f; const float mnC = -mn * C;
;   for (int r = 0; r < 16; ++r) p0[r] = fmaf(p0[r], C, mnC); for (int r = 0; r < 16; ++r) p1[r] = fmaf(p1[r], C, mnC);
; }
.LBB0_232:
	ds_read_b64_tr_b16 v[66:67], v188 offset:0
	ds_read_b64_tr_b16 v[68:69], v188 offset:0x800
	ds_read_b64_tr_b16 v[70:71], v188 offset:0x1000
	ds_read_b64_tr_b16 v[72:73], v188 offset:0x1800
	ds_read_b64_tr_b16 v[74:75], v188 offset:0x2000
	ds_read_b64_tr_b16 v[76:77], v188 offset:0x2800
	ds_read_b64_tr_b16 v[78:79], v188 offset:0x3000
	ds_read_b64_tr_b16 v[80:81], v188 offset:0x3800
	s_waitcnt lgkmcnt(0)
	s_nop 0
	v_mfma_f32_32x32x16_bf16 v[18:33], v[90:93], v[66:69], v[18:33]
	v_max_f32_e32 v66, v115, v115
	v_max_f32_e32 v67, v114, v114
	v_max_f32_e32 v66, v67, v66
	v_max3_f32 v66, v66, v116, v117
	v_max3_f32 v66, v66, v118, v119
	v_max3_f32 v66, v66, v120, v121
	v_max3_f32 v66, v66, v122, v123
	v_mfma_f32_32x32x16_bf16 v[18:33], v[86:89], v[70:73], v[18:33]
	v_max3_f32 v66, v66, v124, v125
	v_max3_f32 v68, v66, v126, v127
	ds_read_b64_tr_b16 v[66:67], v188 offset:0x200
	v_max3_f32 v209, v68, v128, v129
	ds_read_b64_tr_b16 v[68:69], v188 offset:0xa00
	ds_read_b64_tr_b16 v[70:71], v188 offset:0x1200
	ds_read_b64_tr_b16 v[72:73], v188 offset:0x1a00
	v_mfma_f32_32x32x16_bf16 v[18:33], v[170:173], v[74:77], v[18:33]
	ds_read_b64_tr_b16 v[74:75], v188 offset:0x2200
	ds_read_b64_tr_b16 v[76:77], v188 offset:0x2a00
	ds_read_b64_tr_b16 v[210:211], v188 offset:0x3200
	ds_read_b64_tr_b16 v[212:213], v188 offset:0x3a00
	s_waitcnt lgkmcnt(0)
	v_mfma_f32_32x32x16_bf16 v[18:33], v[82:85], v[78:81], v[18:33]
	v_mfma_f32_32x32x16_bf16 v[50:65], v[90:93], v[66:69], v[50:65]
	v_max3_f32 v78, v209, v98, v99
	v_max3_f32 v78, v78, v100, v101
	v_max3_f32 v78, v78, v102, v103
	v_max3_f32 v78, v78, v104, v105
	v_max3_f32 v78, v78, v106, v107
	v_max3_f32 v78, v78, v108, v109
	v_max3_f32 v66, v78, v110, v111
	v_max3_f32 v66, v66, v112, v113
	v_mfma_f32_32x32x16_bf16 v[50:65], v[86:89], v[70:73], v[50:65]
	v_mov_b32_e32 v67, v66
	s_nop 1
	v_permlane32_swap_b32_e32 v66, v67
	v_max_f32_e32 v67, v67, v67
	v_max_f32_e32 v66, v66, v66
	v_max_f32_e32 v66, v66, v67
	v_sub_f32_e32 v67, v66, v206
	v_cmp_ge_f32_e32 vcc, s45, v67
	v_max_f32_e32 v67, v206, v206
	v_max_f32_e32 v66, v67, v66
	v_sub_f32_e32 v67, v206, v66
	v_mfma_f32_32x32x16_bf16 v[50:65], v[170:173], v[74:77], v[50:65]
	v_mul_f32_e32 v67, 0x3e0293ee, v67
	v_exp_f32_e32 v67, v67
	s_cmp_eq_u64 vcc, exec
	s_cselect_b64 vcc, -1, 0
	v_cndmask_b32_e32 v206, v66, v206, vcc
	v_cndmask_b32_e64 v209, v67, 1.0, vcc
	ds_read_b64_tr_b16 v[66:67], v188 offset:0x400
	ds_read_b64_tr_b16 v[68:69], v188 offset:0xc00
	v_mfma_f32_32x32x16_bf16 v[50:65], v[82:85], v[210:213], v[50:65]
	ds_read_b64_tr_b16 v[210:211], v188 offset:0x1400
	ds_read_b64_tr_b16 v[212:213], v188 offset:0x1c00
	ds_read_b64_tr_b16 v[214:215], v188 offset:0x2400
	ds_read_b64_tr_b16 v[216:217], v188 offset:0x2c00
	ds_read_b64_tr_b16 v[218:219], v188 offset:0x3400
	ds_read_b64_tr_b16 v[220:221], v188 offset:0x3c00
	s_waitcnt lgkmcnt(0)
	v_mfma_f32_32x32x16_bf16 v[34:49], v[90:93], v[66:69], v[34:49]
	v_mul_f32_e32 v222, 0xbe0293ee, v206
	v_fma_f32 v80, v128, s8, v222
	v_fma_f32 v81, v129, s8, v222
	v_fma_f32 v78, v126, s8, v222
	v_fma_f32 v79, v127, s8, v222
	v_fma_f32 v76, v124, s8, v222
	v_fma_f32 v77, v125, s8, v222
	v_fma_f32 v74, v122, s8, v222
	v_fma_f32 v75, v123, s8, v222
	v_fma_f32 v72, v120, s8, v222
	v_fma_f32 v73, v121, s8, v222
	v_fma_f32 v70, v118, s8, v222
	v_fma_f32 v71, v119, s8, v222
	v_mfma_f32_32x32x16_bf16 v[34:49], v[86:89], v[210:213], v[34:49]
	v_fma_f32 v68, v116, s8, v222
	v_fma_f32 v69, v117, s8, v222
	v_fma_f32 v66, v114, s8, v222
	v_fma_f32 v67, v115, s8, v222
	v_fma_f32 v112, v112, s8, v222
	v_fma_f32 v113, v113, s8, v222
	v_fma_f32 v110, v110, s8, v222
	v_fma_f32 v111, v111, s8, v222
	v_fma_f32 v108, v108, s8, v222
	v_fma_f32 v109, v109, s8, v222
	v_fma_f32 v106, v106, s8, v222
	v_fma_f32 v107, v107, s8, v222
	v_fma_f32 v104, v104, s8, v222
	v_fma_f32 v105, v105, s8, v222
	v_mfma_f32_32x32x16_bf16 v[34:49], v[170:173], v[214:217], v[34:49]
	v_fma_f32 v102, v102, s8, v222
	v_fma_f32 v103, v103, s8, v222
	v_fma_f32 v100, v100, s8, v222
	v_fma_f32 v101, v101, s8, v222
	v_fma_f32 v98, v98, s8, v222
	v_fma_f32 v99, v99, s8, v222
	ds_read_b64_tr_b16 v[114:115], v188 offset:0x600
	ds_read_b64_tr_b16 v[116:117], v188 offset:0xe00
	ds_read_b64_tr_b16 v[118:119], v188 offset:0x1600
	ds_read_b64_tr_b16 v[120:121], v188 offset:0x1e00
	v_mfma_f32_32x32x16_bf16 v[34:49], v[82:85], v[218:221], v[34:49]
	ds_read_b64_tr_b16 v[124:125], v188 offset:0x2600
	ds_read_b64_tr_b16 v[126:127], v188 offset:0x2e00
	ds_read_b64_tr_b16 v[210:211], v188 offset:0x3600
	ds_read_b64_tr_b16 v[212:213], v188 offset:0x3e00
	s_waitcnt lgkmcnt(0)
	v_mfma_f32_32x32x16_bf16 v[2:17], v[90:93], v[114:117], v[2:17]
	v_exp_f32_e32 v114, v66
	v_exp_f32_e32 v115, v67
	v_exp_f32_e32 v116, v68
	v_exp_f32_e32 v117, v69
	v_exp_f32_e32 v122, v74
	v_exp_f32_e32 v123, v75
	v_exp_f32_e32 v128, v80
	v_mfma_f32_32x32x16_bf16 v[2:17], v[86:89], v[118:121], v[2:17]
	v_exp_f32_e32 v118, v70
	v_exp_f32_e32 v119, v71
	v_exp_f32_e32 v120, v72
	v_exp_f32_e32 v121, v73
	v_exp_f32_e32 v129, v81
	v_mfma_f32_32x32x16_bf16 v[2:17], v[170:173], v[124:127], v[2:17]
	v_exp_f32_e32 v124, v76
	v_exp_f32_e32 v125, v77
	v_exp_f32_e32 v126, v78
	v_exp_f32_e32 v127, v79
	v_mfma_f32_32x32x16_bf16 v[2:17], v[82:85], v[210:213], v[2:17]
	s_barrier
; #define SWAIT() do { if constexpr (SDEPTH == 2) asm volatile("s_waitcnt vmcnt(4)" ::: "memory"); else asm volatile("s_waitcnt vmcnt(0)" ::: "memory"); } while (0)
; #define RESC(a) do { if (__any((a) < 1.f)) { if (hi == 0) al_l[r32] = (a); asm volatile("s_waitcnt lgkmcnt(0)" ::: "memory"); \
;     for (int d = 0; d < 4; ++d) for (int r = 0; r < 16; ++r) o[d][r] *= al_l[crow(r, hi)]; } } while (0)
; template <int MODE, int QMODE> ...
;     ...
;     __syncthreads(); SWAIT(); SWRITE(1, SO);
;     RESC(alA); __syncthreads();
	s_waitcnt vmcnt(0)
	v_cmp_gt_f32_e32 vcc, 1.0, v209
	s_waitcnt vmcnt(3)
	ds_write_b128 v201, v[94:97]
	s_waitcnt vmcnt(1)
	ds_write_b128 v202, v[174:177]
	ds_write_b128 v199, v[162:165] offset:32768
	s_waitcnt vmcnt(0)
	ds_write_b128 v200, v[166:169] offset:32768
	s_cbranch_vccz .LBB0_236
	s_and_saveexec_b64 s[22:23], s[2:3]
	ds_write_b32 v187, v209 offset:128
	s_or_b64 exec, exec, s[22:23]
	s_waitcnt lgkmcnt(0)
	v_add_u32_e32 v78, s80, v180
	ds_read_b128 v[66:69], v78 offset:224
	ds_read_b128 v[70:73], v78 offset:192
	ds_read_b128 v[74:77], v78 offset:160
	ds_read_b128 v[78:81], v78 offset:128
	s_waitcnt lgkmcnt(3)
	v_pk_mul_f32 v[30:31], v[30:31], v[66:67]
	s_waitcnt lgkmcnt(2)
	v_pk_mul_f32 v[26:27], v[26:27], v[70:71]
	s_waitcnt lgkmcnt(1)
	v_pk_mul_f32 v[22:23], v[22:23], v[74:75]
	v_pk_mul_f32 v[32:33], v[32:33], v[68:69]
	v_pk_mul_f32 v[28:29], v[28:29], v[72:73]
	v_pk_mul_f32 v[24:25], v[24:25], v[76:77]
	s_waitcnt lgkmcnt(0)
	v_pk_mul_f32 v[20:21], v[20:21], v[80:81]
	v_pk_mul_f32 v[18:19], v[18:19], v[78:79]
	v_pk_mul_f32 v[62:63], v[62:63], v[66:67]
	v_pk_mul_f32 v[58:59], v[58:59], v[70:71]
	v_pk_mul_f32 v[54:55], v[54:55], v[74:75]
	v_pk_mul_f32 v[64:65], v[64:65], v[68:69]
	v_pk_mul_f32 v[60:61], v[60:61], v[72:73]
	v_pk_mul_f32 v[56:57], v[56:57], v[76:77]
	v_pk_mul_f32 v[52:53], v[52:53], v[80:81]
	v_pk_mul_f32 v[50:51], v[50:51], v[78:79]
	v_pk_mul_f32 v[46:47], v[46:47], v[66:67]
	v_pk_mul_f32 v[42:43], v[42:43], v[70:71]
	v_pk_mul_f32 v[38:39], v[38:39], v[74:75]
	v_pk_mul_f32 v[48:49], v[48:49], v[68:69]
	v_pk_mul_f32 v[44:45], v[44:45], v[72:73]
	v_pk_mul_f32 v[40:41], v[40:41], v[76:77]
	v_pk_mul_f32 v[36:37], v[36:37], v[80:81]
	v_pk_mul_f32 v[34:35], v[34:35], v[78:79]
	v_pk_mul_f32 v[14:15], v[14:15], v[66:67]
	v_pk_mul_f32 v[10:11], v[10:11], v[70:71]
	v_pk_mul_f32 v[6:7], v[6:7], v[74:75]
	v_pk_mul_f32 v[16:17], v[16:17], v[68:69]
	v_pk_mul_f32 v[12:13], v[12:13], v[72:73]
	v_pk_mul_f32 v[8:9], v[8:9], v[76:77]
	v_pk_mul_f32 v[4:5], v[4:5], v[80:81]
	v_pk_mul_f32 v[2:3], v[2:3], v[78:79]

; __device__ __forceinline__ void psm_decide(float pmax, const f32x16& p1, float& m_reg, float& mn, float& alpha) {
;   constexpr float C = SCALE * 1.4426950408889634f;
;   for (int r = 0; r < 16; ++r) pmax = fmaxf(pmax, p1[r]);
;   { auto rr = __builtin_amdgcn_permlane32_swap(__float_as_uint(pmax), __float_as_uint(pmax), false, false);
;     pmax = fmaxf(__uint_as_float(rr[0]), __uint_as_float(rr[1])); }
;   if (__builtin_expect(__all(pmax - m_reg <= THR / SCALE), 1)) { mn = m_reg; alpha = 1.f; }
;   else { mn = fmaxf(m_reg, pmax); alpha = __builtin_amdgcn_exp2f((m_reg - mn) * C); m_reg = mn; }
; }
; __device__ __forceinline__ void psm_scale(f32x16& p0, f32x16& p1, float mn) {
;   constexpr float C = SCALE * 1.4426950408889634f; const float mnC = -mn * C;
;   for (int r = 0; r < 16; ++r) p0[r] = fmaf(p0[r], C, mnC); for (int r = 0; r < 16; ++r) p1[r] = fmaf(p1[r], C, mnC);
; }
; __device__ __forceinline__ void finishSM(f32x16& p0, f32x16& p1, float alpha, float& l_reg, bf16x8& pa0, bf16x8& pa1, bf16x8& pa2, bf16x8& pa3) {
;   for (int r = 0; r < 16; ++r) p1[r] = __builtin_amdgcn_exp2f(p1[r]);
;   float ps = 0; for (int r = 0; r < 16; ++r) ps += p0[r]; for (int r = 0; r < 16; ++r) ps += p1[r];
;   { auto rr = __builtin_amdgcn_permlane32_swap(__float_as_uint(ps), __float_as_uint(ps), false, false);
;     ps = __uint_as_float(rr[0]) + __uint_as_float(rr[1]); }
;   l_reg = l_reg * alpha + ps;
;     ...
;   PK4(p0, 0, pa0); PK4(p0, 8, pa1); PK4(p1, 0, pa2); PK4(p1, 8, pa3);
;     ...
; }
; __device__ __forceinline__ void qkt(f32x16& p0, f32x16& p1, const bf16* Ks, const bf16x8* qr, int r32, int hi) {
;   p0 = f32x16{}; p1 = f32x16{};
;   for (int d0 = 0; d0 < 8; ++d0) { int cb = (d0 * 16 + hi * 8) * 2;
;     bf16x8 b0 = *reinterpret_cast<const bf16x8*>((const char*)Ks + KSWZ(r32, cb));
;     bf16x8 b1 = *reinterpret_cast<const bf16x8*>((const char*)Ks + KSWZ(32 + r32, cb));
;     p0 = __builtin_amdgcn_mfma_f32_32x32x16_bf16(b0, qr[d0], p0, 0, 0, 0);
;     p1 = __builtin_amdgcn_mfma_f32_32x32x16_bf16(b1, qr[d0], p1, 0, 0, 0); }
; }
; __device__ __forceinline__ int v_st(int k, int c) { const int kk = (k & ~0xC) | ((k & 4) << 1) | ((k & 8) >> 1); return ((kk >> 3) * 4 + (c >> 5)) * 512 + ((kk & 7) * 32 + (c & 31)) * 2; }
; __device__ __forceinline__ int v_rd_base(int lane) { return ((lane & 3) << 3) | (((lane >> 2) & 3) << 6) | (((lane >> 4) & 1) << 5) | (((lane >> 5) & 1) << 8); }
.LBB0_238:
	ds_read_b64_tr_b16 v[98:99], v204 offset:0
	ds_read_b64_tr_b16 v[100:101], v204 offset:0x800
	ds_read_b64_tr_b16 v[102:103], v204 offset:0x1000
	ds_read_b64_tr_b16 v[104:105], v204 offset:0x1800
	ds_read_b64_tr_b16 v[106:107], v204 offset:0x2000
	ds_read_b64_tr_b16 v[108:109], v204 offset:0x2800
	ds_read_b64_tr_b16 v[110:111], v204 offset:0x3000
	ds_read_b64_tr_b16 v[112:113], v204 offset:0x3800
	s_waitcnt lgkmcnt(0)
	s_nop 0
	v_mfma_f32_32x32x16_bf16 v[18:33], v[174:177], v[98:101], v[18:33]
	v_max_f32_e32 v98, v83, v83
	v_max_f32_e32 v99, v82, v82
	v_max_f32_e32 v98, v99, v98
	v_max3_f32 v98, v98, v84, v85
	v_max3_f32 v98, v98, v86, v87
	v_max3_f32 v98, v98, v88, v89
	v_max3_f32 v98, v98, v90, v91
	v_mfma_f32_32x32x16_bf16 v[18:33], v[118:121], v[102:105], v[18:33]
	v_max3_f32 v98, v98, v92, v93
	v_max3_f32 v100, v98, v94, v95
	ds_read_b64_tr_b16 v[98:99], v204 offset:0x200
	v_max3_f32 v178, v100, v96, v97
	ds_read_b64_tr_b16 v[100:101], v204 offset:0xa00
	ds_read_b64_tr_b16 v[102:103], v204 offset:0x1200
	ds_read_b64_tr_b16 v[104:105], v204 offset:0x1a00
	v_mfma_f32_32x32x16_bf16 v[18:33], v[122:125], v[106:109], v[18:33]
	ds_read_b64_tr_b16 v[106:107], v204 offset:0x2200
	ds_read_b64_tr_b16 v[108:109], v204 offset:0x2a00
	ds_read_b64_tr_b16 v[212:213], v204 offset:0x3200
	ds_read_b64_tr_b16 v[214:215], v204 offset:0x3a00
	s_waitcnt lgkmcnt(0)
	v_mfma_f32_32x32x16_bf16 v[18:33], v[114:117], v[110:113], v[18:33]
	v_mfma_f32_32x32x16_bf16 v[50:65], v[174:177], v[98:101], v[50:65]
	v_max3_f32 v110, v178, v66, v67
	v_max3_f32 v110, v110, v68, v69
	v_max3_f32 v110, v110, v70, v71
	v_max3_f32 v110, v110, v72, v73
	v_max3_f32 v110, v110, v74, v75
	v_max3_f32 v110, v110, v76, v77
	v_max3_f32 v98, v110, v78, v79
	v_max3_f32 v98, v98, v80, v81
	v_mfma_f32_32x32x16_bf16 v[50:65], v[118:121], v[102:105], v[50:65]
	v_mov_b32_e32 v99, v98
	s_nop 1
	v_permlane32_swap_b32_e32 v98, v99
	v_max_f32_e32 v99, v99, v99
	v_max_f32_e32 v98, v98, v98
	v_max_f32_e32 v98, v98, v99
	v_sub_f32_e32 v99, v98, v206
	v_cmp_ge_f32_e32 vcc, s45, v99
	v_max_f32_e32 v99, v206, v206
	v_max_f32_e32 v98, v99, v98
	v_sub_f32_e32 v99, v206, v98
	v_mfma_f32_32x32x16_bf16 v[50:65], v[122:125], v[106:109], v[50:65]
	v_mul_f32_e32 v99, 0x3e0293ee, v99
	v_exp_f32_e32 v99, v99
	s_cmp_eq_u64 vcc, exec
	s_cselect_b64 vcc, -1, 0
	v_cndmask_b32_e32 v206, v98, v206, vcc
	v_cndmask_b32_e64 v178, v99, 1.0, vcc
	ds_read_b64_tr_b16 v[98:99], v204 offset:0x400
	ds_read_b64_tr_b16 v[100:101], v204 offset:0xc00
	v_mfma_f32_32x32x16_bf16 v[50:65], v[114:117], v[212:215], v[50:65]
	ds_read_b64_tr_b16 v[212:213], v204 offset:0x1400
	ds_read_b64_tr_b16 v[214:215], v204 offset:0x1c00
	ds_read_b64_tr_b16 v[216:217], v204 offset:0x2400
	ds_read_b64_tr_b16 v[218:219], v204 offset:0x2c00
	ds_read_b64_tr_b16 v[220:221], v204 offset:0x3400
	ds_read_b64_tr_b16 v[222:223], v204 offset:0x3c00
	s_waitcnt lgkmcnt(0)
	v_mfma_f32_32x32x16_bf16 v[34:49], v[174:177], v[98:101], v[34:49]
	v_mul_f32_e32 v224, 0xbe0293ee, v206
	v_fma_f32 v112, v96, s8, v224
	v_fma_f32 v113, v97, s8, v224
	v_fma_f32 v110, v94, s8, v224
	v_fma_f32 v111, v95, s8, v224
	v_fma_f32 v108, v92, s8, v224
	v_fma_f32 v109, v93, s8, v224
	v_fma_f32 v106, v90, s8, v224
	v_fma_f32 v107, v91, s8, v224
	v_fma_f32 v104, v88, s8, v224
	v_fma_f32 v105, v89, s8, v224
	v_fma_f32 v102, v86, s8, v224
	v_fma_f32 v103, v87, s8, v224
	v_mfma_f32_32x32x16_bf16 v[34:49], v[118:121], v[212:215], v[34:49]
	v_fma_f32 v100, v84, s8, v224
	v_fma_f32 v101, v85, s8, v224
	v_fma_f32 v98, v82, s8, v224
	v_fma_f32 v99, v83, s8, v224
	v_fma_f32 v96, v80, s8, v224
	v_fma_f32 v97, v81, s8, v224
	v_fma_f32 v94, v78, s8, v224
	v_fma_f32 v95, v79, s8, v224
	v_fma_f32 v92, v76, s8, v224
	v_fma_f32 v93, v77, s8, v224
	v_fma_f32 v90, v74, s8, v224
	v_fma_f32 v91, v75, s8, v224
	v_fma_f32 v88, v72, s8, v224
	v_fma_f32 v89, v73, s8, v224
	v_mfma_f32_32x32x16_bf16 v[34:49], v[122:125], v[216:219], v[34:49]
	v_fma_f32 v86, v70, s8, v224
	v_fma_f32 v87, v71, s8, v224
	v_fma_f32 v84, v68, s8, v224
	v_fma_f32 v85, v69, s8, v224
	v_fma_f32 v82, v66, s8, v224
	v_fma_f32 v83, v67, s8, v224
	ds_read_b64_tr_b16 v[66:67], v204 offset:0x600
	ds_read_b64_tr_b16 v[68:69], v204 offset:0xe00
	ds_read_b64_tr_b16 v[70:71], v204 offset:0x1600
	ds_read_b64_tr_b16 v[72:73], v204 offset:0x1e00
	v_mfma_f32_32x32x16_bf16 v[34:49], v[114:117], v[220:223], v[34:49]
	ds_read_b64_tr_b16 v[76:77], v204 offset:0x2600
	ds_read_b64_tr_b16 v[78:79], v204 offset:0x2e00
	ds_read_b64_tr_b16 v[212:213], v204 offset:0x3600
	ds_read_b64_tr_b16 v[214:215], v204 offset:0x3e00
	s_waitcnt lgkmcnt(0)
	v_mfma_f32_32x32x16_bf16 v[2:17], v[174:177], v[66:69], v[2:17]
	v_exp_f32_e32 v66, v98
	v_exp_f32_e32 v67, v99
	v_exp_f32_e32 v68, v100
	v_exp_f32_e32 v69, v101
	v_exp_f32_e32 v74, v106
	v_exp_f32_e32 v75, v107
	v_exp_f32_e32 v80, v112
	v_mfma_f32_32x32x16_bf16 v[2:17], v[118:121], v[70:73], v[2:17]
	v_exp_f32_e32 v70, v102
	v_exp_f32_e32 v71, v103
	v_exp_f32_e32 v72, v104
	v_exp_f32_e32 v73, v105
	v_exp_f32_e32 v81, v113
	v_mfma_f32_32x32x16_bf16 v[2:17], v[122:125], v[76:79], v[2:17]
	v_exp_f32_e32 v76, v108
	v_exp_f32_e32 v77, v109
	v_exp_f32_e32 v78, v110
	v_exp_f32_e32 v79, v111
	v_mfma_f32_32x32x16_bf16 v[2:17], v[114:117], v[212:215], v[2:17]
	s_barrier
; #define SWAIT() do { if constexpr (SDEPTH == 2) asm volatile("s_waitcnt vmcnt(4)" ::: "memory"); else asm volatile("s_waitcnt vmcnt(0)" ::: "memory"); } while (0)
; #define RESC(a) do { if (__any((a) < 1.f)) { if (hi == 0) al_l[r32] = (a); asm volatile("s_waitcnt lgkmcnt(0)" ::: "memory"); \
;     for (int d = 0; d < 4; ++d) for (int r = 0; r < 16; ++r) o[d][r] *= al_l[crow(r, hi)]; } } while (0)
; template <int MODE, int QMODE> ...
;     ...
;     __syncthreads(); SWAIT(); SWRITE(1, SO);
;     RESC(alA); __syncthreads();
	s_waitcnt vmcnt(0)
	v_cmp_gt_f32_e32 vcc, 1.0, v178
	s_waitcnt vmcnt(3)
	ds_write_b128 v201, v[126:129] offset:16384
	s_waitcnt vmcnt(1)
	ds_write_b128 v202, v[170:173] offset:16384
	ds_write_b128 v199, v[162:165] offset:49152
	s_waitcnt vmcnt(0)
	ds_write_b128 v200, v[166:169] offset:49152
	s_cbranch_vccz .LBB0_242
	s_and_saveexec_b64 s[22:23], s[2:3]
	ds_write_b32 v187, v178 offset:128
	s_or_b64 exec, exec, s[22:23]
	s_waitcnt lgkmcnt(0)
	v_add_u32_e32 v110, s80, v180
	ds_read_b128 v[98:101], v110 offset:224
	ds_read_b128 v[102:105], v110 offset:192
	ds_read_b128 v[106:109], v110 offset:128
	ds_read_b128 v[110:113], v110 offset:160
	s_waitcnt lgkmcnt(3)
	v_pk_mul_f32 v[32:33], v[32:33], v[100:101]
	v_pk_mul_f32 v[30:31], v[30:31], v[98:99]
	s_waitcnt lgkmcnt(2)
	v_pk_mul_f32 v[28:29], v[28:29], v[104:105]
	v_pk_mul_f32 v[26:27], v[26:27], v[102:103]
	s_waitcnt lgkmcnt(0)
	v_pk_mul_f32 v[24:25], v[24:25], v[112:113]
	v_pk_mul_f32 v[22:23], v[22:23], v[110:111]
	v_pk_mul_f32 v[20:21], v[20:21], v[108:109]
	v_pk_mul_f32 v[18:19], v[18:19], v[106:107]
	v_pk_mul_f32 v[64:65], v[64:65], v[100:101]
	v_pk_mul_f32 v[62:63], v[62:63], v[98:99]
	v_pk_mul_f32 v[60:61], v[60:61], v[104:105]
	v_pk_mul_f32 v[58:59], v[58:59], v[102:103]
	v_pk_mul_f32 v[56:57], v[56:57], v[112:113]
	v_pk_mul_f32 v[54:55], v[54:55], v[110:111]
	v_pk_mul_f32 v[52:53], v[52:53], v[108:109]
	v_pk_mul_f32 v[50:51], v[50:51], v[106:107]
	v_pk_mul_f32 v[48:49], v[48:49], v[100:101]
	v_pk_mul_f32 v[46:47], v[46:47], v[98:99]
	v_pk_mul_f32 v[44:45], v[44:45], v[104:105]
	v_pk_mul_f32 v[42:43], v[42:43], v[102:103]
	v_pk_mul_f32 v[40:41], v[40:41], v[112:113]
	v_pk_mul_f32 v[38:39], v[38:39], v[110:111]
	v_pk_mul_f32 v[36:37], v[36:37], v[108:109]
	v_pk_mul_f32 v[34:35], v[34:35], v[106:107]
	v_pk_mul_f32 v[16:17], v[16:17], v[100:101]
	v_pk_mul_f32 v[14:15], v[14:15], v[98:99]
	v_pk_mul_f32 v[12:13], v[12:13], v[104:105]
	v_pk_mul_f32 v[10:11], v[10:11], v[102:103]
	v_pk_mul_f32 v[8:9], v[8:9], v[112:113]
	v_pk_mul_f32 v[6:7], v[6:7], v[110:111]
	v_pk_mul_f32 v[4:5], v[4:5], v[108:109]
	v_pk_mul_f32 v[2:3], v[2:3], v[106:107]

; __device__ __forceinline__ void psm_decide(float pmax, const f32x16& p1, float& m_reg, float& mn, float& alpha) {
;   constexpr float C = SCALE * 1.4426950408889634f;
;   for (int r = 0; r < 16; ++r) pmax = fmaxf(pmax, p1[r]);
;   { auto rr = __builtin_amdgcn_permlane32_swap(__float_as_uint(pmax), __float_as_uint(pmax), false, false);
;     pmax = fmaxf(__uint_as_float(rr[0]), __uint_as_float(rr[1])); }
;   if (__builtin_expect(__all(pmax - m_reg <= THR / SCALE), 1)) { mn = m_reg; alpha = 1.f; }
;   else { mn = fmaxf(m_reg, pmax); alpha = __builtin_amdgcn_exp2f((m_reg - mn) * C); m_reg = mn; }
; }
; __device__ __forceinline__ void psm_scale(f32x16& p0, f32x16& p1, float mn) {
;   constexpr float C = SCALE * 1.4426950408889634f; const float mnC = -mn * C;
;   for (int r = 0; r < 16; ++r) p0[r] = fmaf(p0[r], C, mnC); for (int r = 0; r < 16; ++r) p1[r] = fmaf(p1[r], C, mnC);
; }
; __device__ __forceinline__ void finishSM(f32x16& p0, f32x16& p1, float alpha, float& l_reg, bf16x8& pa0, bf16x8& pa1, bf16x8& pa2, bf16x8& pa3) {
;   for (int r = 0; r < 16; ++r) p1[r] = __builtin_amdgcn_exp2f(p1[r]);
;   float ps = 0; for (int r = 0; r < 16; ++r) ps += p0[r]; for (int r = 0; r < 16; ++r) ps += p1[r];
;   { auto rr = __builtin_amdgcn_permlane32_swap(__float_as_uint(ps), __float_as_uint(ps), false, false);
;     ps = __uint_as_float(rr[0]) + __uint_as_float(rr[1]); }
;   l_reg = l_reg * alpha + ps;
;     ...
;   PK4(p0, 0, pa0); PK4(p0, 8, pa1); PK4(p1, 0, pa2); PK4(p1, 8, pa3);
;     ...
; }
; __device__ __forceinline__ void qkt(f32x16& p0, f32x16& p1, const bf16* Ks, const bf16x8* qr, int r32, int hi) {
;   p0 = f32x16{}; p1 = f32x16{};
;   for (int d0 = 0; d0 < 8; ++d0) { int cb = (d0 * 16 + hi * 8) * 2;
;     bf16x8 b0 = *reinterpret_cast<const bf16x8*>((const char*)Ks + KSWZ(r32, cb));
;     bf16x8 b1 = *reinterpret_cast<const bf16x8*>((const char*)Ks + KSWZ(32 + r32, cb));
;     p0 = __builtin_amdgcn_mfma_f32_32x32x16_bf16(b0, qr[d0], p0, 0, 0, 0);
;     p1 = __builtin_amdgcn_mfma_f32_32x32x16_bf16(b1, qr[d0], p1, 0, 0, 0); }
; }
; __device__ __forceinline__ int v_st(int k, int c) { const int kk = (k & ~0xC) | ((k & 4) << 1) | ((k & 8) >> 1); return ((kk >> 3) * 4 + (c >> 5)) * 512 + ((kk & 7) * 32 + (c & 31)) * 2; }
; __device__ __forceinline__ int v_rd_base(int lane) { return ((lane & 3) << 3) | (((lane >> 2) & 3) << 6) | (((lane >> 4) & 1) << 5) | (((lane >> 5) & 1) << 8); }
.LBB0_249:
	ds_read_b64_tr_b16 v[66:67], v188 offset:0
	ds_read_b64_tr_b16 v[68:69], v188 offset:0x800
	ds_read_b64_tr_b16 v[70:71], v188 offset:0x1000
	ds_read_b64_tr_b16 v[72:73], v188 offset:0x1800
	ds_read_b64_tr_b16 v[74:75], v188 offset:0x2000
	ds_read_b64_tr_b16 v[76:77], v188 offset:0x2800
	ds_read_b64_tr_b16 v[78:79], v188 offset:0x3000
	ds_read_b64_tr_b16 v[80:81], v188 offset:0x3800
	s_waitcnt lgkmcnt(0)
	s_nop 0
	v_mfma_f32_32x32x16_bf16 v[18:33], v[142:145], v[66:69], v[18:33]
	v_max_f32_e32 v66, v115, v115
	v_max_f32_e32 v67, v114, v114
	v_max_f32_e32 v66, v67, v66
	v_max3_f32 v66, v66, v116, v117
	v_max3_f32 v66, v66, v118, v119
	v_max3_f32 v66, v66, v120, v121
	v_max3_f32 v66, v66, v122, v123
	v_mfma_f32_32x32x16_bf16 v[18:33], v[134:137], v[70:73], v[18:33]
	v_max3_f32 v66, v66, v124, v125
	v_max3_f32 v68, v66, v126, v127
	ds_read_b64_tr_b16 v[66:67], v188 offset:0x200
	v_max3_f32 v86, v68, v128, v129
	ds_read_b64_tr_b16 v[68:69], v188 offset:0xa00
	ds_read_b64_tr_b16 v[70:71], v188 offset:0x1200
	ds_read_b64_tr_b16 v[72:73], v188 offset:0x1a00
	v_mfma_f32_32x32x16_bf16 v[18:33], v[138:141], v[74:77], v[18:33]
	ds_read_b64_tr_b16 v[74:75], v188 offset:0x2200
	ds_read_b64_tr_b16 v[76:77], v188 offset:0x2a00
	ds_read_b64_tr_b16 v[82:83], v188 offset:0x3200
	ds_read_b64_tr_b16 v[84:85], v188 offset:0x3a00
	s_waitcnt lgkmcnt(0)
	v_mfma_f32_32x32x16_bf16 v[18:33], v[130:133], v[78:81], v[18:33]
	v_max3_f32 v78, v86, v98, v99
	v_mfma_f32_32x32x16_bf16 v[50:65], v[142:145], v[66:69], v[50:65]
	v_max3_f32 v78, v78, v100, v101
	v_max3_f32 v78, v78, v102, v103
	v_max3_f32 v78, v78, v104, v105
	v_max3_f32 v78, v78, v106, v107
	v_max3_f32 v78, v78, v108, v109
	v_max3_f32 v66, v78, v110, v111
	v_max3_f32 v66, v66, v112, v113
	v_mov_b32_e32 v67, v66
	v_mfma_f32_32x32x16_bf16 v[50:65], v[134:137], v[70:73], v[50:65]
	s_nop 0
	v_permlane32_swap_b32_e32 v66, v67
	v_max_f32_e32 v67, v67, v67
	v_max_f32_e32 v66, v66, v66
	v_max_f32_e32 v66, v66, v67
	v_sub_f32_e32 v67, v66, v206
	v_cmp_ge_f32_e32 vcc, s45, v67
	v_max_f32_e32 v67, v206, v206
	v_max_f32_e32 v66, v67, v66
	v_sub_f32_e32 v67, v206, v66
	v_mul_f32_e32 v67, 0x3e0293ee, v67
	v_mfma_f32_32x32x16_bf16 v[50:65], v[138:141], v[74:77], v[50:65]
	v_exp_f32_e32 v67, v67
	s_cmp_eq_u64 vcc, exec
	s_cselect_b64 vcc, -1, 0
	v_cndmask_b32_e32 v74, v66, v206, vcc
	v_cndmask_b32_e64 v146, v67, 1.0, vcc
	ds_read_b64_tr_b16 v[66:67], v188 offset:0x400
	ds_read_b64_tr_b16 v[68:69], v188 offset:0xc00
	ds_read_b64_tr_b16 v[70:71], v188 offset:0x1400
	v_mfma_f32_32x32x16_bf16 v[50:65], v[130:133], v[82:85], v[50:65]
	ds_read_b64_tr_b16 v[72:73], v188 offset:0x1c00
	ds_read_b64_tr_b16 v[152:153], v188 offset:0x2400
	ds_read_b64_tr_b16 v[154:155], v188 offset:0x2c00
	ds_read_b64_tr_b16 v[156:157], v188 offset:0x3400
	ds_read_b64_tr_b16 v[158:159], v188 offset:0x3c00
	s_waitcnt lgkmcnt(0)
	v_mfma_f32_32x32x16_bf16 v[34:49], v[142:145], v[66:69], v[34:49]
	v_mul_f32_e32 v148, 0xbe0293ee, v74
	v_fma_f32 v96, v128, s8, v148
	v_fma_f32 v97, v129, s8, v148
	v_fma_f32 v94, v126, s8, v148
	v_fma_f32 v95, v127, s8, v148
	v_fma_f32 v92, v124, s8, v148
	v_fma_f32 v93, v125, s8, v148
	v_fma_f32 v90, v122, s8, v148
	v_fma_f32 v91, v123, s8, v148
	v_fma_f32 v88, v120, s8, v148
	v_fma_f32 v89, v121, s8, v148
	v_fma_f32 v86, v118, s8, v148
	v_fma_f32 v87, v119, s8, v148
	v_mfma_f32_32x32x16_bf16 v[34:49], v[134:137], v[70:73], v[34:49]
	v_fma_f32 v84, v116, s8, v148
	v_fma_f32 v85, v117, s8, v148
	v_fma_f32 v82, v114, s8, v148
	v_fma_f32 v83, v115, s8, v148
	v_fma_f32 v80, v112, s8, v148
	v_fma_f32 v81, v113, s8, v148
	v_fma_f32 v78, v110, s8, v148
	v_fma_f32 v79, v111, s8, v148
	v_fma_f32 v76, v108, s8, v148
	v_fma_f32 v77, v109, s8, v148
	v_fma_f32 v74, v106, s8, v148
	v_fma_f32 v75, v107, s8, v148
	v_fma_f32 v72, v104, s8, v148
	v_fma_f32 v73, v105, s8, v148
	v_mfma_f32_32x32x16_bf16 v[34:49], v[138:141], v[152:155], v[34:49]
	v_fma_f32 v70, v102, s8, v148
	v_fma_f32 v71, v103, s8, v148
	v_fma_f32 v68, v100, s8, v148
	v_fma_f32 v69, v101, s8, v148
	v_fma_f32 v66, v98, s8, v148
	v_fma_f32 v67, v99, s8, v148
	ds_read_b64_tr_b16 v[98:99], v188 offset:0x600
	ds_read_b64_tr_b16 v[100:101], v188 offset:0xe00
	ds_read_b64_tr_b16 v[102:103], v188 offset:0x1600
	ds_read_b64_tr_b16 v[104:105], v188 offset:0x1e00
	v_mfma_f32_32x32x16_bf16 v[34:49], v[130:133], v[156:159], v[34:49]
	ds_read_b64_tr_b16 v[106:107], v188 offset:0x2600
	ds_read_b64_tr_b16 v[108:109], v188 offset:0x2e00
	ds_read_b64_tr_b16 v[110:111], v188 offset:0x3600
	ds_read_b64_tr_b16 v[112:113], v188 offset:0x3e00
	s_waitcnt lgkmcnt(0)
	v_mfma_f32_32x32x16_bf16 v[2:17], v[142:145], v[98:101], v[2:17]
	v_exp_f32_e32 v82, v82
	v_exp_f32_e32 v83, v83
	v_exp_f32_e32 v84, v84
	v_exp_f32_e32 v85, v85
	v_exp_f32_e32 v86, v86
	v_exp_f32_e32 v87, v87
	v_exp_f32_e32 v88, v88
	v_mfma_f32_32x32x16_bf16 v[2:17], v[134:137], v[102:105], v[2:17]
	v_exp_f32_e32 v89, v89
	v_exp_f32_e32 v90, v90
	v_exp_f32_e32 v91, v91
	v_exp_f32_e32 v92, v92
	v_exp_f32_e32 v93, v93
	v_exp_f32_e32 v94, v94
	v_exp_f32_e32 v95, v95
	v_mfma_f32_32x32x16_bf16 v[2:17], v[138:141], v[106:109], v[2:17]
	v_exp_f32_e32 v96, v96
	v_exp_f32_e32 v97, v97
	v_mfma_f32_32x32x16_bf16 v[2:17], v[130:133], v[110:113], v[2:17]
	v_cmp_gt_f32_e32 vcc, 1.0, v146
	s_barrier
; #define RESC(a) do { if (__any((a) < 1.f)) { if (hi == 0) al_l[r32] = (a); asm volatile("s_waitcnt lgkmcnt(0)" ::: "memory"); \
;     for (int d = 0; d < 4; ++d) for (int r = 0; r < 16; ++r) o[d][r] *= al_l[crow(r, hi)]; } } while (0)
; template <int MODE, int QMODE> ...
;     ...
;   __syncthreads(); RESC(alB);
	s_cbranch_vccz .LBB0_253
	v_cmp_gt_u32_e32 vcc, 32, v181
	s_and_saveexec_b64 s[2:3], vcc
	ds_write_b32 v187, v146 offset:128
	s_or_b64 exec, exec, s[2:3]
	s_waitcnt lgkmcnt(0)
	v_add_u32_e32 v110, s80, v180
	ds_read_b128 v[98:101], v110 offset:224
	ds_read_b128 v[102:105], v110 offset:192
	ds_read_b128 v[106:109], v110 offset:160
	ds_read_b128 v[110:113], v110 offset:128
	s_waitcnt lgkmcnt(3)
	v_pk_mul_f32 v[30:31], v[30:31], v[98:99]
	s_waitcnt lgkmcnt(2)
	v_pk_mul_f32 v[26:27], v[26:27], v[102:103]
	s_waitcnt lgkmcnt(1)
	v_pk_mul_f32 v[22:23], v[22:23], v[106:107]
	v_pk_mul_f32 v[32:33], v[32:33], v[100:101]
	v_pk_mul_f32 v[28:29], v[28:29], v[104:105]
	v_pk_mul_f32 v[24:25], v[24:25], v[108:109]
	s_waitcnt lgkmcnt(0)
	v_pk_mul_f32 v[20:21], v[20:21], v[112:113]
	v_pk_mul_f32 v[18:19], v[18:19], v[110:111]
	v_pk_mul_f32 v[62:63], v[62:63], v[98:99]
	v_pk_mul_f32 v[58:59], v[58:59], v[102:103]
	v_pk_mul_f32 v[54:55], v[54:55], v[106:107]
	v_pk_mul_f32 v[64:65], v[64:65], v[100:101]
	v_pk_mul_f32 v[60:61], v[60:61], v[104:105]
	v_pk_mul_f32 v[56:57], v[56:57], v[108:109]
	v_pk_mul_f32 v[52:53], v[52:53], v[112:113]
	v_pk_mul_f32 v[50:51], v[50:51], v[110:111]
	v_pk_mul_f32 v[46:47], v[46:47], v[98:99]
	v_pk_mul_f32 v[42:43], v[42:43], v[102:103]
	v_pk_mul_f32 v[38:39], v[38:39], v[106:107]
	v_pk_mul_f32 v[48:49], v[48:49], v[100:101]
	v_pk_mul_f32 v[44:45], v[44:45], v[104:105]
	v_pk_mul_f32 v[40:41], v[40:41], v[108:109]
	v_pk_mul_f32 v[36:37], v[36:37], v[112:113]
	v_pk_mul_f32 v[34:35], v[34:35], v[110:111]
	v_pk_mul_f32 v[14:15], v[14:15], v[98:99]
	v_pk_mul_f32 v[10:11], v[10:11], v[102:103]
	v_pk_mul_f32 v[6:7], v[6:7], v[106:107]
	v_pk_mul_f32 v[16:17], v[16:17], v[100:101]
	v_pk_mul_f32 v[12:13], v[12:13], v[104:105]
	v_pk_mul_f32 v[8:9], v[8:9], v[108:109]
	v_pk_mul_f32 v[4:5], v[4:5], v[112:113]
	v_pk_mul_f32 v[2:3], v[2:3], v[110:111]

; __device__ __forceinline__ int v_st(int k, int c) { const int kk = (k & ~0xC) | ((k & 4) << 1) | ((k & 8) >> 1); return ((kk >> 3) * 4 + (c >> 5)) * 512 + ((kk & 7) * 32 + (c & 31)) * 2; }
; __device__ __forceinline__ int v_rd_base(int lane) { return ((lane & 3) << 3) | (((lane >> 2) & 3) << 6) | (((lane >> 4) & 1) << 5) | (((lane >> 5) & 1) << 8); }
; #define SLOAD(i, k0) do { const long to_ = (long)(k0) * ldk * 2; const char* vt_ = (const char*)Vh + to_; const char* kt_ = (const char*)Kh + to_; \
;     sr_[i].vs0 = *(const bf16x8*)(vt_ + toff); sr_[i].vs1 = *(const bf16x8*)(vt_ + h32 + toff); \
;     sr_[i].ks0 = *(const bf16x8*)(kt_ + toff); sr_[i].ks1 = *(const bf16x8*)(kt_ + h32 + toff); } while (0)
; #define MASK(P0, P1, k0) do { if constexpr (MODE == 1) { const int k0_ = (k0); \
;     if ((k0_ + 63 - qw0 > 128) || (k0_ - (qw0 + 31) < -128)) maskwin(P0, P1, k0_ - (qw0 + r32) + 128 + 4 * hi); } } while (0)
; __device__ __forceinline__ void qkt(f32x16& p0, f32x16& p1, const bf16* Ks, const bf16x8* qr, int r32, int hi) {
;   p0 = f32x16{}; p1 = f32x16{};
;   for (int d0 = 0; d0 < 8; ++d0) { int cb = (d0 * 16 + hi * 8) * 2;
;     bf16x8 b0 = *reinterpret_cast<const bf16x8*>((const char*)Ks + KSWZ(r32, cb));
;     bf16x8 b1 = *reinterpret_cast<const bf16x8*>((const char*)Ks + KSWZ(32 + r32, cb));
;     p0 = __builtin_amdgcn_mfma_f32_32x32x16_bf16(b0, qr[d0], p0, 0, 0, 0);
;     p1 = __builtin_amdgcn_mfma_f32_32x32x16_bf16(b1, qr[d0], p1, 0, 0, 0); }
; template <int MODE, int QMODE> ...
;     ...
;   const int sr = tid >> 4, sc = (tid & 15) * 8, vst0 = v_st(sr, sc), vst1 = v_st(32 + sr, sc);
;   const int vb0 = (int)(uintptr_t)V_lds + v_rd_base(lane);
;   const unsigned toff = (unsigned)(sr * ldk + sc) * 2u; const long h32 = (long)ldk * 64;
;   constexpr int SDEPTH = (MODE == 0 && QMODE == 2) ? 2 : 1;
;   struct { typename St::T vs0, vs1, ks0, ks1; } sr_[SDEPTH];
;     ...
;   const int qw0 = qrel + wrow;
;     ...
;   if (wid >= 4) __builtin_amdgcn_s_setprio(1);
;   f32x16 pA0, pA1, pB0, pB1; float mnA, mnB, alA, alB; bf16x8 pa0, pa1, pa2, pa3; const int NT = seq / KVBLK;
;   constexpr int SE = 0, SO = SDEPTH - 1;
;   SLOAD(SE, 0); asm volatile("s_waitcnt vmcnt(0)" ::: "memory"); SWRITE(0, SE); __syncthreads();
;   qkt(pA0, pA1, K_lds, qr, r32, hi); MASK(pA0, pA1, 0); partialSM(pA0, pA1, m_reg, mnA, alA);
.LBB0_292:
	s_add_i32 s4, s13, 0xffffc000
	s_lshr_b32 s4, s4, 5
	s_and_b32 s4, s4, 0x7ffff00
	s_add_i32 s8, s4, 0x100
	s_lshl_b64 s[4:5], s[8:9], 10
	s_cmpk_gt_i32 s18, 0x3fff
	s_cselect_b32 s5, s5, 0
	s_cselect_b32 s4, s4, 0
	s_lshl_b64 s[4:5], s[4:5], 1
	s_add_u32 s4, s42, s4
	s_addc_u32 s5, s43, s5
	s_lshl_b32 s8, s3, 1
	s_add_u32 s4, s4, s8
	v_lshlrev_b32_e32 v19, 3, v35
	s_addc_u32 s5, s5, 0
	v_and_b32_e32 v2, 0x78, v19
	s_add_u32 s20, s4, 0x400
	v_ashrrev_i32_e32 v18, 4, v35
	v_lshlrev_b32_e32 v20, 1, v2
	s_addc_u32 s21, s5, 0
	v_lshl_or_b32 v10, v18, 11, v20
	v_mov_b32_e32 v11, v195
	v_lshl_add_u64 v[178:179], s[20:21], 0, v[10:11]
	v_add_co_u32_e32 v2, vcc, s24, v178
	v_lshl_add_u64 v[186:187], s[4:5], 0, v[10:11]
	s_nop 0
	v_addc_co_u32_e32 v3, vcc, 0, v179, vcc
	global_load_dwordx4 v[2:5], v[2:3], off
	s_nop 0
	global_load_dwordx4 v[6:9], v10, s[4:5] offset:1024
	s_nop 0
	global_load_dwordx4 v[10:13], v10, s[4:5]
	v_add_co_u32_e32 v14, vcc, s24, v186
	v_lshlrev_b32_e32 v22, 4, v34
	s_nop 0
	v_addc_co_u32_e32 v15, vcc, 0, v187, vcc
	global_load_dwordx4 v[14:17], v[14:15], off
	v_and_b32_e32 v23, 0xfffff0, v18
	v_lshlrev_b32_e32 v24, 1, v18
	v_lshrrev_b32_e32 v25, 1, v18
	v_and_b32_e32 v26, 3, v18
	v_add_u32_e32 v27, 32, v18
	v_and_b32_e32 v45, 0xf0, v22
	v_and_or_b32 v22, v24, 8, v23
	v_and_or_b32 v23, v25, 4, v26
	v_and_b32_e32 v24, 0xfffff0, v27
	v_lshlrev_b32_e32 v25, 1, v27
	v_and_b32_e32 v21, 0xf0, v35
	v_bfe_u32 v19, v19, 5, 2
	v_lshlrev_b32_e32 v18, 8, v18
	v_lshlrev_b32_e32 v26, 8, v27
	v_lshrrev_b32_e32 v22, 1, v22
	v_and_or_b32 v24, v25, 8, v24
	v_and_b32_e32 v28, 48, v20
	v_bitop3_b32 v18, v20, v18, v21 bitop3:0xde
	v_bitop3_b32 v20, v20, v26, v21 bitop3:0xde
	v_or_b32_e32 v21, v22, v19
	v_lshrrev_b32_e32 v22, 1, v24
	v_lshlrev_b32_e32 v44, 8, v34
	v_lshlrev_b32_e32 v23, 6, v23
	v_add_u32_e32 v214, 0, v18
	v_lshlrev_b32_e32 v18, 9, v21
	v_or_b32_e32 v19, v22, v19
	v_bitop3_b32 v27, v194, v44, v45 bitop3:0xde
	v_or3_b32 v18, v18, v23, v28
	v_lshlrev_b32_e32 v19, 9, v19
	v_add_u32_e32 v203, 0, v27
	v_or3_b32 v19, v19, v23, v28
	v_add_u32_e32 v216, 0, v18
	v_add_u32_e32 v215, 0, v20
	v_add_u32_e32 v217, 0, v19
	s_waitcnt vmcnt(0)
	v_and_b32_e32 v35, 63, v35
	v_or_b32_e32 v46, 0xc0, v194
	v_or_b32_e32 v47, 0xe0, v194
	v_lshlrev_b32_e32 v48, 3, v35
	v_and_b32_e32 v51, 0x100, v48
	s_and_b32 s2, s2, 0x3fffffc0
	s_lshl_b32 s2, s2, 2
	s_add_i32 s59, s2, 0
	s_add_i32 s59, s59, 0x10000
	s_cmp_lg_u32 0, -1
	s_cselect_b32 s2, 0, 0
	v_cmp_gt_u32_e64 s[4:5], 32, v35
	v_lshl_add_u32 v197, v34, 2, s59
	s_waitcnt vmcnt(2)
	ds_write_b128 v216, v[6:9]
	ds_write_b128 v217, v[2:5]
	s_waitcnt vmcnt(1)
	ds_write_b128 v214, v[10:13] offset:32768
	s_waitcnt vmcnt(0)
	ds_write_b128 v215, v[14:17] offset:32768
	s_waitcnt lgkmcnt(0)
	s_barrier
	ds_read_b128 v[2:5], v203 offset:32768
	ds_read_b128 v[6:9], v203 offset:40960
	s_waitcnt lgkmcnt(1)
	v_mfma_f32_32x32x16_bf16 v[18:33], v[2:5], v[158:161], 0
	v_or_b32_e32 v2, 32, v194
	v_bitop3_b32 v2, v2, v44, v45 bitop3:0xde
	v_add_u32_e32 v204, 0, v2
	ds_read_b128 v[36:39], v204 offset:32768
	ds_read_b128 v[40:43], v204 offset:40960
	s_waitcnt lgkmcnt(2)
	v_mfma_f32_32x32x16_bf16 v[2:17], v[6:9], v[158:161], 0
	s_waitcnt lgkmcnt(1)
	v_mfma_f32_32x32x16_bf16 v[18:33], v[36:39], v[154:157], v[18:33]
	v_or_b32_e32 v36, 64, v194
	v_bitop3_b32 v36, v36, v44, v45 bitop3:0xde
	v_add_u32_e32 v205, 0, v36
	s_waitcnt lgkmcnt(0)
	v_mfma_f32_32x32x16_bf16 v[2:17], v[40:43], v[154:157], v[2:17]
	ds_read_b128 v[36:39], v205 offset:32768
	ds_read_b128 v[40:43], v205 offset:40960
	s_waitcnt lgkmcnt(1)
	v_mfma_f32_32x32x16_bf16 v[18:33], v[36:39], v[150:153], v[18:33]
	v_or_b32_e32 v36, 0x60, v194
	v_bitop3_b32 v36, v36, v44, v45 bitop3:0xde
	v_add_u32_e32 v206, 0, v36
	s_waitcnt lgkmcnt(0)
	v_mfma_f32_32x32x16_bf16 v[2:17], v[40:43], v[150:153], v[2:17]
	ds_read_b128 v[36:39], v206 offset:32768
	ds_read_b128 v[40:43], v206 offset:40960
	s_waitcnt lgkmcnt(1)
	v_mfma_f32_32x32x16_bf16 v[18:33], v[36:39], v[146:149], v[18:33]
	v_or_b32_e32 v36, 0x80, v194
	v_bitop3_b32 v36, v36, v44, v45 bitop3:0xde
	v_add_u32_e32 v207, 0, v36
	s_waitcnt lgkmcnt(0)
	v_mfma_f32_32x32x16_bf16 v[2:17], v[40:43], v[146:149], v[2:17]
	ds_read_b128 v[36:39], v207 offset:32768
	ds_read_b128 v[40:43], v207 offset:40960
	s_waitcnt lgkmcnt(1)
	v_mfma_f32_32x32x16_bf16 v[18:33], v[36:39], v[142:145], v[18:33]
	v_or_b32_e32 v36, 0xa0, v194
	v_bitop3_b32 v36, v36, v44, v45 bitop3:0xde
	v_add_u32_e32 v209, 0, v36
	ds_read_b128 v[36:39], v209 offset:32768
	s_waitcnt lgkmcnt(1)
	v_mfma_f32_32x32x16_bf16 v[2:17], v[40:43], v[142:145], v[2:17]
	v_lshlrev_b32_e32 v40, 4, v35
	v_lshlrev_b32_e32 v41, 1, v35
	v_and_b32_e32 v49, 0xc0, v40
	v_and_b32_e32 v50, 32, v41
	ds_read_b128 v[40:43], v209 offset:40960
	s_waitcnt lgkmcnt(1)
	v_mfma_f32_32x32x16_bf16 v[18:33], v[36:39], v[138:141], v[18:33]
	v_bitop3_b32 v36, v46, v44, v45 bitop3:0xde
	v_bitop3_b32 v37, v47, v44, v45 bitop3:0xde
	v_add_u32_e32 v211, 0, v36
	v_add_u32_e32 v210, 0, v37
	ds_read_b128 v[36:39], v211 offset:32768
	v_and_or_b32 v44, v48, 24, v49
	v_add_co_u32_e32 v48, vcc, s26, v186
	s_waitcnt lgkmcnt(1)
	v_mfma_f32_32x32x16_bf16 v[2:17], v[40:43], v[138:141], v[2:17]
	ds_read_b128 v[40:43], v211 offset:40960
	v_addc_co_u32_e32 v49, vcc, 0, v187, vcc
	v_add_co_u32_e32 v52, vcc, s27, v186
	v_or3_b32 v162, v44, v50, v51
	s_nop 0
	v_addc_co_u32_e32 v53, vcc, 0, v187, vcc
	s_waitcnt lgkmcnt(1)
	v_mfma_f32_32x32x16_bf16 v[18:33], v[36:39], v[134:137], v[18:33]
	ds_read_b128 v[36:39], v210 offset:32768
	v_add_co_u32_e32 v44, vcc, s26, v178
	v_add_u32_e32 v201, s2, v162
	s_nop 0
	v_addc_co_u32_e32 v45, vcc, 0, v179, vcc
	v_add_co_u32_e32 v46, vcc, s27, v178
	s_waitcnt lgkmcnt(1)
; __device__ __forceinline__ void partialSM(f32x16& p0, f32x16& p1, float& m_reg, float& mn, float& alpha) {
;   constexpr float C = SCALE * 1.4426950408889634f;
;   float pmax = p0[0]; for (int r = 1; r < 16; ++r) pmax = fmaxf(pmax, p0[r]); for (int r = 0; r < 16; ++r) pmax = fmaxf(pmax, p1[r]);
;   { auto rr = __builtin_amdgcn_permlane32_swap(__float_as_uint(pmax), __float_as_uint(pmax), false, false);
;     pmax = fmaxf(__uint_as_float(rr[0]), __uint_as_float(rr[1])); }
;   if (__builtin_expect(__all(pmax - m_reg <= THR / SCALE), 1)) { mn = m_reg; alpha = 1.f; }
;   else { mn = fmaxf(m_reg, pmax); alpha = __builtin_amdgcn_exp2f((m_reg - mn) * C); m_reg = mn; }
;   float mnC = -mn * C;
;   for (int r = 0; r < 16; ++r) p0[r] = fmaf(p0[r], C, mnC); for (int r = 0; r < 16; ++r) p1[r] = fmaf(p1[r], C, mnC);
;   for (int r = 0; r < 16; ++r) p0[r] = __builtin_amdgcn_exp2f(p0[r]);
; }
; __device__ __forceinline__ void psm_decide(float pmax, const f32x16& p1, float& m_reg, float& mn, float& alpha) {
;   constexpr float C = SCALE * 1.4426950408889634f;
;   for (int r = 0; r < 16; ++r) pmax = fmaxf(pmax, p1[r]);
;   { auto rr = __builtin_amdgcn_permlane32_swap(__float_as_uint(pmax), __float_as_uint(pmax), false, false);
;     pmax = fmaxf(__uint_as_float(rr[0]), __uint_as_float(rr[1])); }
;   if (__builtin_expect(__all(pmax - m_reg <= THR / SCALE), 1)) { mn = m_reg; alpha = 1.f; }
;   else { mn = fmaxf(m_reg, pmax); alpha = __builtin_amdgcn_exp2f((m_reg - mn) * C); m_reg = mn; }
; }
; __device__ __forceinline__ void psm_scale(f32x16& p0, f32x16& p1, float mn) {
;   constexpr float C = SCALE * 1.4426950408889634f; const float mnC = -mn * C;
;   for (int r = 0; r < 16; ++r) p0[r] = fmaf(p0[r], C, mnC); for (int r = 0; r < 16; ++r) p1[r] = fmaf(p1[r], C, mnC);
; }
; __device__ __forceinline__ void finishSM(f32x16& p0, f32x16& p1, float alpha, float& l_reg, bf16x8& pa0, bf16x8& pa1, bf16x8& pa2, bf16x8& pa3) {
;   for (int r = 0; r < 16; ++r) p1[r] = __builtin_amdgcn_exp2f(p1[r]);
;   float ps = 0; for (int r = 0; r < 16; ++r) ps += p0[r]; for (int r = 0; r < 16; ++r) ps += p1[r];
;   { auto rr = __builtin_amdgcn_permlane32_swap(__float_as_uint(ps), __float_as_uint(ps), false, false);
;     ps = __uint_as_float(rr[0]) + __uint_as_float(rr[1]); }
;   l_reg = l_reg * alpha + ps;
;     ...
;   PK4(p0, 0, pa0); PK4(p0, 8, pa1); PK4(p1, 0, pa2); PK4(p1, 8, pa3);
;     ...
; }
	v_mfma_f32_32x32x16_bf16 v[2:17], v[40:43], v[134:137], v[2:17]
	v_addc_co_u32_e32 v47, vcc, 0, v179, vcc
	ds_read_b128 v[40:43], v210 offset:40960
	s_waitcnt lgkmcnt(1)
	v_mfma_f32_32x32x16_bf16 v[18:33], v[36:39], v[130:133], v[18:33]
	global_load_dwordx4 v[36:39], v[44:45], off
	s_nop 0
	global_load_dwordx4 v[44:47], v[46:47], off
	s_nop 0
	global_load_dwordx4 v[48:51], v[48:49], off
	s_nop 0
	global_load_dwordx4 v[52:55], v[52:53], off
	s_waitcnt vmcnt(0)
	s_waitcnt vmcnt(3)
	ds_write_b128 v216, v[36:39] offset:16384
	s_waitcnt vmcnt(2)
	ds_write_b128 v217, v[44:47] offset:16384
	s_waitcnt vmcnt(1)
	ds_write_b128 v214, v[48:51] offset:49152
	s_waitcnt vmcnt(0)
	ds_write_b128 v215, v[52:55] offset:49152
	s_waitcnt lgkmcnt(4)
	v_mfma_f32_32x32x16_bf16 v[2:17], v[40:43], v[130:133], v[2:17]
	v_max_f32_e32 v40, v19, v19
	v_max_f32_e32 v41, v18, v18
	v_max_f32_e32 v40, v41, v40
	v_max3_f32 v40, v40, v20, v21
	v_max3_f32 v40, v40, v22, v23
	v_max3_f32 v40, v40, v24, v25
	v_max3_f32 v40, v40, v26, v27
	v_max3_f32 v40, v40, v28, v29
	v_max3_f32 v40, v40, v30, v31
	v_max3_f32 v40, v40, v32, v33
	s_nop 1
	v_max3_f32 v40, v40, v2, v3
	v_max3_f32 v40, v40, v4, v5
	v_max3_f32 v40, v40, v6, v7
	v_max3_f32 v40, v40, v8, v9
	v_max3_f32 v40, v40, v10, v11
	v_max3_f32 v40, v40, v12, v13
	v_max3_f32 v40, v40, v14, v15
	v_max3_f32 v40, v40, v16, v17
	v_mov_b32_e32 v41, v40
	s_nop 1
	v_permlane32_swap_b32_e32 v40, v41
	v_max_f32_e32 v41, v41, v41
	v_max_f32_e32 v40, v40, v40
	v_max_f32_e32 v40, v40, v41
	v_add_f32_e32 v41, 0x7149f2ca, v40
	v_cmp_ge_f32_e32 vcc, s25, v41
	s_cmp_eq_u64 vcc, exec
	v_max_f32_e32 v163, 0xf149f2ca, v40
	s_cselect_b64 s[2:3], -1, 0
	v_cndmask_b32_e64 v82, v163, v1, s[2:3]
	v_mul_f32_e32 v83, 0xbe0293ee, v82
	v_fmamk_f32 v18, v18, 0x3e0293ee, v83
	v_fmamk_f32 v19, v19, 0x3e0293ee, v83
	v_fmamk_f32 v20, v20, 0x3e0293ee, v83
	v_fmamk_f32 v21, v21, 0x3e0293ee, v83
	v_fmamk_f32 v22, v22, 0x3e0293ee, v83
	v_fmamk_f32 v23, v23, 0x3e0293ee, v83
	v_fmamk_f32 v24, v24, 0x3e0293ee, v83
	v_fmamk_f32 v25, v25, 0x3e0293ee, v83
	v_fmamk_f32 v26, v26, 0x3e0293ee, v83
	v_fmamk_f32 v27, v27, 0x3e0293ee, v83
	v_fmamk_f32 v28, v28, 0x3e0293ee, v83
	v_fmamk_f32 v29, v29, 0x3e0293ee, v83
	v_fmamk_f32 v30, v30, 0x3e0293ee, v83
	v_fmamk_f32 v31, v31, 0x3e0293ee, v83
	v_fmamk_f32 v32, v32, 0x3e0293ee, v83
	v_fmamk_f32 v33, v33, 0x3e0293ee, v83
	v_fmamk_f32 v84, v2, 0x3e0293ee, v83
	v_fmamk_f32 v85, v3, 0x3e0293ee, v83
	v_fmamk_f32 v86, v4, 0x3e0293ee, v83
	v_fmamk_f32 v87, v5, 0x3e0293ee, v83
	v_fmamk_f32 v88, v6, 0x3e0293ee, v83
	v_fmamk_f32 v89, v7, 0x3e0293ee, v83
	v_fmamk_f32 v90, v8, 0x3e0293ee, v83
	v_fmamk_f32 v91, v9, 0x3e0293ee, v83
	v_fmamk_f32 v92, v10, 0x3e0293ee, v83
	v_fmamk_f32 v93, v11, 0x3e0293ee, v83
	v_fmamk_f32 v94, v12, 0x3e0293ee, v83
	v_fmamk_f32 v95, v13, 0x3e0293ee, v83
	v_fmamk_f32 v96, v14, 0x3e0293ee, v83
	v_fmamk_f32 v97, v15, 0x3e0293ee, v83
	v_fmamk_f32 v98, v16, 0x3e0293ee, v83
	v_fmac_f32_e32 v83, 0x3e0293ee, v17
	v_exp_f32_e32 v99, v18
	v_exp_f32_e32 v100, v19
	v_exp_f32_e32 v101, v20
	v_exp_f32_e32 v102, v21
	v_exp_f32_e32 v103, v22
	v_exp_f32_e32 v104, v23
	v_exp_f32_e32 v105, v24
	v_exp_f32_e32 v109, v25
	v_exp_f32_e32 v110, v26
	v_exp_f32_e32 v111, v27
	v_exp_f32_e32 v112, v28
	v_exp_f32_e32 v113, v29
	v_exp_f32_e32 v114, v30
	v_exp_f32_e32 v115, v31
	v_exp_f32_e32 v116, v32
	v_exp_f32_e32 v117, v33
	s_waitcnt lgkmcnt(0)
	s_barrier
	ds_read_b128 v[2:5], v203 offset:49152
	ds_read_b128 v[6:9], v203 offset:57344
	v_exp_f32_e32 v84, v84
	v_exp_f32_e32 v85, v85
	v_exp_f32_e32 v86, v86
	s_waitcnt lgkmcnt(1)
	v_mfma_f32_32x32x16_bf16 v[66:81], v[2:5], v[158:161], 0
	v_exp_f32_e32 v87, v87
	v_exp_f32_e32 v88, v88
	s_waitcnt lgkmcnt(0)
	v_mfma_f32_32x32x16_bf16 v[50:65], v[6:9], v[158:161], 0
	ds_read_b128 v[2:5], v204 offset:49152
	ds_read_b128 v[6:9], v204 offset:57344
	ds_read_b128 v[10:13], v205 offset:49152
	ds_read_b128 v[14:17], v205 offset:57344
	s_waitcnt lgkmcnt(3)
	v_mfma_f32_32x32x16_bf16 v[66:81], v[2:5], v[154:157], v[66:81]
	ds_read_b128 v[2:5], v206 offset:49152
	ds_read_b128 v[18:21], v206 offset:57344
	ds_read_b128 v[22:25], v207 offset:49152
	ds_read_b128 v[26:29], v207 offset:57344
	ds_read_b128 v[30:33], v209 offset:49152
	ds_read_b128 v[34:37], v209 offset:57344
	ds_read_b128 v[38:41], v211 offset:49152
	ds_read_b128 v[42:45], v211 offset:57344
	s_waitcnt lgkmcnt(10)
	v_mfma_f32_32x32x16_bf16 v[50:65], v[6:9], v[154:157], v[50:65]
	ds_read_b128 v[6:9], v210 offset:49152
	ds_read_b128 v[46:49], v210 offset:57344
	v_cvt_pk_bf16_f32 v106, v99, v100
	v_cvt_pk_bf16_f32 v107, v101, v102
	v_cvt_pk_bf16_f32 v108, v103, v104
	s_nop 0
	v_permlane32_swap_b32_e32 v106, v108
	s_waitcnt lgkmcnt(11)
	v_mfma_f32_32x32x16_bf16 v[66:81], v[10:13], v[150:153], v[66:81]
	v_exp_f32_e32 v10, v89
	v_exp_f32_e32 v11, v90
	v_exp_f32_e32 v12, v91
	v_exp_f32_e32 v13, v92
	v_exp_f32_e32 v89, v93
	v_exp_f32_e32 v90, v94
	v_exp_f32_e32 v91, v95
	s_waitcnt lgkmcnt(10)
	v_mfma_f32_32x32x16_bf16 v[50:65], v[14:17], v[150:153], v[50:65]
	v_exp_f32_e32 v17, v83
	v_add_f32_e32 v83, 0, v99
	v_add_f32_e32 v83, v100, v83
	v_add_f32_e32 v83, v101, v83
	v_exp_f32_e32 v14, v96
	v_exp_f32_e32 v15, v97
	v_exp_f32_e32 v16, v98
	s_waitcnt lgkmcnt(9)
	v_mfma_f32_32x32x16_bf16 v[66:81], v[2:5], v[146:149], v[66:81]
	v_add_f32_e32 v2, v102, v83
	v_add_f32_e32 v2, v103, v2
	v_add_f32_e32 v2, v104, v2
	v_add_f32_e32 v2, v105, v2
	v_add_f32_e32 v2, v109, v2
	v_add_f32_e32 v2, v110, v2
	v_add_f32_e32 v2, v111, v2
	s_waitcnt lgkmcnt(8)
; __device__ __forceinline__ void psm_decide(float pmax, const f32x16& p1, float& m_reg, float& mn, float& alpha) {
;   constexpr float C = SCALE * 1.4426950408889634f;
;   for (int r = 0; r < 16; ++r) pmax = fmaxf(pmax, p1[r]);
;   { auto rr = __builtin_amdgcn_permlane32_swap(__float_as_uint(pmax), __float_as_uint(pmax), false, false);
;     pmax = fmaxf(__uint_as_float(rr[0]), __uint_as_float(rr[1])); }
;   if (__builtin_expect(__all(pmax - m_reg <= THR / SCALE), 1)) { mn = m_reg; alpha = 1.f; }
;   else { mn = fmaxf(m_reg, pmax); alpha = __builtin_amdgcn_exp2f((m_reg - mn) * C); m_reg = mn; }
; }
; __device__ __forceinline__ void psm_scale(f32x16& p0, f32x16& p1, float mn) {
;   constexpr float C = SCALE * 1.4426950408889634f; const float mnC = -mn * C;
;   for (int r = 0; r < 16; ++r) p0[r] = fmaf(p0[r], C, mnC); for (int r = 0; r < 16; ++r) p1[r] = fmaf(p1[r], C, mnC);
; }
; __device__ __forceinline__ void finishSM(f32x16& p0, f32x16& p1, float alpha, float& l_reg, bf16x8& pa0, bf16x8& pa1, bf16x8& pa2, bf16x8& pa3) {
;   for (int r = 0; r < 16; ++r) p1[r] = __builtin_amdgcn_exp2f(p1[r]);
;   float ps = 0; for (int r = 0; r < 16; ++r) ps += p0[r]; for (int r = 0; r < 16; ++r) ps += p1[r];
;   { auto rr = __builtin_amdgcn_permlane32_swap(__float_as_uint(ps), __float_as_uint(ps), false, false);
;     ps = __uint_as_float(rr[0]) + __uint_as_float(rr[1]); }
;   l_reg = l_reg * alpha + ps;
;     ...
;   PK4(p0, 0, pa0); PK4(p0, 8, pa1); PK4(p1, 0, pa2); PK4(p1, 8, pa3);
;     ...
; }
; __device__ __forceinline__ void qkt(f32x16& p0, f32x16& p1, const bf16* Ks, const bf16x8* qr, int r32, int hi) {
;   p0 = f32x16{}; p1 = f32x16{};
;   for (int d0 = 0; d0 < 8; ++d0) { int cb = (d0 * 16 + hi * 8) * 2;
;     bf16x8 b0 = *reinterpret_cast<const bf16x8*>((const char*)Ks + KSWZ(r32, cb));
;     bf16x8 b1 = *reinterpret_cast<const bf16x8*>((const char*)Ks + KSWZ(32 + r32, cb));
;     p0 = __builtin_amdgcn_mfma_f32_32x32x16_bf16(b0, qr[d0], p0, 0, 0, 0);
;     p1 = __builtin_amdgcn_mfma_f32_32x32x16_bf16(b1, qr[d0], p1, 0, 0, 0); }
; }
; __device__ __forceinline__ int v_st(int k, int c) { const int kk = (k & ~0xC) | ((k & 4) << 1) | ((k & 8) >> 1); return ((kk >> 3) * 4 + (c >> 5)) * 512 + ((kk & 7) * 32 + (c & 31)) * 2; }
; __device__ __forceinline__ int v_rd_base(int lane) { return ((lane & 3) << 3) | (((lane >> 2) & 3) << 6) | (((lane >> 4) & 1) << 5) | (((lane >> 5) & 1) << 8); }
	v_mfma_f32_32x32x16_bf16 v[50:65], v[18:21], v[146:149], v[50:65]
	v_add_f32_e32 v2, v112, v2
	v_add_f32_e32 v2, v113, v2
	v_add_f32_e32 v2, v114, v2
	v_add_f32_e32 v2, v115, v2
	v_add_f32_e32 v2, v116, v2
	v_add_f32_e32 v2, v117, v2
	v_add_f32_e32 v2, v84, v2
	s_waitcnt lgkmcnt(7)
	v_mfma_f32_32x32x16_bf16 v[66:81], v[22:25], v[142:145], v[66:81]
	v_add_f32_e32 v2, v85, v2
	v_add_f32_e32 v2, v86, v2
	v_add_f32_e32 v2, v87, v2
	v_add_f32_e32 v2, v88, v2
	v_add_f32_e32 v2, v10, v2
	v_add_f32_e32 v2, v11, v2
	v_add_f32_e32 v2, v12, v2
	s_waitcnt lgkmcnt(6)
	v_mfma_f32_32x32x16_bf16 v[50:65], v[26:29], v[142:145], v[50:65]
	v_add_f32_e32 v2, v13, v2
	v_add_f32_e32 v2, v89, v2
	v_add_f32_e32 v2, v90, v2
	v_add_f32_e32 v2, v91, v2
	v_add_f32_e32 v2, v14, v2
	v_add_f32_e32 v2, v15, v2
	v_add_f32_e32 v2, v16, v2
	s_waitcnt lgkmcnt(5)
	v_mfma_f32_32x32x16_bf16 v[66:81], v[30:33], v[138:141], v[66:81]
	v_add_f32_e32 v198, v17, v2
	v_mov_b32_e32 v199, v198
	s_nop 1
	v_permlane32_swap_b32_e32 v198, v199
	v_cvt_pk_bf16_f32 v109, v105, v109
	v_cvt_pk_bf16_f32 v102, v110, v111
	v_cvt_pk_bf16_f32 v103, v112, v113
	s_waitcnt lgkmcnt(4)
	v_mfma_f32_32x32x16_bf16 v[50:65], v[34:37], v[138:141], v[50:65]
	v_cvt_pk_bf16_f32 v104, v114, v115
	v_cvt_pk_bf16_f32 v105, v116, v117
	v_cvt_pk_bf16_f32 v110, v84, v85
	v_cvt_pk_bf16_f32 v111, v86, v87
	v_cvt_pk_bf16_f32 v112, v88, v10
	v_cvt_pk_bf16_f32 v113, v11, v12
	v_cvt_pk_bf16_f32 v98, v13, v89
	s_waitcnt lgkmcnt(3)
	v_mfma_f32_32x32x16_bf16 v[66:81], v[38:41], v[134:137], v[66:81]
	v_cvt_pk_bf16_f32 v99, v90, v91
	v_cvt_pk_bf16_f32 v100, v14, v15
	v_cvt_pk_bf16_f32 v101, v16, v17
	v_permlane32_swap_b32_e32 v107, v109
	v_permlane32_swap_b32_e32 v102, v104
	s_waitcnt lgkmcnt(2)
	v_mfma_f32_32x32x16_bf16 v[50:65], v[42:45], v[134:137], v[50:65]
	v_permlane32_swap_b32_e32 v103, v105
	v_permlane32_swap_b32_e32 v110, v112
	v_permlane32_swap_b32_e32 v111, v113
	v_permlane32_swap_b32_e32 v98, v100
	s_waitcnt lgkmcnt(1)
	v_mfma_f32_32x32x16_bf16 v[66:81], v[6:9], v[130:133], v[66:81]
	v_permlane32_swap_b32_e32 v99, v101
	s_waitcnt lgkmcnt(0)
	v_mfma_f32_32x32x16_bf16 v[50:65], v[46:49], v[130:133], v[50:65]
	v_add_co_u32_e32 v2, vcc, s28, v178
	s_nop 1
	v_addc_co_u32_e32 v3, vcc, 0, v179, vcc
	v_add_co_u32_e32 v4, vcc, s29, v178
	s_nop 1
	v_addc_co_u32_e32 v5, vcc, 0, v179, vcc
	global_load_dwordx4 v[114:117], v[2:3], off
	global_load_dwordx4 v[118:121], v[4:5], off
	v_add_co_u32_e32 v2, vcc, s28, v186
	s_nop 1
	v_addc_co_u32_e32 v3, vcc, 0, v187, vcc
	v_add_co_u32_e32 v4, vcc, s29, v186
	s_nop 1
	v_addc_co_u32_e32 v5, vcc, 0, v187, vcc
	global_load_dwordx4 v[122:125], v[2:3], off
	global_load_dwordx4 v[126:129], v[4:5], off
	ds_read_b64_tr_b16 v[2:3], v201 offset:0
	ds_read_b64_tr_b16 v[4:5], v201 offset:0x800
	ds_read_b64_tr_b16 v[18:19], v201 offset:0x1000
	ds_read_b64_tr_b16 v[20:21], v201 offset:0x1800
	ds_read_b64_tr_b16 v[22:23], v201 offset:0x2000
	ds_read_b64_tr_b16 v[24:25], v201 offset:0x2800
	ds_read_b64_tr_b16 v[26:27], v201 offset:0x3000
	ds_read_b64_tr_b16 v[28:29], v201 offset:0x3800
	s_waitcnt lgkmcnt(0)
	s_nop 0
	v_mfma_f32_32x32x16_bf16 v[2:17], v[106:109], v[2:5], 0
	v_max_f32_e32 v30, v67, v67
	v_max_f32_e32 v31, v66, v66
	v_max_f32_e32 v30, v31, v30
	v_max3_f32 v30, v30, v68, v69
	v_mfma_f32_32x32x16_bf16 v[2:17], v[102:105], v[18:21], v[2:17]
	v_max3_f32 v18, v30, v70, v71
	v_max3_f32 v18, v18, v72, v73
	v_max3_f32 v18, v18, v74, v75
	v_max3_f32 v18, v18, v76, v77
	v_max3_f32 v20, v18, v78, v79
	ds_read_b64_tr_b16 v[18:19], v201 offset:0x200
	v_max3_f32 v30, v20, v80, v81
	v_mfma_f32_32x32x16_bf16 v[2:17], v[110:113], v[22:25], v[2:17]
	ds_read_b64_tr_b16 v[20:21], v201 offset:0xa00
	ds_read_b64_tr_b16 v[34:35], v201 offset:0x1200
	ds_read_b64_tr_b16 v[36:37], v201 offset:0x1a00
	ds_read_b64_tr_b16 v[38:39], v201 offset:0x2200
	ds_read_b64_tr_b16 v[40:41], v201 offset:0x2a00
	ds_read_b64_tr_b16 v[42:43], v201 offset:0x3200
	ds_read_b64_tr_b16 v[44:45], v201 offset:0x3a00
	v_mfma_f32_32x32x16_bf16 v[2:17], v[98:101], v[26:29], v[2:17]
	s_waitcnt lgkmcnt(0)
	v_max3_f32 v22, v30, v50, v51
	v_max3_f32 v22, v22, v52, v53
	v_max3_f32 v22, v22, v54, v55
	v_max3_f32 v22, v22, v56, v57
	v_max3_f32 v22, v22, v58, v59
	v_max3_f32 v46, v22, v60, v61
	v_mfma_f32_32x32x16_bf16 v[18:33], v[106:109], v[18:21], 0
	v_max3_f32 v46, v46, v62, v63
	v_max3_f32 v46, v46, v64, v65
	v_mov_b32_e32 v47, v46
	s_nop 1
	v_permlane32_swap_b32_e32 v46, v47
	v_max_f32_e32 v47, v47, v47
	v_max_f32_e32 v46, v46, v46
	v_mfma_f32_32x32x16_bf16 v[18:33], v[102:105], v[34:37], v[18:33]
	v_max_f32_e32 v34, v46, v47
	v_sub_f32_e32 v35, v34, v82
	v_max_f32_e32 v34, v82, v34
	v_cmp_ge_f32_e32 vcc, s25, v35
	v_sub_f32_e32 v35, v82, v34
	v_mul_f32_e32 v35, 0x3e0293ee, v35
	v_exp_f32_e32 v35, v35
	v_mfma_f32_32x32x16_bf16 v[18:33], v[110:113], v[38:41], v[18:33]
	s_cmp_eq_u64 vcc, exec
	s_cselect_b64 vcc, -1, 0
	v_cndmask_b32_e32 v218, v34, v82, vcc
	v_cndmask_b32_e64 v200, v35, 1.0, vcc
	ds_read_b64_tr_b16 v[34:35], v201 offset:0x400
	ds_read_b64_tr_b16 v[36:37], v201 offset:0xc00
	ds_read_b64_tr_b16 v[164:165], v201 offset:0x1400
	v_mfma_f32_32x32x16_bf16 v[18:33], v[98:101], v[42:45], v[18:33]
	ds_read_b64_tr_b16 v[166:167], v201 offset:0x1c00
	ds_read_b64_tr_b16 v[168:169], v201 offset:0x2400
	ds_read_b64_tr_b16 v[170:171], v201 offset:0x2c00
	ds_read_b64_tr_b16 v[172:173], v201 offset:0x3400
	ds_read_b64_tr_b16 v[174:175], v201 offset:0x3c00
	s_waitcnt lgkmcnt(0)
; __device__ __forceinline__ void psm_scale(f32x16& p0, f32x16& p1, float mn) {
;   constexpr float C = SCALE * 1.4426950408889634f; const float mnC = -mn * C;
;   for (int r = 0; r < 16; ++r) p0[r] = fmaf(p0[r], C, mnC); for (int r = 0; r < 16; ++r) p1[r] = fmaf(p1[r], C, mnC);
; }
; __device__ __forceinline__ void finishSM(f32x16& p0, f32x16& p1, float alpha, float& l_reg, bf16x8& pa0, bf16x8& pa1, bf16x8& pa2, bf16x8& pa3) {
;   for (int r = 0; r < 16; ++r) p1[r] = __builtin_amdgcn_exp2f(p1[r]);
;   float ps = 0; for (int r = 0; r < 16; ++r) ps += p0[r]; for (int r = 0; r < 16; ++r) ps += p1[r];
;   { auto rr = __builtin_amdgcn_permlane32_swap(__float_as_uint(ps), __float_as_uint(ps), false, false);
;     ps = __uint_as_float(rr[0]) + __uint_as_float(rr[1]); }
;   l_reg = l_reg * alpha + ps;
;     ...
;   PK4(p0, 0, pa0); PK4(p0, 8, pa1); PK4(p1, 0, pa2); PK4(p1, 8, pa3);
;     ...
; }
; __device__ __forceinline__ void qkt(f32x16& p0, f32x16& p1, const bf16* Ks, const bf16x8* qr, int r32, int hi) {
;   p0 = f32x16{}; p1 = f32x16{};
;   for (int d0 = 0; d0 < 8; ++d0) { int cb = (d0 * 16 + hi * 8) * 2;
;     bf16x8 b0 = *reinterpret_cast<const bf16x8*>((const char*)Ks + KSWZ(r32, cb));
;     bf16x8 b1 = *reinterpret_cast<const bf16x8*>((const char*)Ks + KSWZ(32 + r32, cb));
;     p0 = __builtin_amdgcn_mfma_f32_32x32x16_bf16(b0, qr[d0], p0, 0, 0, 0);
;     p1 = __builtin_amdgcn_mfma_f32_32x32x16_bf16(b1, qr[d0], p1, 0, 0, 0); }
; }
; __device__ __forceinline__ int v_st(int k, int c) { const int kk = (k & ~0xC) | ((k & 4) << 1) | ((k & 8) >> 1); return ((kk >> 3) * 4 + (c >> 5)) * 512 + ((kk & 7) * 32 + (c & 31)) * 2; }
; __device__ __forceinline__ int v_rd_base(int lane) { return ((lane & 3) << 3) | (((lane >> 2) & 3) << 6) | (((lane >> 4) & 1) << 5) | (((lane >> 5) & 1) << 8); }
; template <int OFF> __device__ __forceinline__ s16x4 tr_read(int vb) {
;   s16x4 r; asm volatile("ds_read_b64_tr_b16 %0, %1 offset:%2" : "=&v"(r) : "v"(vb), "i"(OFF) : "memory"); return r;
; }
; template <int D0> __device__ __forceinline__ void pv_one(f32x16& od, int vb, bf16x8 pa0, bf16x8 pa1, bf16x8 pa2, bf16x8 pa3) {
;   const s16x4 l0 = tr_read<v_rd_off(D0, 0, 0)>(vb), h0 = tr_read<v_rd_off(D0, 0, 1)>(vb), l1 = tr_read<v_rd_off(D0, 1, 0)>(vb), h1 = tr_read<v_rd_off(D0, 1, 1)>(vb);
	v_mfma_f32_32x32x16_bf16 v[34:49], v[106:109], v[34:37], 0
	v_mul_f32_e32 v176, 0xbe0293ee, v218
	v_fma_f32 v96, v80, s12, v176
	v_fma_f32 v97, v81, s12, v176
	v_fma_f32 v94, v78, s12, v176
	v_fma_f32 v95, v79, s12, v176
	v_fma_f32 v92, v76, s12, v176
	v_fma_f32 v93, v77, s12, v176
	v_fma_f32 v90, v74, s12, v176
	v_fma_f32 v91, v75, s12, v176
	v_fma_f32 v88, v72, s12, v176
	v_fma_f32 v89, v73, s12, v176
	v_fma_f32 v86, v70, s12, v176
	v_fma_f32 v87, v71, s12, v176
	v_mfma_f32_32x32x16_bf16 v[34:49], v[102:105], v[164:167], v[34:49]
	v_fma_f32 v84, v68, s12, v176
	v_fma_f32 v85, v69, s12, v176
	v_fma_f32 v82, v66, s12, v176
	v_fma_f32 v83, v67, s12, v176
	v_fma_f32 v80, v64, s12, v176
	v_fma_f32 v81, v65, s12, v176
	v_fma_f32 v78, v62, s12, v176
	v_fma_f32 v79, v63, s12, v176
	v_fma_f32 v76, v60, s12, v176
	v_fma_f32 v77, v61, s12, v176
	v_fma_f32 v74, v58, s12, v176
	v_fma_f32 v75, v59, s12, v176
	v_fma_f32 v72, v56, s12, v176
	v_fma_f32 v73, v57, s12, v176
	v_mfma_f32_32x32x16_bf16 v[34:49], v[110:113], v[168:171], v[34:49]
	v_fma_f32 v70, v54, s12, v176
	v_fma_f32 v71, v55, s12, v176
	v_fma_f32 v68, v52, s12, v176
	v_fma_f32 v69, v53, s12, v176
	v_fma_f32 v66, v50, s12, v176
	v_fma_f32 v67, v51, s12, v176
	ds_read_b64_tr_b16 v[50:51], v201 offset:0x600
	ds_read_b64_tr_b16 v[52:53], v201 offset:0xe00
	ds_read_b64_tr_b16 v[164:165], v201 offset:0x1600
	ds_read_b64_tr_b16 v[166:167], v201 offset:0x1e00
	v_mfma_f32_32x32x16_bf16 v[34:49], v[98:101], v[172:175], v[34:49]
	ds_read_b64_tr_b16 v[168:169], v201 offset:0x2600
	ds_read_b64_tr_b16 v[170:171], v201 offset:0x2e00
	ds_read_b64_tr_b16 v[180:181], v201 offset:0x3600
	ds_read_b64_tr_b16 v[182:183], v201 offset:0x3e00
	s_waitcnt lgkmcnt(0)
	v_mfma_f32_32x32x16_bf16 v[50:65], v[106:109], v[50:53], 0
	v_exp_f32_e32 v82, v82
	v_exp_f32_e32 v83, v83
	v_exp_f32_e32 v84, v84
	v_exp_f32_e32 v85, v85
	v_exp_f32_e32 v86, v86
	v_exp_f32_e32 v87, v87
	v_exp_f32_e32 v88, v88
	v_mfma_f32_32x32x16_bf16 v[50:65], v[102:105], v[164:167], v[50:65]
	v_exp_f32_e32 v89, v89
	v_exp_f32_e32 v90, v90
	v_exp_f32_e32 v91, v91
	v_exp_f32_e32 v92, v92
	v_exp_f32_e32 v93, v93
	v_exp_f32_e32 v94, v94
	v_exp_f32_e32 v95, v95
	v_mfma_f32_32x32x16_bf16 v[50:65], v[110:113], v[168:171], v[50:65]
	v_exp_f32_e32 v96, v96
	v_exp_f32_e32 v97, v97
	v_mfma_f32_32x32x16_bf16 v[50:65], v[98:101], v[180:183], v[50:65]
	s_barrier
	s_waitcnt vmcnt(0)
	v_cmp_gt_f32_e32 vcc, 1.0, v200
	s_waitcnt vmcnt(3)
	ds_write_b128 v216, v[114:117]
	s_waitcnt vmcnt(2)
	ds_write_b128 v217, v[118:121]
	s_waitcnt vmcnt(1)
	ds_write_b128 v214, v[122:125] offset:32768
	s_waitcnt vmcnt(0)
	ds_write_b128 v215, v[126:129] offset:32768
	s_cbranch_vccz .LBB0_296
	s_and_saveexec_b64 s[20:21], s[4:5]
	ds_write_b32 v197, v200 offset:128
	s_or_b64 exec, exec, s[20:21]
	s_waitcnt lgkmcnt(0)
	v_add_u32_e32 v110, s59, v194
	ds_read_b128 v[98:101], v110 offset:224
	ds_read_b128 v[102:105], v110 offset:192
	ds_read_b128 v[106:109], v110 offset:160
	ds_read_b128 v[110:113], v110 offset:128
	s_waitcnt lgkmcnt(3)
	v_pk_mul_f32 v[14:15], v[14:15], v[98:99]
	s_waitcnt lgkmcnt(2)
	v_pk_mul_f32 v[10:11], v[10:11], v[102:103]
	s_waitcnt lgkmcnt(1)
	v_pk_mul_f32 v[6:7], v[6:7], v[106:107]
	v_pk_mul_f32 v[16:17], v[16:17], v[100:101]
	v_pk_mul_f32 v[12:13], v[12:13], v[104:105]
	v_pk_mul_f32 v[8:9], v[8:9], v[108:109]
	s_waitcnt lgkmcnt(0)
	v_pk_mul_f32 v[4:5], v[4:5], v[112:113]
	v_pk_mul_f32 v[2:3], v[2:3], v[110:111]
	v_pk_mul_f32 v[30:31], v[30:31], v[98:99]
	v_pk_mul_f32 v[26:27], v[26:27], v[102:103]
	v_pk_mul_f32 v[22:23], v[22:23], v[106:107]
	v_pk_mul_f32 v[32:33], v[32:33], v[100:101]
	v_pk_mul_f32 v[28:29], v[28:29], v[104:105]
	v_pk_mul_f32 v[24:25], v[24:25], v[108:109]
	v_pk_mul_f32 v[20:21], v[20:21], v[112:113]
	v_pk_mul_f32 v[18:19], v[18:19], v[110:111]
	v_pk_mul_f32 v[46:47], v[46:47], v[98:99]
	v_pk_mul_f32 v[42:43], v[42:43], v[102:103]
	v_pk_mul_f32 v[38:39], v[38:39], v[106:107]
	v_pk_mul_f32 v[48:49], v[48:49], v[100:101]
	v_pk_mul_f32 v[44:45], v[44:45], v[104:105]
	v_pk_mul_f32 v[40:41], v[40:41], v[108:109]
	v_pk_mul_f32 v[36:37], v[36:37], v[112:113]
	v_pk_mul_f32 v[34:35], v[34:35], v[110:111]
	v_pk_mul_f32 v[62:63], v[62:63], v[98:99]
	v_pk_mul_f32 v[58:59], v[58:59], v[102:103]
	v_pk_mul_f32 v[54:55], v[54:55], v[106:107]
	v_pk_mul_f32 v[64:65], v[64:65], v[100:101]
	v_pk_mul_f32 v[60:61], v[60:61], v[104:105]
	v_pk_mul_f32 v[56:57], v[56:57], v[108:109]
	v_pk_mul_f32 v[52:53], v[52:53], v[112:113]
	v_pk_mul_f32 v[50:51], v[50:51], v[110:111]
; #define SBAR() __builtin_amdgcn_sched_barrier(0)
; #define SLOAD(i, k0) do { const long to_ = (long)(k0) * ldk * 2; const char* vt_ = (const char*)Vh + to_; const char* kt_ = (const char*)Kh + to_; \
;     sr_[i].vs0 = *(const bf16x8*)(vt_ + toff); sr_[i].vs1 = *(const bf16x8*)(vt_ + h32 + toff); \
;     sr_[i].ks0 = *(const bf16x8*)(kt_ + toff); sr_[i].ks1 = *(const bf16x8*)(kt_ + h32 + toff); } while (0)
; #define RESC(a) do { if (__any((a) < 1.f)) { if (hi == 0) al_l[r32] = (a); asm volatile("s_waitcnt lgkmcnt(0)" ::: "memory"); \
;     for (int d = 0; d < 4; ++d) for (int r = 0; r < 16; ++r) o[d][r] *= al_l[crow(r, hi)]; } } while (0)
; __device__ __forceinline__ void finishSM(f32x16& p0, f32x16& p1, float alpha, float& l_reg, bf16x8& pa0, bf16x8& pa1, bf16x8& pa2, bf16x8& pa3) {
;   for (int r = 0; r < 16; ++r) p1[r] = __builtin_amdgcn_exp2f(p1[r]);
;   float ps = 0; for (int r = 0; r < 16; ++r) ps += p0[r]; for (int r = 0; r < 16; ++r) ps += p1[r];
;   { auto rr = __builtin_amdgcn_permlane32_swap(__float_as_uint(ps), __float_as_uint(ps), false, false);
;     ps = __uint_as_float(rr[0]) + __uint_as_float(rr[1]); }
;   l_reg = l_reg * alpha + ps;
;     ...
;   PK4(p0, 0, pa0); PK4(p0, 8, pa1); PK4(p1, 0, pa2); PK4(p1, 8, pa3);
;     ...
; }
; __device__ __forceinline__ void qkt(f32x16& p0, f32x16& p1, const bf16* Ks, const bf16x8* qr, int r32, int hi) {
;   p0 = f32x16{}; p1 = f32x16{};
;   for (int d0 = 0; d0 < 8; ++d0) { int cb = (d0 * 16 + hi * 8) * 2;
;     bf16x8 b0 = *reinterpret_cast<const bf16x8*>((const char*)Ks + KSWZ(r32, cb));
;     bf16x8 b1 = *reinterpret_cast<const bf16x8*>((const char*)Ks + KSWZ(32 + r32, cb));
;     p0 = __builtin_amdgcn_mfma_f32_32x32x16_bf16(b0, qr[d0], p0, 0, 0, 0);
;     p1 = __builtin_amdgcn_mfma_f32_32x32x16_bf16(b1, qr[d0], p1, 0, 0, 0); }
; }
; template <int MODE, int QMODE> ...
;     ...
;     RESC(alB); __syncthreads();
;     SBAR(); qkt(pA0, pA1, K_lds, qr, r32, hi);
;     finishSM(pB0, pB1, alB, l_reg, pa0, pa1, pa2, pa3); SBAR();
;     if (SDEPTH == 1 || j + 3 < NT) SLOAD(SE, (j + 1 + SDEPTH) * KVBLK); SBAR();
.LBB0_296:
	v_sub_f32_e32 v98, 0xf149f2ca, v163
	v_mul_f32_e32 v98, 0x3e0293ee, v98
	s_ashr_i32 s19, s18, 31
	v_exp_f32_e32 v202, v98
	s_cmp_lg_u32 0, -1
	s_cselect_b32 s20, 0, 0
	s_addk_i32 s20, 0x4000
	v_add_u32_e32 v208, s20, v162
	s_waitcnt lgkmcnt(0)
	s_barrier
	ds_read_b128 v[98:101], v203 offset:32768
	ds_read_b128 v[102:105], v203 offset:40960
	ds_read_b128 v[162:165], v204 offset:32768
	ds_read_b128 v[166:169], v204 offset:40960
	ds_read_b128 v[170:173], v205 offset:32768
	ds_read_b128 v[174:177], v205 offset:40960
	v_exp_f32_e32 v66, v66
	v_exp_f32_e32 v67, v67
	s_waitcnt lgkmcnt(5)
	v_mfma_f32_32x32x16_bf16 v[114:129], v[98:101], v[158:161], 0
	v_exp_f32_e32 v68, v68
	v_exp_f32_e32 v69, v69
	v_exp_f32_e32 v70, v70
	v_exp_f32_e32 v71, v71
	v_exp_f32_e32 v72, v72
	v_exp_f32_e32 v73, v73
	v_exp_f32_e32 v74, v74
	s_waitcnt lgkmcnt(4)
	v_mfma_f32_32x32x16_bf16 v[98:113], v[102:105], v[158:161], 0
	v_exp_f32_e32 v75, v75
	v_exp_f32_e32 v76, v76
	v_exp_f32_e32 v77, v77
	v_exp_f32_e32 v78, v78
	v_exp_f32_e32 v79, v79
	v_exp_f32_e32 v80, v80
	v_exp_f32_e32 v81, v81
	s_waitcnt lgkmcnt(2)
	v_mfma_f32_32x32x16_bf16 v[98:113], v[166:169], v[154:157], v[98:113]
	v_add_f32_e32 v166, 0, v82
	v_add_f32_e32 v166, v83, v166
	v_add_f32_e32 v166, v84, v166
	v_mfma_f32_32x32x16_bf16 v[114:129], v[162:165], v[154:157], v[114:129]
	ds_read_b128 v[162:165], v206 offset:32768
	ds_read_b128 v[180:183], v206 offset:40960
	ds_read_b128 v[188:191], v207 offset:32768
	ds_read_b128 v[220:223], v207 offset:40960
	ds_read_b128 v[224:227], v209 offset:32768
	ds_read_b128 v[228:231], v209 offset:40960
	ds_read_b128 v[232:235], v211 offset:32768
	ds_read_b128 v[236:239], v211 offset:40960
	ds_read_b128 v[240:243], v210 offset:32768
	ds_read_b128 v[244:247], v210 offset:40960
	s_waitcnt lgkmcnt(10)
	v_mfma_f32_32x32x16_bf16 v[98:113], v[174:177], v[150:153], v[98:113]
	v_mfma_f32_32x32x16_bf16 v[114:129], v[170:173], v[150:153], v[114:129]
	v_cvt_pk_bf16_f32 v170, v82, v83
	v_cvt_pk_bf16_f32 v171, v84, v85
	v_cvt_pk_bf16_f32 v172, v86, v87
	v_cvt_pk_bf16_f32 v173, v88, v89
	s_nop 0
	v_permlane32_swap_b32_e32 v170, v172
	s_waitcnt lgkmcnt(8)
	v_mfma_f32_32x32x16_bf16 v[98:113], v[180:183], v[146:149], v[98:113]
	v_permlane32_swap_b32_e32 v171, v173
	v_mfma_f32_32x32x16_bf16 v[114:129], v[162:165], v[146:149], v[114:129]
	v_add_f32_e32 v162, v85, v166
	v_add_f32_e32 v162, v86, v162
	v_add_f32_e32 v162, v87, v162
	v_add_f32_e32 v162, v88, v162
	v_add_f32_e32 v162, v89, v162
	v_add_f32_e32 v162, v90, v162
	v_add_f32_e32 v162, v91, v162
	s_waitcnt lgkmcnt(6)
	v_mfma_f32_32x32x16_bf16 v[98:113], v[220:223], v[142:145], v[98:113]
	v_add_f32_e32 v162, v92, v162
	v_add_f32_e32 v162, v93, v162
	v_add_f32_e32 v162, v94, v162
	v_add_f32_e32 v162, v95, v162
	v_add_f32_e32 v162, v96, v162
	v_add_f32_e32 v162, v97, v162
	v_add_f32_e32 v162, v66, v162
	v_mfma_f32_32x32x16_bf16 v[114:129], v[188:191], v[142:145], v[114:129]
	v_add_f32_e32 v162, v67, v162
	v_add_f32_e32 v162, v68, v162
	v_add_f32_e32 v162, v69, v162
	v_add_f32_e32 v162, v70, v162
	v_add_f32_e32 v162, v71, v162
	v_add_f32_e32 v162, v72, v162
	v_add_f32_e32 v162, v73, v162
	s_waitcnt lgkmcnt(4)
	v_mfma_f32_32x32x16_bf16 v[98:113], v[228:231], v[138:141], v[98:113]
	v_add_f32_e32 v162, v74, v162
	v_add_f32_e32 v162, v75, v162
	v_add_f32_e32 v162, v76, v162
	v_add_f32_e32 v162, v77, v162
	v_add_f32_e32 v162, v78, v162
	v_add_f32_e32 v162, v79, v162
	v_add_f32_e32 v162, v80, v162
	v_mfma_f32_32x32x16_bf16 v[114:129], v[224:227], v[138:141], v[114:129]
	v_add_f32_e32 v212, v81, v162
	v_mov_b32_e32 v213, v212
	s_nop 1
	v_permlane32_swap_b32_e32 v212, v213
	v_cvt_pk_bf16_f32 v166, v90, v91
	v_cvt_pk_bf16_f32 v167, v92, v93
	v_cvt_pk_bf16_f32 v168, v94, v95
	s_waitcnt lgkmcnt(2)
	v_mfma_f32_32x32x16_bf16 v[98:113], v[236:239], v[134:137], v[98:113]
	v_cvt_pk_bf16_f32 v169, v96, v97
	v_cvt_pk_bf16_f32 v174, v66, v67
	v_cvt_pk_bf16_f32 v175, v68, v69
	v_cvt_pk_bf16_f32 v176, v70, v71
	v_cvt_pk_bf16_f32 v177, v72, v73
	v_cvt_pk_bf16_f32 v162, v74, v75
	v_cvt_pk_bf16_f32 v163, v76, v77
	v_mfma_f32_32x32x16_bf16 v[114:129], v[232:235], v[134:137], v[114:129]
	v_cvt_pk_bf16_f32 v164, v78, v79
	v_cvt_pk_bf16_f32 v165, v80, v81
	v_permlane32_swap_b32_e32 v166, v168
	v_permlane32_swap_b32_e32 v167, v169
	v_permlane32_swap_b32_e32 v174, v176
	s_waitcnt lgkmcnt(0)
	v_mfma_f32_32x32x16_bf16 v[98:113], v[244:247], v[130:133], v[98:113]
	v_permlane32_swap_b32_e32 v175, v177
	v_permlane32_swap_b32_e32 v162, v164
	v_permlane32_swap_b32_e32 v163, v165
	v_mfma_f32_32x32x16_bf16 v[114:129], v[240:243], v[130:133], v[114:129]
	v_add_co_u32_e32 v66, vcc, s30, v178
	s_nop 1
	v_addc_co_u32_e32 v67, vcc, 0, v179, vcc
	v_add_co_u32_e32 v68, vcc, s31, v178
	s_nop 1
	v_addc_co_u32_e32 v69, vcc, 0, v179, vcc
	global_load_dwordx4 v[178:181], v[66:67], off
	global_load_dwordx4 v[182:185], v[68:69], off
	v_add_co_u32_e32 v66, vcc, s30, v186
	s_nop 1
	v_addc_co_u32_e32 v67, vcc, 0, v187, vcc
	v_add_co_u32_e32 v68, vcc, s31, v186
	s_nop 1
	v_addc_co_u32_e32 v69, vcc, 0, v187, vcc
	global_load_dwordx4 v[186:189], v[66:67], off
	global_load_dwordx4 v[190:193], v[68:69], off
	ds_read_b64_tr_b16 v[66:67], v208 offset:0
	ds_read_b64_tr_b16 v[68:69], v208 offset:0x800
	ds_read_b64_tr_b16 v[70:71], v208 offset:0x1000
	ds_read_b64_tr_b16 v[72:73], v208 offset:0x1800
	ds_read_b64_tr_b16 v[74:75], v208 offset:0x2000
	ds_read_b64_tr_b16 v[76:77], v208 offset:0x2800
	ds_read_b64_tr_b16 v[78:79], v208 offset:0x3000
	ds_read_b64_tr_b16 v[80:81], v208 offset:0x3800
	s_waitcnt lgkmcnt(0)
; __device__ __forceinline__ void psm_decide(float pmax, const f32x16& p1, float& m_reg, float& mn, float& alpha) {
;   constexpr float C = SCALE * 1.4426950408889634f;
;   for (int r = 0; r < 16; ++r) pmax = fmaxf(pmax, p1[r]);
;   { auto rr = __builtin_amdgcn_permlane32_swap(__float_as_uint(pmax), __float_as_uint(pmax), false, false);
;     pmax = fmaxf(__uint_as_float(rr[0]), __uint_as_float(rr[1])); }
;   if (__builtin_expect(__all(pmax - m_reg <= THR / SCALE), 1)) { mn = m_reg; alpha = 1.f; }
;   else { mn = fmaxf(m_reg, pmax); alpha = __builtin_amdgcn_exp2f((m_reg - mn) * C); m_reg = mn; }
; }
; __device__ __forceinline__ void psm_scale(f32x16& p0, f32x16& p1, float mn) {
;   constexpr float C = SCALE * 1.4426950408889634f; const float mnC = -mn * C;
;   for (int r = 0; r < 16; ++r) p0[r] = fmaf(p0[r], C, mnC); for (int r = 0; r < 16; ++r) p1[r] = fmaf(p1[r], C, mnC);
; }
; __device__ __forceinline__ void finishSM(f32x16& p0, f32x16& p1, float alpha, float& l_reg, bf16x8& pa0, bf16x8& pa1, bf16x8& pa2, bf16x8& pa3) {
;   for (int r = 0; r < 16; ++r) p1[r] = __builtin_amdgcn_exp2f(p1[r]);
;   float ps = 0; for (int r = 0; r < 16; ++r) ps += p0[r]; for (int r = 0; r < 16; ++r) ps += p1[r];
;   { auto rr = __builtin_amdgcn_permlane32_swap(__float_as_uint(ps), __float_as_uint(ps), false, false);
;     ps = __uint_as_float(rr[0]) + __uint_as_float(rr[1]); }
;   l_reg = l_reg * alpha + ps;
;     ...
;   PK4(p0, 0, pa0); PK4(p0, 8, pa1); PK4(p1, 0, pa2); PK4(p1, 8, pa3);
;     ...
; }
; __device__ __forceinline__ void qkt(f32x16& p0, f32x16& p1, const bf16* Ks, const bf16x8* qr, int r32, int hi) {
;   p0 = f32x16{}; p1 = f32x16{};
;   for (int d0 = 0; d0 < 8; ++d0) { int cb = (d0 * 16 + hi * 8) * 2;
;     bf16x8 b0 = *reinterpret_cast<const bf16x8*>((const char*)Ks + KSWZ(r32, cb));
;     bf16x8 b1 = *reinterpret_cast<const bf16x8*>((const char*)Ks + KSWZ(32 + r32, cb));
;     p0 = __builtin_amdgcn_mfma_f32_32x32x16_bf16(b0, qr[d0], p0, 0, 0, 0);
;     p1 = __builtin_amdgcn_mfma_f32_32x32x16_bf16(b1, qr[d0], p1, 0, 0, 0); }
; }
; __device__ __forceinline__ int v_st(int k, int c) { const int kk = (k & ~0xC) | ((k & 4) << 1) | ((k & 8) >> 1); return ((kk >> 3) * 4 + (c >> 5)) * 512 + ((kk & 7) * 32 + (c & 31)) * 2; }
; __device__ __forceinline__ int v_rd_base(int lane) { return ((lane & 3) << 3) | (((lane >> 2) & 3) << 6) | (((lane >> 4) & 1) << 5) | (((lane >> 5) & 1) << 8); }
	s_nop 0
	v_mfma_f32_32x32x16_bf16 v[2:17], v[170:173], v[66:69], v[2:17]
	v_max_f32_e32 v66, v115, v115
	v_max_f32_e32 v67, v114, v114
	v_max_f32_e32 v66, v67, v66
	v_max3_f32 v66, v66, v116, v117
	v_max3_f32 v66, v66, v118, v119
	v_max3_f32 v66, v66, v120, v121
	v_max3_f32 v66, v66, v122, v123
	v_mfma_f32_32x32x16_bf16 v[2:17], v[166:169], v[70:73], v[2:17]
	v_max3_f32 v66, v66, v124, v125
	v_max3_f32 v68, v66, v126, v127
	ds_read_b64_tr_b16 v[66:67], v208 offset:0x200
	v_max3_f32 v86, v68, v128, v129
	ds_read_b64_tr_b16 v[68:69], v208 offset:0xa00
	ds_read_b64_tr_b16 v[70:71], v208 offset:0x1200
	ds_read_b64_tr_b16 v[72:73], v208 offset:0x1a00
	v_mfma_f32_32x32x16_bf16 v[2:17], v[174:177], v[74:77], v[2:17]
	ds_read_b64_tr_b16 v[74:75], v208 offset:0x2200
	ds_read_b64_tr_b16 v[76:77], v208 offset:0x2a00
	ds_read_b64_tr_b16 v[82:83], v208 offset:0x3200
	ds_read_b64_tr_b16 v[84:85], v208 offset:0x3a00
	s_waitcnt lgkmcnt(0)
	v_mfma_f32_32x32x16_bf16 v[2:17], v[162:165], v[78:81], v[2:17]
	v_max3_f32 v78, v86, v98, v99
	v_mfma_f32_32x32x16_bf16 v[18:33], v[170:173], v[66:69], v[18:33]
	v_max3_f32 v78, v78, v100, v101
	v_max3_f32 v78, v78, v102, v103
	v_max3_f32 v78, v78, v104, v105
	v_max3_f32 v78, v78, v106, v107
	v_max3_f32 v78, v78, v108, v109
	v_max3_f32 v66, v78, v110, v111
	v_max3_f32 v66, v66, v112, v113
	v_mov_b32_e32 v67, v66
	v_mfma_f32_32x32x16_bf16 v[18:33], v[166:169], v[70:73], v[18:33]
	s_nop 0
	v_permlane32_swap_b32_e32 v66, v67
	v_max_f32_e32 v67, v67, v67
	v_max_f32_e32 v66, v66, v66
	v_max_f32_e32 v66, v66, v67
	v_sub_f32_e32 v67, v66, v218
	v_cmp_ge_f32_e32 vcc, s25, v67
	v_max_f32_e32 v67, v218, v218
	v_max_f32_e32 v66, v67, v66
	v_sub_f32_e32 v67, v218, v66
	v_mul_f32_e32 v67, 0x3e0293ee, v67
	v_mfma_f32_32x32x16_bf16 v[18:33], v[174:177], v[74:77], v[18:33]
	v_exp_f32_e32 v67, v67
	s_cmp_eq_u64 vcc, exec
	s_cselect_b64 vcc, -1, 0
	v_cndmask_b32_e32 v219, v66, v218, vcc
	v_cndmask_b32_e64 v218, v67, 1.0, vcc
	ds_read_b64_tr_b16 v[66:67], v208 offset:0x400
	ds_read_b64_tr_b16 v[68:69], v208 offset:0xc00
	ds_read_b64_tr_b16 v[70:71], v208 offset:0x1400
	v_mfma_f32_32x32x16_bf16 v[18:33], v[162:165], v[82:85], v[18:33]
	ds_read_b64_tr_b16 v[72:73], v208 offset:0x1c00
	ds_read_b64_tr_b16 v[220:221], v208 offset:0x2400
	ds_read_b64_tr_b16 v[222:223], v208 offset:0x2c00
	ds_read_b64_tr_b16 v[224:225], v208 offset:0x3400
	ds_read_b64_tr_b16 v[226:227], v208 offset:0x3c00
	s_waitcnt lgkmcnt(0)
	v_mfma_f32_32x32x16_bf16 v[34:49], v[170:173], v[66:69], v[34:49]
	v_mul_f32_e32 v228, 0xbe0293ee, v219
	v_fma_f32 v96, v128, s12, v228
	v_fma_f32 v97, v129, s12, v228
	v_fma_f32 v94, v126, s12, v228
	v_fma_f32 v95, v127, s12, v228
	v_fma_f32 v92, v124, s12, v228
	v_fma_f32 v93, v125, s12, v228
	v_fma_f32 v90, v122, s12, v228
	v_fma_f32 v91, v123, s12, v228
	v_fma_f32 v88, v120, s12, v228
	v_fma_f32 v89, v121, s12, v228
	v_fma_f32 v86, v118, s12, v228
	v_fma_f32 v87, v119, s12, v228
	v_mfma_f32_32x32x16_bf16 v[34:49], v[166:169], v[70:73], v[34:49]
	v_fma_f32 v84, v116, s12, v228
	v_fma_f32 v85, v117, s12, v228
	v_fma_f32 v82, v114, s12, v228
	v_fma_f32 v83, v115, s12, v228
	v_fma_f32 v80, v112, s12, v228
	v_fma_f32 v81, v113, s12, v228
	v_fma_f32 v78, v110, s12, v228
	v_fma_f32 v79, v111, s12, v228
	v_fma_f32 v76, v108, s12, v228
	v_fma_f32 v77, v109, s12, v228
	v_fma_f32 v74, v106, s12, v228
	v_fma_f32 v75, v107, s12, v228
	v_fma_f32 v72, v104, s12, v228
	v_fma_f32 v73, v105, s12, v228
	v_mfma_f32_32x32x16_bf16 v[34:49], v[174:177], v[220:223], v[34:49]
	v_fma_f32 v70, v102, s12, v228
	v_fma_f32 v71, v103, s12, v228
	v_fma_f32 v68, v100, s12, v228
	v_fma_f32 v69, v101, s12, v228
	v_fma_f32 v66, v98, s12, v228
	v_fma_f32 v67, v99, s12, v228
	ds_read_b64_tr_b16 v[98:99], v208 offset:0x600
	ds_read_b64_tr_b16 v[100:101], v208 offset:0xe00
	ds_read_b64_tr_b16 v[102:103], v208 offset:0x1600
	ds_read_b64_tr_b16 v[104:105], v208 offset:0x1e00
	v_mfma_f32_32x32x16_bf16 v[34:49], v[162:165], v[224:227], v[34:49]
	ds_read_b64_tr_b16 v[108:109], v208 offset:0x2600
	ds_read_b64_tr_b16 v[110:111], v208 offset:0x2e00
	ds_read_b64_tr_b16 v[114:115], v208 offset:0x3600
	ds_read_b64_tr_b16 v[116:117], v208 offset:0x3e00
	s_waitcnt lgkmcnt(0)
	v_mfma_f32_32x32x16_bf16 v[50:65], v[170:173], v[98:101], v[50:65]
	v_exp_f32_e32 v98, v82
	v_exp_f32_e32 v99, v83
	v_exp_f32_e32 v100, v84
	v_exp_f32_e32 v101, v85
	v_exp_f32_e32 v106, v90
	v_exp_f32_e32 v107, v91
	v_exp_f32_e32 v112, v96
	v_mfma_f32_32x32x16_bf16 v[50:65], v[166:169], v[102:105], v[50:65]
	v_exp_f32_e32 v102, v86
	v_exp_f32_e32 v103, v87
	v_exp_f32_e32 v104, v88
	v_exp_f32_e32 v105, v89
	v_exp_f32_e32 v113, v97
	v_mfma_f32_32x32x16_bf16 v[50:65], v[174:177], v[108:111], v[50:65]
	v_exp_f32_e32 v108, v92
	v_exp_f32_e32 v109, v93
	v_exp_f32_e32 v110, v94
	v_exp_f32_e32 v111, v95
	v_mfma_f32_32x32x16_bf16 v[50:65], v[162:165], v[114:117], v[50:65]
	s_barrier
	s_waitcnt vmcnt(0)
	v_cmp_gt_f32_e32 vcc, 1.0, v218
	s_waitcnt vmcnt(3)
	ds_write_b128 v216, v[178:181] offset:16384
	s_waitcnt vmcnt(2)
	ds_write_b128 v217, v[182:185] offset:16384
	s_waitcnt vmcnt(1)
	ds_write_b128 v214, v[186:189] offset:49152
	s_waitcnt vmcnt(0)
	ds_write_b128 v215, v[190:193] offset:49152
	s_cbranch_vccz .LBB0_300
	s_and_saveexec_b64 s[20:21], s[4:5]
	ds_write_b32 v197, v218 offset:128
	s_or_b64 exec, exec, s[20:21]
	s_waitcnt lgkmcnt(0)
	v_add_u32_e32 v94, s59, v194
	ds_read_b128 v[82:85], v94 offset:224
	ds_read_b128 v[86:89], v94 offset:192
	ds_read_b128 v[90:93], v94 offset:160
	ds_read_b128 v[94:97], v94 offset:128
	s_waitcnt lgkmcnt(3)
	v_pk_mul_f32 v[14:15], v[14:15], v[82:83]
	s_waitcnt lgkmcnt(2)
	v_pk_mul_f32 v[10:11], v[10:11], v[86:87]
	s_waitcnt lgkmcnt(1)
	v_pk_mul_f32 v[6:7], v[6:7], v[90:91]
	v_pk_mul_f32 v[16:17], v[16:17], v[84:85]
	v_pk_mul_f32 v[12:13], v[12:13], v[88:89]
	v_pk_mul_f32 v[8:9], v[8:9], v[92:93]
	s_waitcnt lgkmcnt(0)
	v_pk_mul_f32 v[4:5], v[4:5], v[96:97]
	v_pk_mul_f32 v[2:3], v[2:3], v[94:95]
	v_pk_mul_f32 v[30:31], v[30:31], v[82:83]
	v_pk_mul_f32 v[26:27], v[26:27], v[86:87]
	v_pk_mul_f32 v[22:23], v[22:23], v[90:91]
	v_pk_mul_f32 v[32:33], v[32:33], v[84:85]
	v_pk_mul_f32 v[28:29], v[28:29], v[88:89]
	v_pk_mul_f32 v[24:25], v[24:25], v[92:93]
	v_pk_mul_f32 v[20:21], v[20:21], v[96:97]
	v_pk_mul_f32 v[18:19], v[18:19], v[94:95]
	v_pk_mul_f32 v[46:47], v[46:47], v[82:83]
	v_pk_mul_f32 v[42:43], v[42:43], v[86:87]
	v_pk_mul_f32 v[38:39], v[38:39], v[90:91]
	v_pk_mul_f32 v[48:49], v[48:49], v[84:85]
	v_pk_mul_f32 v[44:45], v[44:45], v[88:89]
	v_pk_mul_f32 v[40:41], v[40:41], v[92:93]
	v_pk_mul_f32 v[36:37], v[36:37], v[96:97]
	v_pk_mul_f32 v[34:35], v[34:35], v[94:95]
	v_pk_mul_f32 v[62:63], v[62:63], v[82:83]
	v_pk_mul_f32 v[58:59], v[58:59], v[86:87]
	v_pk_mul_f32 v[54:55], v[54:55], v[90:91]
	v_pk_mul_f32 v[64:65], v[64:65], v[84:85]
	v_pk_mul_f32 v[60:61], v[60:61], v[88:89]
	v_pk_mul_f32 v[56:57], v[56:57], v[92:93]
	v_pk_mul_f32 v[52:53], v[52:53], v[96:97]
	v_pk_mul_f32 v[50:51], v[50:51], v[94:95]
; #define SBAR() __builtin_amdgcn_sched_barrier(0)
; __device__ __forceinline__ void finishSM(f32x16& p0, f32x16& p1, float alpha, float& l_reg, bf16x8& pa0, bf16x8& pa1, bf16x8& pa2, bf16x8& pa3) {
;   for (int r = 0; r < 16; ++r) p1[r] = __builtin_amdgcn_exp2f(p1[r]);
;   float ps = 0; for (int r = 0; r < 16; ++r) ps += p0[r]; for (int r = 0; r < 16; ++r) ps += p1[r];
;   { auto rr = __builtin_amdgcn_permlane32_swap(__float_as_uint(ps), __float_as_uint(ps), false, false);
;     ps = __uint_as_float(rr[0]) + __uint_as_float(rr[1]); }
;   l_reg = l_reg * alpha + ps;
;     ...
;   PK4(p0, 0, pa0); PK4(p0, 8, pa1); PK4(p1, 0, pa2); PK4(p1, 8, pa3);
;     ...
; }
; __device__ __forceinline__ void qkt(f32x16& p0, f32x16& p1, const bf16* Ks, const bf16x8* qr, int r32, int hi) {
;   p0 = f32x16{}; p1 = f32x16{};
;   for (int d0 = 0; d0 < 8; ++d0) { int cb = (d0 * 16 + hi * 8) * 2;
;     bf16x8 b0 = *reinterpret_cast<const bf16x8*>((const char*)Ks + KSWZ(r32, cb));
;     bf16x8 b1 = *reinterpret_cast<const bf16x8*>((const char*)Ks + KSWZ(32 + r32, cb));
;     p0 = __builtin_amdgcn_mfma_f32_32x32x16_bf16(b0, qr[d0], p0, 0, 0, 0);
;     p1 = __builtin_amdgcn_mfma_f32_32x32x16_bf16(b1, qr[d0], p1, 0, 0, 0); }
; }
; template <int MODE, int QMODE> ...
;     ...
;   SBAR(); qkt(pB0, pB1, (bf16*)((char*)K_lds + SHM_K), qr, r32, hi);
;   finishSM(pA0, pA1, alA, l_reg, pa0, pa1, pa2, pa3); SBAR();
;   PVSM(vb0, pB0, pB1, (NT - 1) * KVBLK, mnB, alB);
.LBB0_300:
	s_waitcnt lgkmcnt(0)
	s_barrier
	ds_read_b128 v[82:85], v203 offset:49152
	ds_read_b128 v[86:89], v203 offset:57344
	v_exp_f32_e32 v66, v66
	v_exp_f32_e32 v67, v67
	v_exp_f32_e32 v68, v68
	s_waitcnt lgkmcnt(1)
	v_mfma_f32_32x32x16_bf16 v[114:129], v[82:85], v[158:161], 0
	v_exp_f32_e32 v69, v69
	v_exp_f32_e32 v70, v70
	v_exp_f32_e32 v71, v71
	v_exp_f32_e32 v72, v72
	v_exp_f32_e32 v73, v73
	v_exp_f32_e32 v74, v74
	v_exp_f32_e32 v75, v75
	s_waitcnt lgkmcnt(0)
	v_mfma_f32_32x32x16_bf16 v[82:97], v[86:89], v[158:161], 0
	ds_read_b128 v[158:161], v204 offset:49152
	ds_read_b128 v[162:165], v204 offset:57344
	ds_read_b128 v[166:169], v205 offset:49152
	ds_read_b128 v[170:173], v205 offset:57344
	v_exp_f32_e32 v76, v76
	v_exp_f32_e32 v77, v77
	v_exp_f32_e32 v78, v78
	v_exp_f32_e32 v79, v79
	v_exp_f32_e32 v80, v80
	v_exp_f32_e32 v81, v81
	s_waitcnt lgkmcnt(2)
	v_mfma_f32_32x32x16_bf16 v[82:97], v[162:165], v[154:157], v[82:97]
	v_mfma_f32_32x32x16_bf16 v[114:129], v[158:161], v[154:157], v[114:129]
	ds_read_b128 v[158:161], v206 offset:49152
	ds_read_b128 v[174:177], v206 offset:57344
	ds_read_b128 v[178:181], v207 offset:49152
	ds_read_b128 v[182:185], v207 offset:57344
	ds_read_b128 v[186:189], v209 offset:49152
	ds_read_b128 v[190:193], v209 offset:57344
	ds_read_b128 v[204:207], v211 offset:49152
	ds_read_b128 v[214:217], v211 offset:57344
	ds_read_b128 v[154:157], v210 offset:49152
	ds_read_b128 v[162:165], v210 offset:57344
	s_waitcnt lgkmcnt(10)
	v_mfma_f32_32x32x16_bf16 v[82:97], v[170:173], v[150:153], v[82:97]
	v_mfma_f32_32x32x16_bf16 v[114:129], v[166:169], v[150:153], v[114:129]
	v_add_f32_e32 v150, 0, v98
	v_add_f32_e32 v150, v99, v150
	v_add_f32_e32 v150, v100, v150
	v_add_f32_e32 v150, v101, v150
	v_add_f32_e32 v150, v102, v150
	v_add_f32_e32 v150, v103, v150
	v_add_f32_e32 v150, v104, v150
	s_waitcnt lgkmcnt(8)
	v_mfma_f32_32x32x16_bf16 v[82:97], v[174:177], v[146:149], v[82:97]
	v_add_f32_e32 v150, v105, v150
	v_add_f32_e32 v150, v106, v150
	v_add_f32_e32 v150, v107, v150
	v_mfma_f32_32x32x16_bf16 v[114:129], v[158:161], v[146:149], v[114:129]
	v_add_f32_e32 v146, v108, v150
	v_add_f32_e32 v146, v109, v146
	v_add_f32_e32 v146, v110, v146
	v_add_f32_e32 v146, v111, v146
	v_add_f32_e32 v146, v112, v146
	v_add_f32_e32 v146, v113, v146
	v_add_f32_e32 v146, v66, v146
	s_waitcnt lgkmcnt(6)
	v_mfma_f32_32x32x16_bf16 v[82:97], v[182:185], v[142:145], v[82:97]
	v_add_f32_e32 v146, v67, v146
	v_add_f32_e32 v146, v68, v146
	v_add_f32_e32 v146, v69, v146
	v_add_f32_e32 v146, v70, v146
	v_add_f32_e32 v146, v71, v146
	v_add_f32_e32 v146, v72, v146
	v_add_f32_e32 v146, v73, v146
	v_mfma_f32_32x32x16_bf16 v[114:129], v[178:181], v[142:145], v[114:129]
	v_add_f32_e32 v142, v74, v146
	v_add_f32_e32 v142, v75, v142
	v_add_f32_e32 v142, v76, v142
	v_add_f32_e32 v142, v77, v142
	v_add_f32_e32 v142, v78, v142
	v_add_f32_e32 v142, v79, v142
	v_add_f32_e32 v142, v80, v142
	s_waitcnt lgkmcnt(4)
	v_mfma_f32_32x32x16_bf16 v[82:97], v[190:193], v[138:141], v[82:97]
	v_add_f32_e32 v150, v81, v142
	v_mov_b32_e32 v151, v150
	s_nop 1
	v_permlane32_swap_b32_e32 v150, v151
	v_cvt_pk_bf16_f32 v142, v98, v99
	v_cvt_pk_bf16_f32 v143, v100, v101
	v_cvt_pk_bf16_f32 v144, v102, v103
	v_mfma_f32_32x32x16_bf16 v[114:129], v[186:189], v[138:141], v[114:129]
	v_cvt_pk_bf16_f32 v145, v104, v105
	v_cvt_pk_bf16_f32 v138, v106, v107
	v_cvt_pk_bf16_f32 v139, v108, v109
	v_cvt_pk_bf16_f32 v140, v110, v111
	v_cvt_pk_bf16_f32 v141, v112, v113
	v_cvt_pk_bf16_f32 v146, v66, v67
	v_cvt_pk_bf16_f32 v147, v68, v69
	s_waitcnt lgkmcnt(2)
	v_mfma_f32_32x32x16_bf16 v[82:97], v[214:217], v[134:137], v[82:97]
	v_cvt_pk_bf16_f32 v148, v70, v71
	v_cvt_pk_bf16_f32 v149, v72, v73
	v_permlane32_swap_b32_e32 v142, v144
	v_permlane32_swap_b32_e32 v143, v145
	v_permlane32_swap_b32_e32 v138, v140
	v_mfma_f32_32x32x16_bf16 v[114:129], v[204:207], v[134:137], v[114:129]
	v_cvt_pk_bf16_f32 v134, v74, v75
	v_cvt_pk_bf16_f32 v135, v76, v77
	v_cvt_pk_bf16_f32 v136, v78, v79
	v_cvt_pk_bf16_f32 v137, v80, v81
	v_permlane32_swap_b32_e32 v139, v141
	v_permlane32_swap_b32_e32 v146, v148
	s_waitcnt lgkmcnt(0)
	v_mfma_f32_32x32x16_bf16 v[82:97], v[162:165], v[130:133], v[82:97]
	v_permlane32_swap_b32_e32 v147, v149
	v_permlane32_swap_b32_e32 v134, v136
	v_permlane32_swap_b32_e32 v135, v137
	v_mfma_f32_32x32x16_bf16 v[114:129], v[154:157], v[130:133], v[114:129]
	ds_read_b64_tr_b16 v[66:67], v201 offset:0
	ds_read_b64_tr_b16 v[68:69], v201 offset:0x800
	ds_read_b64_tr_b16 v[70:71], v201 offset:0x1000
	ds_read_b64_tr_b16 v[72:73], v201 offset:0x1800
	ds_read_b64_tr_b16 v[74:75], v201 offset:0x2000
	ds_read_b64_tr_b16 v[76:77], v201 offset:0x2800
	ds_read_b64_tr_b16 v[78:79], v201 offset:0x3000
	ds_read_b64_tr_b16 v[80:81], v201 offset:0x3800
	s_waitcnt lgkmcnt(0)
	s_nop 0
	v_mfma_f32_32x32x16_bf16 v[2:17], v[142:145], v[66:69], v[2:17]
	s_nop 9
	v_max_f32_e32 v66, v115, v115
	v_max_f32_e32 v67, v114, v114
	v_max_f32_e32 v66, v67, v66
	v_max3_f32 v66, v66, v116, v117
	v_max3_f32 v66, v66, v118, v119
	v_max3_f32 v66, v66, v120, v121
	v_max3_f32 v66, v66, v122, v123
	v_mfma_f32_32x32x16_bf16 v[2:17], v[138:141], v[70:73], v[2:17]
	v_max3_f32 v66, v66, v124, v125
	v_max3_f32 v68, v66, v126, v127
	ds_read_b64_tr_b16 v[66:67], v201 offset:0x200
	v_max3_f32 v102, v68, v128, v129
	ds_read_b64_tr_b16 v[68:69], v201 offset:0xa00
	ds_read_b64_tr_b16 v[70:71], v201 offset:0x1200
	ds_read_b64_tr_b16 v[72:73], v201 offset:0x1a00
	v_mfma_f32_32x32x16_bf16 v[2:17], v[146:149], v[74:77], v[2:17]
	ds_read_b64_tr_b16 v[74:75], v201 offset:0x2200
	ds_read_b64_tr_b16 v[76:77], v201 offset:0x2a00
	ds_read_b64_tr_b16 v[98:99], v201 offset:0x3200
	ds_read_b64_tr_b16 v[100:101], v201 offset:0x3a00
	s_waitcnt lgkmcnt(0)
; __device__ __forceinline__ void psm_decide(float pmax, const f32x16& p1, float& m_reg, float& mn, float& alpha) {
;   constexpr float C = SCALE * 1.4426950408889634f;
;   for (int r = 0; r < 16; ++r) pmax = fmaxf(pmax, p1[r]);
;   { auto rr = __builtin_amdgcn_permlane32_swap(__float_as_uint(pmax), __float_as_uint(pmax), false, false);
;     pmax = fmaxf(__uint_as_float(rr[0]), __uint_as_float(rr[1])); }
;   if (__builtin_expect(__all(pmax - m_reg <= THR / SCALE), 1)) { mn = m_reg; alpha = 1.f; }
;   else { mn = fmaxf(m_reg, pmax); alpha = __builtin_amdgcn_exp2f((m_reg - mn) * C); m_reg = mn; }
; }
; __device__ __forceinline__ void psm_scale(f32x16& p0, f32x16& p1, float mn) {
;   constexpr float C = SCALE * 1.4426950408889634f; const float mnC = -mn * C;
;   for (int r = 0; r < 16; ++r) p0[r] = fmaf(p0[r], C, mnC); for (int r = 0; r < 16; ++r) p1[r] = fmaf(p1[r], C, mnC);
; }
; __device__ __forceinline__ void finishSM(f32x16& p0, f32x16& p1, float alpha, float& l_reg, bf16x8& pa0, bf16x8& pa1, bf16x8& pa2, bf16x8& pa3) {
;   for (int r = 0; r < 16; ++r) p1[r] = __builtin_amdgcn_exp2f(p1[r]);
;   float ps = 0; for (int r = 0; r < 16; ++r) ps += p0[r]; for (int r = 0; r < 16; ++r) ps += p1[r];
;   { auto rr = __builtin_amdgcn_permlane32_swap(__float_as_uint(ps), __float_as_uint(ps), false, false);
;     ps = __uint_as_float(rr[0]) + __uint_as_float(rr[1]); }
;   l_reg = l_reg * alpha + ps;
;     ...
;   PK4(p0, 0, pa0); PK4(p0, 8, pa1); PK4(p1, 0, pa2); PK4(p1, 8, pa3);
;     ...
; }
; __device__ __forceinline__ void qkt(f32x16& p0, f32x16& p1, const bf16* Ks, const bf16x8* qr, int r32, int hi) {
;   p0 = f32x16{}; p1 = f32x16{};
;   for (int d0 = 0; d0 < 8; ++d0) { int cb = (d0 * 16 + hi * 8) * 2;
;     bf16x8 b0 = *reinterpret_cast<const bf16x8*>((const char*)Ks + KSWZ(r32, cb));
;     bf16x8 b1 = *reinterpret_cast<const bf16x8*>((const char*)Ks + KSWZ(32 + r32, cb));
;     p0 = __builtin_amdgcn_mfma_f32_32x32x16_bf16(b0, qr[d0], p0, 0, 0, 0);
;     p1 = __builtin_amdgcn_mfma_f32_32x32x16_bf16(b1, qr[d0], p1, 0, 0, 0); }
; }
; __device__ __forceinline__ int v_st(int k, int c) { const int kk = (k & ~0xC) | ((k & 4) << 1) | ((k & 8) >> 1); return ((kk >> 3) * 4 + (c >> 5)) * 512 + ((kk & 7) * 32 + (c & 31)) * 2; }
; __device__ __forceinline__ int v_rd_base(int lane) { return ((lane & 3) << 3) | (((lane >> 2) & 3) << 6) | (((lane >> 4) & 1) << 5) | (((lane >> 5) & 1) << 8); }
	v_mfma_f32_32x32x16_bf16 v[2:17], v[134:137], v[78:81], v[2:17]
	v_max3_f32 v78, v102, v82, v83
	v_mfma_f32_32x32x16_bf16 v[18:33], v[142:145], v[66:69], v[18:33]
	v_max3_f32 v78, v78, v84, v85
	v_max3_f32 v78, v78, v86, v87
	v_max3_f32 v78, v78, v88, v89
	v_max3_f32 v78, v78, v90, v91
	v_max3_f32 v78, v78, v92, v93
	v_max3_f32 v66, v78, v94, v95
	v_max3_f32 v66, v66, v96, v97
	v_mov_b32_e32 v67, v66
	v_mfma_f32_32x32x16_bf16 v[18:33], v[138:141], v[70:73], v[18:33]
	s_nop 0
	v_permlane32_swap_b32_e32 v66, v67
	v_max_f32_e32 v67, v67, v67
	v_max_f32_e32 v66, v66, v66
	v_max_f32_e32 v66, v66, v67
	v_sub_f32_e32 v67, v66, v219
	v_cmp_ge_f32_e32 vcc, s25, v67
	v_max_f32_e32 v67, v219, v219
	v_max_f32_e32 v66, v67, v66
	v_sub_f32_e32 v67, v219, v66
	v_mul_f32_e32 v67, 0x3e0293ee, v67
	v_mfma_f32_32x32x16_bf16 v[18:33], v[146:149], v[74:77], v[18:33]
	v_exp_f32_e32 v67, v67
	s_cmp_eq_u64 vcc, exec
	s_cselect_b64 vcc, -1, 0
	v_cndmask_b32_e32 v74, v66, v219, vcc
	v_cndmask_b32_e64 v130, v67, 1.0, vcc
	ds_read_b64_tr_b16 v[66:67], v201 offset:0x400
	ds_read_b64_tr_b16 v[68:69], v201 offset:0xc00
	ds_read_b64_tr_b16 v[70:71], v201 offset:0x1400
	v_mfma_f32_32x32x16_bf16 v[18:33], v[134:137], v[98:101], v[18:33]
	ds_read_b64_tr_b16 v[72:73], v201 offset:0x1c00
	ds_read_b64_tr_b16 v[152:153], v201 offset:0x2400
	ds_read_b64_tr_b16 v[154:155], v201 offset:0x2c00
	ds_read_b64_tr_b16 v[156:157], v201 offset:0x3400
	ds_read_b64_tr_b16 v[158:159], v201 offset:0x3c00
	s_waitcnt lgkmcnt(0)
	v_mfma_f32_32x32x16_bf16 v[34:49], v[142:145], v[66:69], v[34:49]
	v_mul_f32_e32 v132, 0xbe0293ee, v74
	v_fma_f32 v112, v128, s12, v132
	v_fma_f32 v113, v129, s12, v132
	v_fma_f32 v110, v126, s12, v132
	v_fma_f32 v111, v127, s12, v132
	v_fma_f32 v108, v124, s12, v132
	v_fma_f32 v109, v125, s12, v132
	v_fma_f32 v106, v122, s12, v132
	v_fma_f32 v107, v123, s12, v132
	v_fma_f32 v104, v120, s12, v132
	v_fma_f32 v105, v121, s12, v132
	v_fma_f32 v102, v118, s12, v132
	v_fma_f32 v103, v119, s12, v132
	v_mfma_f32_32x32x16_bf16 v[34:49], v[138:141], v[70:73], v[34:49]
	v_fma_f32 v100, v116, s12, v132
	v_fma_f32 v101, v117, s12, v132
	v_fma_f32 v98, v114, s12, v132
	v_fma_f32 v99, v115, s12, v132
	v_fma_f32 v80, v96, s12, v132
	v_fma_f32 v81, v97, s12, v132
	v_fma_f32 v78, v94, s12, v132
	v_fma_f32 v79, v95, s12, v132
	v_fma_f32 v76, v92, s12, v132
	v_fma_f32 v77, v93, s12, v132
	v_fma_f32 v74, v90, s12, v132
	v_fma_f32 v75, v91, s12, v132
	v_fma_f32 v72, v88, s12, v132
	v_fma_f32 v73, v89, s12, v132
	v_mfma_f32_32x32x16_bf16 v[34:49], v[146:149], v[152:155], v[34:49]
	v_fma_f32 v70, v86, s12, v132
	v_fma_f32 v71, v87, s12, v132
	v_fma_f32 v68, v84, s12, v132
	v_fma_f32 v69, v85, s12, v132
	v_fma_f32 v66, v82, s12, v132
	v_fma_f32 v67, v83, s12, v132
	ds_read_b64_tr_b16 v[82:83], v201 offset:0x600
	ds_read_b64_tr_b16 v[84:85], v201 offset:0xe00
	ds_read_b64_tr_b16 v[86:87], v201 offset:0x1600
	ds_read_b64_tr_b16 v[88:89], v201 offset:0x1e00
	v_mfma_f32_32x32x16_bf16 v[34:49], v[134:137], v[156:159], v[34:49]
	ds_read_b64_tr_b16 v[92:93], v201 offset:0x2600
	ds_read_b64_tr_b16 v[94:95], v201 offset:0x2e00
	ds_read_b64_tr_b16 v[114:115], v201 offset:0x3600
	ds_read_b64_tr_b16 v[116:117], v201 offset:0x3e00
	s_waitcnt lgkmcnt(0)
	v_mfma_f32_32x32x16_bf16 v[50:65], v[142:145], v[82:85], v[50:65]
	v_exp_f32_e32 v82, v98
	v_exp_f32_e32 v83, v99
	v_exp_f32_e32 v84, v100
	v_exp_f32_e32 v85, v101
	v_exp_f32_e32 v90, v106
	v_exp_f32_e32 v91, v107
	v_exp_f32_e32 v96, v112
	v_mfma_f32_32x32x16_bf16 v[50:65], v[138:141], v[86:89], v[50:65]
	v_exp_f32_e32 v86, v102
	v_exp_f32_e32 v87, v103
	v_exp_f32_e32 v88, v104
	v_exp_f32_e32 v89, v105
	v_exp_f32_e32 v97, v113
	v_mfma_f32_32x32x16_bf16 v[50:65], v[146:149], v[92:95], v[50:65]
	v_exp_f32_e32 v92, v108
	v_exp_f32_e32 v93, v109
	v_exp_f32_e32 v94, v110
	v_exp_f32_e32 v95, v111
	v_mfma_f32_32x32x16_bf16 v[50:65], v[134:137], v[114:117], v[50:65]
	v_cmp_gt_f32_e32 vcc, 1.0, v130
	s_barrier
	s_cbranch_vccz .LBB0_304
	s_and_saveexec_b64 s[20:21], s[4:5]
	ds_write_b32 v197, v130 offset:128
	s_or_b64 exec, exec, s[20:21]
	s_waitcnt lgkmcnt(0)
	v_add_u32_e32 v110, s59, v194
	ds_read_b128 v[98:101], v110 offset:224
	ds_read_b128 v[102:105], v110 offset:192
	ds_read_b128 v[106:109], v110 offset:160
	ds_read_b128 v[110:113], v110 offset:128
	s_waitcnt lgkmcnt(3)
	v_pk_mul_f32 v[14:15], v[14:15], v[98:99]
	s_waitcnt lgkmcnt(2)
	v_pk_mul_f32 v[10:11], v[10:11], v[102:103]
	s_waitcnt lgkmcnt(1)
	v_pk_mul_f32 v[6:7], v[6:7], v[106:107]
	v_pk_mul_f32 v[16:17], v[16:17], v[100:101]
	v_pk_mul_f32 v[12:13], v[12:13], v[104:105]
	v_pk_mul_f32 v[8:9], v[8:9], v[108:109]
	s_waitcnt lgkmcnt(0)
	v_pk_mul_f32 v[4:5], v[4:5], v[112:113]
	v_pk_mul_f32 v[2:3], v[2:3], v[110:111]
	v_pk_mul_f32 v[30:31], v[30:31], v[98:99]
	v_pk_mul_f32 v[26:27], v[26:27], v[102:103]
	v_pk_mul_f32 v[22:23], v[22:23], v[106:107]
	v_pk_mul_f32 v[32:33], v[32:33], v[100:101]
	v_pk_mul_f32 v[28:29], v[28:29], v[104:105]
	v_pk_mul_f32 v[24:25], v[24:25], v[108:109]
	v_pk_mul_f32 v[20:21], v[20:21], v[112:113]
	v_pk_mul_f32 v[18:19], v[18:19], v[110:111]
	v_pk_mul_f32 v[46:47], v[46:47], v[98:99]
	v_pk_mul_f32 v[42:43], v[42:43], v[102:103]
	v_pk_mul_f32 v[38:39], v[38:39], v[106:107]
	v_pk_mul_f32 v[48:49], v[48:49], v[100:101]
	v_pk_mul_f32 v[44:45], v[44:45], v[104:105]
	v_pk_mul_f32 v[40:41], v[40:41], v[108:109]
	v_pk_mul_f32 v[36:37], v[36:37], v[112:113]
	v_pk_mul_f32 v[34:35], v[34:35], v[110:111]
	v_pk_mul_f32 v[62:63], v[62:63], v[98:99]
	v_pk_mul_f32 v[58:59], v[58:59], v[102:103]
	v_pk_mul_f32 v[54:55], v[54:55], v[106:107]
	v_pk_mul_f32 v[64:65], v[64:65], v[100:101]
	v_pk_mul_f32 v[60:61], v[60:61], v[104:105]
	v_pk_mul_f32 v[56:57], v[56:57], v[108:109]
	v_pk_mul_f32 v[52:53], v[52:53], v[112:113]
	v_pk_mul_f32 v[50:51], v[50:51], v[110:111]
